# attention QK^T K-fragment reads triple-buffered (LDS latency hidden); GEMM per-phase setprio flips removed
# speedup vs baseline: 1.0075x; 1.0075x over previous
.LBB0_65:
	s_or_b64 exec, exec, s[8:9]
	s_ashr_i32 s3, s2, 31
	s_lshl_b64 s[8:9], s[2:3], 9
	s_add_u32 s8, s18, s8
	s_addc_u32 s9, s19, s9
	v_add_u32_e32 v3, s85, v12
	v_lshl_add_u64 v[6:7], s[8:9], 0, v[0:1]
	s_mov_b64 s[20:21], 0x80
	v_readfirstlane_b32 s47, v3
	v_mov_b32_e32 v3, v1
	v_add_u32_e32 v16, s85, v13
	v_lshl_add_u64 v[4:5], v[6:7], 0, s[20:21]
	s_mov_b32 m0, s47
	v_lshl_add_u64 v[8:9], s[8:9], 0, v[2:3]
	v_readfirstlane_b32 s46, v16
	s_barrier
	global_load_lds_dwordx4 v[4:5], off
	v_lshl_add_u64 v[4:5], v[8:9], 0, s[20:21]
	s_mov_b32 m0, s46
	v_add_u32_e32 v131, 16, v12
	global_load_lds_dwordx4 v[4:5], off
	s_mul_i32 s39, s45, 0x600
	v_add_u32_e32 v4, 0x8000, v131
	v_add_u32_e32 v144, 16, v13
	s_mul_hi_i32 s9, s45, 0x600
	s_add_u32 s52, s25, s39
	v_readfirstlane_b32 s40, v4
	v_add_u32_e32 v4, 0x8000, v144
	s_addc_u32 s53, s28, s9
	s_mov_b32 m0, s40
	v_readfirstlane_b32 s41, v4
	global_load_lds_dwordx4 v11, s[52:53]
	s_mov_b32 m0, s41
	v_and_b32_e32 v19, 15, v130
	global_load_lds_dwordx4 v10, s[52:53]
	s_or_b32 s52, s2, 0x80
	s_ashr_i32 s53, s52, 31
	s_lshl_b64 s[52:53], s[52:53], 9
	s_add_u32 s52, s18, s52
	s_addc_u32 s53, s19, s53
	v_lshl_add_u64 v[4:5], s[52:53], 0, v[0:1]
	v_add_u32_e32 v0, s94, v12
	v_lshl_add_u64 v[16:17], v[4:5], 0, s[20:21]
	v_readfirstlane_b32 s8, v0
	v_add_u32_e32 v0, s94, v13
	s_mov_b32 m0, s8
	v_lshl_add_u64 v[2:3], s[52:53], 0, v[2:3]
	v_readfirstlane_b32 s38, v0
	global_load_lds_dwordx4 v[16:17], off
	v_lshl_add_u64 v[16:17], v[2:3], 0, s[20:21]
	s_mov_b32 m0, s38
	v_lshlrev_b32_e32 v0, 12, v14
	global_load_lds_dwordx4 v[16:17], off
	v_lshlrev_b32_e32 v16, 2, v130
	v_and_b32_e32 v18, 48, v130
	v_and_b32_e32 v14, 0x3000, v0
	v_lshlrev_b32_e32 v0, 6, v19
	v_and_b32_e32 v16, 32, v16
	v_bitop3_b32 v17, v0, v16, v18 bitop3:0x36
	v_lshlrev_b32_e32 v0, 13, v15
	v_lshlrev_b32_e32 v15, 6, v130
	v_and_b32_e32 v15, 0x3c0, v15
	v_add3_u32 v206, s33, v17, v14
	v_bitop3_b32 v15, v15, v16, v18 bitop3:0x36
	s_waitcnt vmcnt(6)
	s_barrier
	v_add_u32_e32 v112, s33, v12
	v_add_u32_e32 v168, s86, v12
	v_add3_u32 v12, 16, v17, v0
	v_add3_u32 v0, 16, v15, v0
	v_add3_u32 v207, s86, v17, v14
	v_add3_u32 v208, s85, v17, v14
	v_add3_u32 v209, s94, v17, v14
	ds_read_b128 v[14:17], v206
	ds_read_b128 v[18:21], v206 offset:1024
	ds_read_b128 v[22:25], v206 offset:2048
	ds_read_b128 v[26:29], v206 offset:3072
	v_add_u32_e32 v62, 0xc000, v131
	v_add_u32_e32 v63, 0xc000, v144
	v_add_u32_e32 v113, s33, v13
	v_add_u32_e32 v13, s86, v13
	s_or_b32 s53, s45, 0x80
	v_add_u32_e32 v184, 0x4000, v131
	v_add_u32_e32 v194, 0x4000, v144
	s_mul_hi_i32 s52, s53, 0x600
	s_mulk_i32 s53, 0x600
	s_add_u32 s56, s25, s53
	v_readfirstlane_b32 s54, v62
	s_addc_u32 s57, s28, s52
	s_mov_b32 m0, s54
	v_readfirstlane_b32 s55, v63
	ds_read_b128 v[30:33], v12
	ds_read_b128 v[34:37], v12 offset:1024
	ds_read_b128 v[38:41], v0 offset:2048
	ds_read_b128 v[42:45], v0 offset:3072
	ds_read_b128 v[46:49], v0 offset:4096
	ds_read_b128 v[50:53], v0 offset:5120
	ds_read_b128 v[54:57], v0 offset:6144
	ds_read_b128 v[58:61], v0 offset:7168
	global_load_lds_dwordx4 v11, s[56:57]
	s_mov_b32 m0, s55
	s_nop 0
	global_load_lds_dwordx4 v10, s[56:57]
	s_waitcnt lgkmcnt(8)
	s_barrier
	s_waitcnt lgkmcnt(0)
	s_waitcnt lgkmcnt(0)
	v_mfma_f32_16x16x32_bf16 v[62:65], v[14:17], v[30:33], 0
	v_mfma_f32_16x16x32_bf16 v[66:69], v[22:25], v[30:33], 0
	v_mfma_f32_16x16x32_bf16 v[70:73], v[14:17], v[38:41], 0
	v_mfma_f32_16x16x32_bf16 v[74:77], v[22:25], v[38:41], 0
	v_mfma_f32_16x16x32_bf16 v[78:81], v[14:17], v[46:49], 0
	v_mfma_f32_16x16x32_bf16 v[82:85], v[22:25], v[46:49], 0
	v_mfma_f32_16x16x32_bf16 v[86:89], v[14:17], v[54:57], 0
	v_mfma_f32_16x16x32_bf16 v[90:93], v[22:25], v[54:57], 0
	v_mfma_f32_16x16x32_bf16 v[62:65], v[18:21], v[34:37], v[62:65]
	v_mfma_f32_16x16x32_bf16 v[66:69], v[26:29], v[34:37], v[66:69]
	v_mfma_f32_16x16x32_bf16 v[70:73], v[18:21], v[42:45], v[70:73]
	v_mfma_f32_16x16x32_bf16 v[74:77], v[26:29], v[42:45], v[74:77]
	v_mfma_f32_16x16x32_bf16 v[78:81], v[18:21], v[50:53], v[78:81]
	v_mfma_f32_16x16x32_bf16 v[82:85], v[26:29], v[50:53], v[82:85]
	v_mfma_f32_16x16x32_bf16 v[86:89], v[18:21], v[58:61], v[86:89]
	v_mfma_f32_16x16x32_bf16 v[90:93], v[26:29], v[58:61], v[90:93]
	s_barrier
	v_readfirstlane_b32 s56, v112
	v_lshl_add_u64 v[110:111], v[6:7], 0, s[36:37]
	s_mov_b32 m0, s56
	v_readfirstlane_b32 s56, v113
	ds_read_b128 v[94:97], v207
	ds_read_b128 v[98:101], v207 offset:1024
	ds_read_b128 v[102:105], v207 offset:2048
	ds_read_b128 v[106:109], v207 offset:3072
	global_load_lds_dwordx4 v[110:111], off
	v_lshl_add_u64 v[110:111], v[8:9], 0, s[36:37]
	s_mov_b32 m0, s56
	s_nop 0
	global_load_lds_dwordx4 v[110:111], off
	s_barrier
	s_waitcnt lgkmcnt(0)
	s_waitcnt lgkmcnt(0)
	v_mfma_f32_16x16x32_bf16 v[110:113], v[94:97], v[30:33], 0
	v_mfma_f32_16x16x32_bf16 v[30:33], v[102:105], v[30:33], 0
	v_mfma_f32_16x16x32_bf16 v[110:113], v[98:101], v[34:37], v[110:113]
	v_mfma_f32_16x16x32_bf16 v[30:33], v[106:109], v[34:37], v[30:33]
	v_mfma_f32_16x16x32_bf16 v[34:37], v[94:97], v[38:41], 0
	v_mfma_f32_16x16x32_bf16 v[38:41], v[102:105], v[38:41], 0
	v_mfma_f32_16x16x32_bf16 v[34:37], v[98:101], v[42:45], v[34:37]
	v_mfma_f32_16x16x32_bf16 v[38:41], v[106:109], v[42:45], v[38:41]
	v_mfma_f32_16x16x32_bf16 v[42:45], v[94:97], v[46:49], 0
	v_mfma_f32_16x16x32_bf16 v[46:49], v[102:105], v[46:49], 0
	v_mfma_f32_16x16x32_bf16 v[42:45], v[98:101], v[50:53], v[42:45]
	v_mfma_f32_16x16x32_bf16 v[46:49], v[106:109], v[50:53], v[46:49]
	v_mfma_f32_16x16x32_bf16 v[50:53], v[94:97], v[54:57], 0
	v_mfma_f32_16x16x32_bf16 v[54:57], v[102:105], v[54:57], 0
	v_mfma_f32_16x16x32_bf16 v[50:53], v[98:101], v[58:61], v[50:53]
	v_mfma_f32_16x16x32_bf16 v[54:57], v[106:109], v[58:61], v[54:57]
	s_add_u32 s56, s29, s39
	v_readfirstlane_b32 s58, v131
	s_addc_u32 s57, s31, s9
	s_mov_b32 m0, s58
	v_readfirstlane_b32 s58, v144
	s_barrier
	ds_read_b128 v[58:61], v12 offset:16384
	ds_read_b128 v[114:117], v12 offset:17408
	ds_read_b128 v[118:121], v0 offset:18432
	ds_read_b128 v[122:125], v0 offset:19456
	ds_read_b128 v[126:129], v0 offset:20480
	ds_read_b128 v[132:135], v0 offset:21504
	ds_read_b128 v[136:139], v0 offset:22528
	ds_read_b128 v[140:143], v0 offset:23552
	global_load_lds_dwordx4 v11, s[56:57]
	s_mov_b32 m0, s58
	s_nop 0
	global_load_lds_dwordx4 v10, s[56:57]
	s_barrier
	s_waitcnt lgkmcnt(0)
	s_waitcnt lgkmcnt(0)
	v_mfma_f32_16x16x32_bf16 v[144:147], v[14:17], v[58:61], 0
	v_mfma_f32_16x16x32_bf16 v[152:155], v[14:17], v[118:121], 0
	v_mfma_f32_16x16x32_bf16 v[160:163], v[14:17], v[126:129], 0
	v_mfma_f32_16x16x32_bf16 v[14:17], v[14:17], v[136:139], 0
	v_mfma_f32_16x16x32_bf16 v[144:147], v[18:21], v[114:117], v[144:147]
	v_mfma_f32_16x16x32_bf16 v[152:155], v[18:21], v[122:125], v[152:155]
	v_mfma_f32_16x16x32_bf16 v[160:163], v[18:21], v[132:135], v[160:163]
	v_mfma_f32_16x16x32_bf16 v[14:17], v[18:21], v[140:143], v[14:17]
	v_mfma_f32_16x16x32_bf16 v[18:21], v[22:25], v[136:139], 0
	v_mfma_f32_16x16x32_bf16 v[148:151], v[22:25], v[58:61], 0
	v_mfma_f32_16x16x32_bf16 v[156:159], v[22:25], v[118:121], 0
	v_mfma_f32_16x16x32_bf16 v[164:167], v[22:25], v[126:129], 0
	v_mfma_f32_16x16x32_bf16 v[18:21], v[26:29], v[140:143], v[18:21]
	v_mfma_f32_16x16x32_bf16 v[148:151], v[26:29], v[114:117], v[148:151]
	v_mfma_f32_16x16x32_bf16 v[156:159], v[26:29], v[122:125], v[156:159]
	v_mfma_f32_16x16x32_bf16 v[164:167], v[26:29], v[132:135], v[164:167]
	s_barrier
	v_readfirstlane_b32 s56, v168
	v_lshl_add_u64 v[22:23], v[4:5], 0, s[36:37]
	s_mov_b32 m0, s56
	v_readfirstlane_b32 s56, v13
	global_load_lds_dwordx4 v[22:23], off
	v_lshl_add_u64 v[22:23], v[2:3], 0, s[36:37]
	s_mov_b32 m0, s56
	s_nop 0
	global_load_lds_dwordx4 v[22:23], off
	s_waitcnt vmcnt(6)
	s_barrier
	v_mfma_f32_16x16x32_bf16 v[22:25], v[94:97], v[58:61], 0
	v_mfma_f32_16x16x32_bf16 v[26:29], v[102:105], v[58:61], 0
	v_mfma_f32_16x16x32_bf16 v[22:25], v[98:101], v[114:117], v[22:25]
	v_mfma_f32_16x16x32_bf16 v[26:29], v[106:109], v[114:117], v[26:29]
	v_mfma_f32_16x16x32_bf16 v[58:61], v[94:97], v[118:121], 0
	v_mfma_f32_16x16x32_bf16 v[114:117], v[102:105], v[118:121], 0
	v_mfma_f32_16x16x32_bf16 v[118:121], v[94:97], v[126:129], 0
	v_mfma_f32_16x16x32_bf16 v[94:97], v[94:97], v[136:139], 0
	v_mfma_f32_16x16x32_bf16 v[58:61], v[98:101], v[122:125], v[58:61]
	v_mfma_f32_16x16x32_bf16 v[114:117], v[106:109], v[122:125], v[114:117]
	v_mfma_f32_16x16x32_bf16 v[118:121], v[98:101], v[132:135], v[118:121]
	v_mfma_f32_16x16x32_bf16 v[122:125], v[102:105], v[126:129], 0
	v_mfma_f32_16x16x32_bf16 v[94:97], v[98:101], v[140:143], v[94:97]
	v_mfma_f32_16x16x32_bf16 v[98:101], v[102:105], v[136:139], 0
	v_mfma_f32_16x16x32_bf16 v[122:125], v[106:109], v[132:135], v[122:125]
	v_mfma_f32_16x16x32_bf16 v[98:101], v[106:109], v[140:143], v[98:101]
	s_barrier
	ds_read_b128 v[102:105], v208
	ds_read_b128 v[106:109], v208 offset:1024
	ds_read_b128 v[126:129], v208 offset:2048
	ds_read_b128 v[132:135], v208 offset:3072
	s_add_u32 s56, s29, s53
	v_readfirstlane_b32 s58, v184
	s_addc_u32 s57, s31, s52
	s_mov_b32 m0, s58
	v_readfirstlane_b32 s58, v194
	ds_read_b128 v[136:139], v12 offset:32768
	ds_read_b128 v[140:143], v12 offset:33792
	ds_read_b128 v[168:171], v0 offset:34816
	ds_read_b128 v[172:175], v0 offset:35840
	ds_read_b128 v[176:179], v0 offset:36864
	ds_read_b128 v[180:183], v0 offset:37888
	ds_read_b128 v[186:189], v0 offset:38912
	ds_read_b128 v[190:193], v0 offset:39936
	global_load_lds_dwordx4 v11, s[56:57]
	s_mov_b32 m0, s58
	s_nop 0
	global_load_lds_dwordx4 v10, s[56:57]
	s_waitcnt lgkmcnt(8)
	s_barrier
	s_waitcnt lgkmcnt(0)
	s_waitcnt lgkmcnt(0)
	v_mfma_f32_16x16x32_bf16 v[62:65], v[102:105], v[136:139], v[62:65]
	v_mfma_f32_16x16x32_bf16 v[66:69], v[126:129], v[136:139], v[66:69]
	v_mfma_f32_16x16x32_bf16 v[70:73], v[102:105], v[168:171], v[70:73]
	v_mfma_f32_16x16x32_bf16 v[74:77], v[126:129], v[168:171], v[74:77]
	v_mfma_f32_16x16x32_bf16 v[78:81], v[102:105], v[176:179], v[78:81]
	v_mfma_f32_16x16x32_bf16 v[82:85], v[126:129], v[176:179], v[82:85]
	v_mfma_f32_16x16x32_bf16 v[86:89], v[102:105], v[186:189], v[86:89]
	v_mfma_f32_16x16x32_bf16 v[90:93], v[126:129], v[186:189], v[90:93]
	v_mfma_f32_16x16x32_bf16 v[62:65], v[106:109], v[140:143], v[62:65]
	v_mfma_f32_16x16x32_bf16 v[66:69], v[132:135], v[140:143], v[66:69]
	v_mfma_f32_16x16x32_bf16 v[70:73], v[106:109], v[172:175], v[70:73]
	v_mfma_f32_16x16x32_bf16 v[74:77], v[132:135], v[172:175], v[74:77]
	v_mfma_f32_16x16x32_bf16 v[78:81], v[106:109], v[180:183], v[78:81]
	v_mfma_f32_16x16x32_bf16 v[82:85], v[132:135], v[180:183], v[82:85]
	v_mfma_f32_16x16x32_bf16 v[86:89], v[106:109], v[190:193], v[86:89]
	v_mfma_f32_16x16x32_bf16 v[90:93], v[132:135], v[190:193], v[90:93]
	s_barrier
	s_mov_b32 m0, s47
	v_lshl_add_u64 v[6:7], v[6:7], 0, s[60:61]
	ds_read_b128 v[194:197], v209
	ds_read_b128 v[198:201], v209 offset:1024
	ds_read_b128 v[202:205], v209 offset:2048
	ds_read_b128 v[218:221], v209 offset:3072
	global_load_lds_dwordx4 v[6:7], off
	v_lshl_add_u64 v[6:7], v[8:9], 0, s[60:61]
	s_mov_b32 m0, s46
	s_nop 0
	global_load_lds_dwordx4 v[6:7], off
	s_barrier
	s_waitcnt lgkmcnt(0)
	s_waitcnt lgkmcnt(0)
	v_mfma_f32_16x16x32_bf16 v[6:9], v[194:197], v[136:139], v[110:113]
	v_mfma_f32_16x16x32_bf16 v[30:33], v[202:205], v[136:139], v[30:33]
	v_mfma_f32_16x16x32_bf16 v[34:37], v[194:197], v[168:171], v[34:37]
	v_mfma_f32_16x16x32_bf16 v[38:41], v[202:205], v[168:171], v[38:41]
	v_mfma_f32_16x16x32_bf16 v[42:45], v[194:197], v[176:179], v[42:45]
	v_mfma_f32_16x16x32_bf16 v[46:49], v[202:205], v[176:179], v[46:49]
	v_mfma_f32_16x16x32_bf16 v[50:53], v[194:197], v[186:189], v[50:53]
	v_mfma_f32_16x16x32_bf16 v[54:57], v[202:205], v[186:189], v[54:57]
	v_mfma_f32_16x16x32_bf16 v[6:9], v[198:201], v[140:143], v[6:9]
	v_mfma_f32_16x16x32_bf16 v[30:33], v[218:221], v[140:143], v[30:33]
	v_mfma_f32_16x16x32_bf16 v[34:37], v[198:201], v[172:175], v[34:37]
	v_mfma_f32_16x16x32_bf16 v[38:41], v[218:221], v[172:175], v[38:41]
	v_mfma_f32_16x16x32_bf16 v[42:45], v[198:201], v[180:183], v[42:45]
	v_mfma_f32_16x16x32_bf16 v[46:49], v[218:221], v[180:183], v[46:49]
	v_mfma_f32_16x16x32_bf16 v[50:53], v[198:201], v[190:193], v[50:53]
	v_mfma_f32_16x16x32_bf16 v[54:57], v[218:221], v[190:193], v[54:57]
	s_add_u32 s46, s42, s39
	s_addc_u32 s47, s43, s9
	s_mov_b32 m0, s40
	s_barrier
	ds_read_b128 v[110:113], v12 offset:49152
	ds_read_b128 v[136:139], v12 offset:50176
	ds_read_b128 v[140:143], v0 offset:51200
	ds_read_b128 v[168:171], v0 offset:52224
	ds_read_b128 v[172:175], v0 offset:53248
	ds_read_b128 v[176:179], v0 offset:54272
	ds_read_b128 v[180:183], v0 offset:55296
	ds_read_b128 v[186:189], v0 offset:56320
	global_load_lds_dwordx4 v11, s[46:47]
	s_mov_b32 m0, s41
	s_nop 0
	global_load_lds_dwordx4 v10, s[46:47]
	s_barrier
	s_waitcnt lgkmcnt(0)
	s_waitcnt lgkmcnt(0)
	v_mfma_f32_16x16x32_bf16 v[14:17], v[102:105], v[180:183], v[14:17]
	v_mfma_f32_16x16x32_bf16 v[18:21], v[126:129], v[180:183], v[18:21]
	v_mfma_f32_16x16x32_bf16 v[144:147], v[102:105], v[110:113], v[144:147]
	v_mfma_f32_16x16x32_bf16 v[148:151], v[126:129], v[110:113], v[148:151]
	v_mfma_f32_16x16x32_bf16 v[152:155], v[102:105], v[140:143], v[152:155]
	v_mfma_f32_16x16x32_bf16 v[156:159], v[126:129], v[140:143], v[156:159]
	v_mfma_f32_16x16x32_bf16 v[160:163], v[102:105], v[172:175], v[160:163]
	v_mfma_f32_16x16x32_bf16 v[164:167], v[126:129], v[172:175], v[164:167]
	v_mfma_f32_16x16x32_bf16 v[14:17], v[106:109], v[186:189], v[14:17]
	v_mfma_f32_16x16x32_bf16 v[18:21], v[132:135], v[186:189], v[18:21]
	v_mfma_f32_16x16x32_bf16 v[144:147], v[106:109], v[136:139], v[144:147]
	v_mfma_f32_16x16x32_bf16 v[148:151], v[132:135], v[136:139], v[148:151]
	v_mfma_f32_16x16x32_bf16 v[152:155], v[106:109], v[168:171], v[152:155]
	v_mfma_f32_16x16x32_bf16 v[156:159], v[132:135], v[168:171], v[156:159]
	v_mfma_f32_16x16x32_bf16 v[160:163], v[106:109], v[176:179], v[160:163]
	v_mfma_f32_16x16x32_bf16 v[164:167], v[132:135], v[176:179], v[164:167]
	s_barrier
	s_mov_b32 m0, s8
	v_lshl_add_u64 v[4:5], v[4:5], 0, s[60:61]
	global_load_lds_dwordx4 v[4:5], off
	v_lshl_add_u64 v[2:3], v[2:3], 0, s[60:61]
	s_mov_b32 m0, s38
	s_nop 0
	global_load_lds_dwordx4 v[2:3], off
	s_waitcnt vmcnt(6)
	s_barrier
	v_mfma_f32_16x16x32_bf16 v[2:5], v[194:197], v[110:113], v[22:25]
	v_mfma_f32_16x16x32_bf16 v[22:25], v[202:205], v[110:113], v[26:29]
	v_mfma_f32_16x16x32_bf16 v[26:29], v[194:197], v[140:143], v[58:61]
	v_mfma_f32_16x16x32_bf16 v[58:61], v[202:205], v[140:143], v[114:117]
	v_mfma_f32_16x16x32_bf16 v[102:105], v[194:197], v[172:175], v[118:121]
	v_mfma_f32_16x16x32_bf16 v[106:109], v[202:205], v[172:175], v[122:125]
	v_mfma_f32_16x16x32_bf16 v[94:97], v[194:197], v[180:183], v[94:97]
	v_mfma_f32_16x16x32_bf16 v[98:101], v[202:205], v[180:183], v[98:101]
	v_mfma_f32_16x16x32_bf16 v[2:5], v[198:201], v[136:139], v[2:5]
	v_mfma_f32_16x16x32_bf16 v[22:25], v[218:221], v[136:139], v[22:25]
	v_mfma_f32_16x16x32_bf16 v[26:29], v[198:201], v[168:171], v[26:29]
	v_mfma_f32_16x16x32_bf16 v[58:61], v[218:221], v[168:171], v[58:61]
	v_mfma_f32_16x16x32_bf16 v[102:105], v[198:201], v[176:179], v[102:105]
	v_mfma_f32_16x16x32_bf16 v[106:109], v[218:221], v[176:179], v[106:109]
	v_mfma_f32_16x16x32_bf16 v[94:97], v[198:201], v[186:189], v[94:97]
	v_mfma_f32_16x16x32_bf16 v[98:101], v[218:221], v[186:189], v[98:101]
	s_add_u32 s8, s42, s53
	s_addc_u32 s9, s43, s52
	s_mov_b32 m0, s54
	s_barrier
	ds_read_b128 v[110:113], v206
	ds_read_b128 v[114:117], v206 offset:1024
	ds_read_b128 v[118:121], v206 offset:2048
	ds_read_b128 v[122:125], v206 offset:3072
	ds_read_b128 v[126:129], v12
	ds_read_b128 v[132:135], v12 offset:1024
	ds_read_b128 v[136:139], v0 offset:2048
	ds_read_b128 v[140:143], v0 offset:3072
	ds_read_b128 v[168:171], v0 offset:4096
	ds_read_b128 v[172:175], v0 offset:5120
	ds_read_b128 v[176:179], v0 offset:6144
	ds_read_b128 v[180:183], v0 offset:7168
	global_load_lds_dwordx4 v11, s[8:9]
	s_mov_b32 m0, s55
	s_nop 0
	global_load_lds_dwordx4 v10, s[8:9]
	s_barrier
	s_waitcnt lgkmcnt(0)
	s_waitcnt lgkmcnt(0)
	v_mfma_f32_16x16x32_bf16 v[62:65], v[110:113], v[126:129], v[62:65]
	v_mfma_f32_16x16x32_bf16 v[66:69], v[118:121], v[126:129], v[66:69]
	v_mfma_f32_16x16x32_bf16 v[70:73], v[110:113], v[136:139], v[70:73]
	v_mfma_f32_16x16x32_bf16 v[74:77], v[118:121], v[136:139], v[74:77]
	v_mfma_f32_16x16x32_bf16 v[78:81], v[110:113], v[168:171], v[78:81]
	v_mfma_f32_16x16x32_bf16 v[82:85], v[118:121], v[168:171], v[82:85]
	v_mfma_f32_16x16x32_bf16 v[86:89], v[110:113], v[176:179], v[86:89]
	v_mfma_f32_16x16x32_bf16 v[62:65], v[114:117], v[132:135], v[62:65]
	v_mfma_f32_16x16x32_bf16 v[66:69], v[122:125], v[132:135], v[66:69]
	v_mfma_f32_16x16x32_bf16 v[70:73], v[114:117], v[140:143], v[70:73]
	v_mfma_f32_16x16x32_bf16 v[74:77], v[122:125], v[140:143], v[74:77]
	v_mfma_f32_16x16x32_bf16 v[78:81], v[114:117], v[172:175], v[78:81]
	v_mfma_f32_16x16x32_bf16 v[82:85], v[122:125], v[172:175], v[82:85]
	v_mfma_f32_16x16x32_bf16 v[86:89], v[114:117], v[180:183], v[86:89]
	v_mfma_f32_16x16x32_bf16 v[90:93], v[118:121], v[176:179], v[90:93]
	v_mfma_f32_16x16x32_bf16 v[186:189], v[122:125], v[180:183], v[90:93]
	s_barrier
	s_nop 4
	ds_read_b128 v[90:93], v207
	ds_read_b128 v[190:193], v207 offset:1024
	ds_read_b128 v[194:197], v207 offset:2048
	ds_read_b128 v[198:201], v207 offset:3072
	s_barrier
	s_waitcnt lgkmcnt(0)
	s_waitcnt lgkmcnt(0)
	v_mfma_f32_16x16x32_bf16 v[6:9], v[90:93], v[126:129], v[6:9]
	v_mfma_f32_16x16x32_bf16 v[30:33], v[194:197], v[126:129], v[30:33]
	v_mfma_f32_16x16x32_bf16 v[34:37], v[90:93], v[136:139], v[34:37]
	v_mfma_f32_16x16x32_bf16 v[38:41], v[194:197], v[136:139], v[38:41]
	v_mfma_f32_16x16x32_bf16 v[42:45], v[90:93], v[168:171], v[42:45]
	v_mfma_f32_16x16x32_bf16 v[46:49], v[194:197], v[168:171], v[46:49]
	v_mfma_f32_16x16x32_bf16 v[50:53], v[90:93], v[176:179], v[50:53]
	v_mfma_f32_16x16x32_bf16 v[54:57], v[194:197], v[176:179], v[54:57]
	v_mfma_f32_16x16x32_bf16 v[6:9], v[190:193], v[132:135], v[6:9]
	v_mfma_f32_16x16x32_bf16 v[30:33], v[198:201], v[132:135], v[30:33]
	v_mfma_f32_16x16x32_bf16 v[34:37], v[190:193], v[140:143], v[34:37]
	v_mfma_f32_16x16x32_bf16 v[38:41], v[198:201], v[140:143], v[38:41]
	v_mfma_f32_16x16x32_bf16 v[42:45], v[190:193], v[172:175], v[42:45]
	v_mfma_f32_16x16x32_bf16 v[46:49], v[198:201], v[172:175], v[46:49]
	v_mfma_f32_16x16x32_bf16 v[50:53], v[190:193], v[180:183], v[50:53]
	v_mfma_f32_16x16x32_bf16 v[54:57], v[198:201], v[180:183], v[54:57]
	s_barrier
	ds_read_b128 v[126:129], v12 offset:16384
	ds_read_b128 v[132:135], v12 offset:17408
	ds_read_b128 v[136:139], v0 offset:18432
	ds_read_b128 v[140:143], v0 offset:19456
	ds_read_b128 v[168:171], v0 offset:20480
	ds_read_b128 v[172:175], v0 offset:21504
	ds_read_b128 v[176:179], v0 offset:22528
	ds_read_b128 v[180:183], v0 offset:23552
	s_waitcnt vmcnt(4)
	s_barrier
	s_waitcnt lgkmcnt(0)
	s_waitcnt lgkmcnt(0)
	v_mfma_f32_16x16x32_bf16 v[14:17], v[110:113], v[176:179], v[14:17]
	v_mfma_f32_16x16x32_bf16 v[18:21], v[118:121], v[176:179], v[18:21]
	v_mfma_f32_16x16x32_bf16 v[144:147], v[110:113], v[126:129], v[144:147]
	v_mfma_f32_16x16x32_bf16 v[148:151], v[118:121], v[126:129], v[148:151]
	v_mfma_f32_16x16x32_bf16 v[152:155], v[110:113], v[136:139], v[152:155]
	v_mfma_f32_16x16x32_bf16 v[156:159], v[118:121], v[136:139], v[156:159]
	v_mfma_f32_16x16x32_bf16 v[160:163], v[110:113], v[168:171], v[160:163]
	v_mfma_f32_16x16x32_bf16 v[164:167], v[118:121], v[168:171], v[164:167]
	v_mfma_f32_16x16x32_bf16 v[14:17], v[114:117], v[180:183], v[14:17]
	v_mfma_f32_16x16x32_bf16 v[18:21], v[122:125], v[180:183], v[18:21]
	v_mfma_f32_16x16x32_bf16 v[144:147], v[114:117], v[132:135], v[144:147]
	v_mfma_f32_16x16x32_bf16 v[148:151], v[122:125], v[132:135], v[148:151]
	v_mfma_f32_16x16x32_bf16 v[152:155], v[114:117], v[140:143], v[152:155]
	v_mfma_f32_16x16x32_bf16 v[156:159], v[122:125], v[140:143], v[156:159]
	v_mfma_f32_16x16x32_bf16 v[160:163], v[114:117], v[172:175], v[160:163]
	v_mfma_f32_16x16x32_bf16 v[164:167], v[122:125], v[172:175], v[164:167]
	v_mfma_f32_16x16x32_bf16 v[2:5], v[90:93], v[126:129], v[2:5]
	v_mfma_f32_16x16x32_bf16 v[22:25], v[194:197], v[126:129], v[22:25]
	v_mfma_f32_16x16x32_bf16 v[26:29], v[90:93], v[136:139], v[26:29]
	v_mfma_f32_16x16x32_bf16 v[2:5], v[190:193], v[132:135], v[2:5]
	v_mfma_f32_16x16x32_bf16 v[22:25], v[198:201], v[132:135], v[22:25]
	v_mfma_f32_16x16x32_bf16 v[132:135], v[190:193], v[140:143], v[26:29]
	v_mfma_f32_16x16x32_bf16 v[26:29], v[194:197], v[136:139], v[58:61]
	v_mfma_f32_16x16x32_bf16 v[136:139], v[198:201], v[140:143], v[26:29]
	v_mfma_f32_16x16x32_bf16 v[26:29], v[90:93], v[168:171], v[102:105]
	v_mfma_f32_16x16x32_bf16 v[140:143], v[190:193], v[172:175], v[26:29]
	v_mfma_f32_16x16x32_bf16 v[26:29], v[194:197], v[168:171], v[106:109]
	v_mfma_f32_16x16x32_bf16 v[168:171], v[198:201], v[172:175], v[26:29]
	v_mfma_f32_16x16x32_bf16 v[26:29], v[90:93], v[176:179], v[94:97]
	v_mfma_f32_16x16x32_bf16 v[172:175], v[190:193], v[180:183], v[26:29]
	v_mfma_f32_16x16x32_bf16 v[26:29], v[194:197], v[176:179], v[98:101]
	v_mfma_f32_16x16x32_bf16 v[176:179], v[198:201], v[180:183], v[26:29]
	s_barrier
	ds_read_b128 v[180:183], v208
	ds_read_b128 v[190:193], v208 offset:1024
	ds_read_b128 v[194:197], v208 offset:2048
	ds_read_b128 v[198:201], v208 offset:3072
	s_nop 0
	ds_read_b128 v[26:29], v12 offset:32768
	ds_read_b128 v[58:61], v12 offset:33792
	ds_read_b128 v[98:101], v0 offset:34816
	ds_read_b128 v[202:205], v0 offset:35840
	ds_read_b128 v[218:221], v0 offset:36864
	ds_read_b128 v[222:225], v0 offset:37888
	ds_read_b128 v[226:229], v0 offset:38912
	ds_read_b128 v[230:233], v0 offset:39936
	s_waitcnt vmcnt(2)
	s_barrier
	s_waitcnt lgkmcnt(0)
	s_waitcnt lgkmcnt(0)
	v_mfma_f32_16x16x32_bf16 v[62:65], v[180:183], v[26:29], v[62:65]
	v_mfma_f32_16x16x32_bf16 v[126:129], v[190:193], v[58:61], v[62:65]
	v_mfma_f32_16x16x32_bf16 v[62:65], v[194:197], v[26:29], v[66:69]
	v_mfma_f32_16x16x32_bf16 v[122:125], v[198:201], v[58:61], v[62:65]
	v_mfma_f32_16x16x32_bf16 v[62:65], v[180:183], v[98:101], v[70:73]
	v_mfma_f32_16x16x32_bf16 v[110:113], v[190:193], v[202:205], v[62:65]
	v_mfma_f32_16x16x32_bf16 v[62:65], v[194:197], v[98:101], v[74:77]
	v_mfma_f32_16x16x32_bf16 v[106:109], v[198:201], v[202:205], v[62:65]
	v_mfma_f32_16x16x32_bf16 v[62:65], v[180:183], v[218:221], v[78:81]
	v_mfma_f32_16x16x32_bf16 v[94:97], v[190:193], v[222:225], v[62:65]
	v_mfma_f32_16x16x32_bf16 v[62:65], v[194:197], v[218:221], v[82:85]
	v_mfma_f32_16x16x32_bf16 v[90:93], v[198:201], v[222:225], v[62:65]
	v_mfma_f32_16x16x32_bf16 v[62:65], v[180:183], v[226:229], v[86:89]
	v_mfma_f32_16x16x32_bf16 v[78:81], v[190:193], v[230:233], v[62:65]
	v_mfma_f32_16x16x32_bf16 v[62:65], v[194:197], v[226:229], v[186:189]
	v_mfma_f32_16x16x32_bf16 v[74:77], v[198:201], v[230:233], v[62:65]
	s_barrier
	ds_read_b128 v[186:189], v209
	ds_read_b128 v[234:237], v209 offset:1024
	ds_read_b128 v[238:241], v209 offset:2048
	ds_read_b128 v[242:245], v209 offset:3072
	s_waitcnt vmcnt(0)
	s_barrier
	s_waitcnt lgkmcnt(0)
	s_waitcnt lgkmcnt(0)
	v_mfma_f32_16x16x32_bf16 v[6:9], v[186:189], v[26:29], v[6:9]
	v_mfma_f32_16x16x32_bf16 v[118:121], v[234:237], v[58:61], v[6:9]
	v_mfma_f32_16x16x32_bf16 v[6:9], v[238:241], v[26:29], v[30:33]
	v_mfma_f32_16x16x32_bf16 v[114:117], v[242:245], v[58:61], v[6:9]
	v_mfma_f32_16x16x32_bf16 v[6:9], v[186:189], v[98:101], v[34:37]
	v_mfma_f32_16x16x32_bf16 v[102:105], v[234:237], v[202:205], v[6:9]
	v_mfma_f32_16x16x32_bf16 v[6:9], v[238:241], v[98:101], v[38:41]
	v_mfma_f32_16x16x32_bf16 v[98:101], v[242:245], v[202:205], v[6:9]
	v_mfma_f32_16x16x32_bf16 v[6:9], v[186:189], v[218:221], v[42:45]
	v_mfma_f32_16x16x32_bf16 v[86:89], v[234:237], v[222:225], v[6:9]
	v_mfma_f32_16x16x32_bf16 v[6:9], v[238:241], v[218:221], v[46:49]
	v_mfma_f32_16x16x32_bf16 v[82:85], v[242:245], v[222:225], v[6:9]
	v_mfma_f32_16x16x32_bf16 v[6:9], v[186:189], v[226:229], v[50:53]
	v_mfma_f32_16x16x32_bf16 v[70:73], v[234:237], v[230:233], v[6:9]
	v_mfma_f32_16x16x32_bf16 v[6:9], v[238:241], v[226:229], v[54:57]
	v_mfma_f32_16x16x32_bf16 v[66:69], v[242:245], v[230:233], v[6:9]
	s_barrier
	s_nop 4
	ds_read_b128 v[6:9], v12 offset:49152
	ds_read_b128 v[34:37], v12 offset:50176
	ds_read_b128 v[202:205], v0 offset:51200
	ds_read_b128 v[218:221], v0 offset:52224
	ds_read_b128 v[222:225], v0 offset:53248
	ds_read_b128 v[226:229], v0 offset:54272
	ds_read_b128 v[230:233], v0 offset:55296
	ds_read_b128 v[246:249], v0 offset:56320
	s_barrier
	s_waitcnt lgkmcnt(0)
	s_waitcnt lgkmcnt(0)
	v_mfma_f32_16x16x32_bf16 v[10:13], v[180:183], v[6:9], v[144:147]
	v_mfma_f32_16x16x32_bf16 v[62:65], v[190:193], v[34:37], v[10:13]
	v_mfma_f32_16x16x32_bf16 v[10:13], v[194:197], v[6:9], v[148:151]
	v_mfma_f32_16x16x32_bf16 v[58:61], v[198:201], v[34:37], v[10:13]
	v_mfma_f32_16x16x32_bf16 v[10:13], v[180:183], v[202:205], v[152:155]
	v_mfma_f32_16x16x32_bf16 v[46:49], v[190:193], v[218:221], v[10:13]
	v_mfma_f32_16x16x32_bf16 v[10:13], v[194:197], v[202:205], v[156:159]
	v_mfma_f32_16x16x32_bf16 v[42:45], v[198:201], v[218:221], v[10:13]
	v_mfma_f32_16x16x32_bf16 v[10:13], v[180:183], v[222:225], v[160:163]
	v_mfma_f32_16x16x32_bf16 v[30:33], v[190:193], v[226:229], v[10:13]
	v_mfma_f32_16x16x32_bf16 v[10:13], v[194:197], v[222:225], v[164:167]
	v_mfma_f32_16x16x32_bf16 v[26:29], v[198:201], v[226:229], v[10:13]
	v_mfma_f32_16x16x32_bf16 v[10:13], v[180:183], v[230:233], v[14:17]
	v_mfma_f32_16x16x32_bf16 v[14:17], v[190:193], v[246:249], v[10:13]
	v_mfma_f32_16x16x32_bf16 v[10:13], v[194:197], v[230:233], v[18:21]
	v_mfma_f32_16x16x32_bf16 v[10:13], v[198:201], v[246:249], v[10:13]
	v_mfma_f32_16x16x32_bf16 v[2:5], v[186:189], v[6:9], v[2:5]
	v_mfma_f32_16x16x32_bf16 v[54:57], v[234:237], v[34:37], v[2:5]
	v_mfma_f32_16x16x32_bf16 v[2:5], v[238:241], v[6:9], v[22:25]
	v_mfma_f32_16x16x32_bf16 v[50:53], v[242:245], v[34:37], v[2:5]
	v_mfma_f32_16x16x32_bf16 v[2:5], v[186:189], v[202:205], v[132:135]
	v_mfma_f32_16x16x32_bf16 v[38:41], v[234:237], v[218:221], v[2:5]
	v_mfma_f32_16x16x32_bf16 v[2:5], v[238:241], v[202:205], v[136:139]
	v_mfma_f32_16x16x32_bf16 v[34:37], v[242:245], v[218:221], v[2:5]
	v_mfma_f32_16x16x32_bf16 v[2:5], v[186:189], v[222:225], v[140:143]
	v_mfma_f32_16x16x32_bf16 v[22:25], v[234:237], v[226:229], v[2:5]
	v_mfma_f32_16x16x32_bf16 v[2:5], v[238:241], v[222:225], v[168:171]
	v_mfma_f32_16x16x32_bf16 v[18:21], v[242:245], v[226:229], v[2:5]
	v_mfma_f32_16x16x32_bf16 v[2:5], v[186:189], v[230:233], v[172:175]
	v_mfma_f32_16x16x32_bf16 v[6:9], v[234:237], v[246:249], v[2:5]
	v_mfma_f32_16x16x32_bf16 v[2:5], v[238:241], v[230:233], v[176:179]
	v_mfma_f32_16x16x32_bf16 v[2:5], v[242:245], v[246:249], v[2:5]
	s_movk_i32 s1, 0x100
	v_cmp_gt_u32_e32 vcc, s1, v130
	s_barrier
	s_and_saveexec_b64 s[8:9], vcc
	s_cbranch_execz .LBB0_67
	s_barrier

.LBB0_76:
	s_or_b64 exec, exec, s[8:9]
	s_ashr_i32 s3, s2, 31
	s_lshl_b64 s[8:9], s[2:3], 9
	s_add_u32 s8, s18, s8
	s_addc_u32 s9, s19, s9
	v_add_u32_e32 v3, s85, v12
	v_lshl_add_u64 v[6:7], s[8:9], 0, v[0:1]
	s_mov_b64 s[20:21], 0x80
	v_readfirstlane_b32 s45, v3
	v_mov_b32_e32 v3, v1
	v_add_u32_e32 v16, s85, v13
	v_lshl_add_u64 v[4:5], v[6:7], 0, s[20:21]
	s_mov_b32 m0, s45
	v_lshl_add_u64 v[8:9], s[8:9], 0, v[2:3]
	v_readfirstlane_b32 s44, v16
	s_barrier
	global_load_lds_dwordx4 v[4:5], off
	v_lshl_add_u64 v[4:5], v[8:9], 0, s[20:21]
	s_mov_b32 m0, s44
	v_add_u32_e32 v131, 16, v12
	global_load_lds_dwordx4 v[4:5], off
	s_mul_i32 s23, s43, 0x600
	v_add_u32_e32 v4, 0x8000, v131
	v_add_u32_e32 v144, 16, v13
	s_mul_hi_i32 s9, s43, 0x600
	s_add_u32 s46, s25, s23
	v_readfirstlane_b32 s38, v4
	v_add_u32_e32 v4, 0x8000, v144
	s_addc_u32 s47, s28, s9
	s_mov_b32 m0, s38
	v_readfirstlane_b32 s39, v4
	global_load_lds_dwordx4 v11, s[46:47]
	s_mov_b32 m0, s39
	v_and_b32_e32 v19, 15, v130
	global_load_lds_dwordx4 v10, s[46:47]
	s_or_b32 s46, s2, 0x80
	s_ashr_i32 s47, s46, 31
	s_lshl_b64 s[46:47], s[46:47], 9
	s_add_u32 s46, s18, s46
	s_addc_u32 s47, s19, s47
	v_lshl_add_u64 v[4:5], s[46:47], 0, v[0:1]
	v_add_u32_e32 v0, s94, v12
	v_lshl_add_u64 v[16:17], v[4:5], 0, s[20:21]
	v_readfirstlane_b32 s8, v0
	v_add_u32_e32 v0, s94, v13
	s_mov_b32 m0, s8
	v_lshl_add_u64 v[2:3], s[46:47], 0, v[2:3]
	v_readfirstlane_b32 s22, v0
	global_load_lds_dwordx4 v[16:17], off
	v_lshl_add_u64 v[16:17], v[2:3], 0, s[20:21]
	s_mov_b32 m0, s22
	v_lshlrev_b32_e32 v0, 12, v14
	global_load_lds_dwordx4 v[16:17], off
	v_lshlrev_b32_e32 v16, 2, v130
	v_and_b32_e32 v18, 48, v130
	v_and_b32_e32 v14, 0x3000, v0
	v_lshlrev_b32_e32 v0, 6, v19
	v_and_b32_e32 v16, 32, v16
	v_bitop3_b32 v17, v0, v16, v18 bitop3:0x36
	v_lshlrev_b32_e32 v0, 13, v15
	v_lshlrev_b32_e32 v15, 6, v130
	v_and_b32_e32 v15, 0x3c0, v15
	v_add3_u32 v206, s33, v17, v14
	v_bitop3_b32 v15, v15, v16, v18 bitop3:0x36
	s_waitcnt vmcnt(6)
	s_barrier
	v_add_u32_e32 v112, s33, v12
	v_add_u32_e32 v168, s86, v12
	v_add3_u32 v12, 16, v17, v0
	v_add3_u32 v0, 16, v15, v0
	v_add3_u32 v207, s86, v17, v14
	v_add3_u32 v208, s85, v17, v14
	v_add3_u32 v209, s94, v17, v14
	ds_read_b128 v[14:17], v206
	ds_read_b128 v[18:21], v206 offset:1024
	ds_read_b128 v[22:25], v206 offset:2048
	ds_read_b128 v[26:29], v206 offset:3072
	v_add_u32_e32 v62, 0xc000, v131
	v_add_u32_e32 v63, 0xc000, v144
	v_add_u32_e32 v113, s33, v13
	v_add_u32_e32 v13, s86, v13
	s_or_b32 s47, s43, 0x80
	v_add_u32_e32 v184, 0x4000, v131
	v_add_u32_e32 v194, 0x4000, v144
	s_mul_hi_i32 s46, s47, 0x600
	s_mulk_i32 s47, 0x600
	s_add_u32 s54, s25, s47
	v_readfirstlane_b32 s52, v62
	s_addc_u32 s55, s28, s46
	s_mov_b32 m0, s52
	v_readfirstlane_b32 s53, v63
	ds_read_b128 v[30:33], v12
	ds_read_b128 v[34:37], v12 offset:1024
	ds_read_b128 v[38:41], v0 offset:2048
	ds_read_b128 v[42:45], v0 offset:3072
	ds_read_b128 v[46:49], v0 offset:4096
	ds_read_b128 v[50:53], v0 offset:5120
	ds_read_b128 v[54:57], v0 offset:6144
	ds_read_b128 v[58:61], v0 offset:7168
	global_load_lds_dwordx4 v11, s[54:55]
	s_mov_b32 m0, s53
	s_nop 0
	global_load_lds_dwordx4 v10, s[54:55]
	s_waitcnt lgkmcnt(8)
	s_barrier
	s_waitcnt lgkmcnt(0)
	s_waitcnt lgkmcnt(0)
	v_mfma_f32_16x16x32_bf16 v[62:65], v[14:17], v[30:33], 0
	v_mfma_f32_16x16x32_bf16 v[66:69], v[22:25], v[30:33], 0
	v_mfma_f32_16x16x32_bf16 v[70:73], v[14:17], v[38:41], 0
	v_mfma_f32_16x16x32_bf16 v[74:77], v[22:25], v[38:41], 0
	v_mfma_f32_16x16x32_bf16 v[78:81], v[14:17], v[46:49], 0
	v_mfma_f32_16x16x32_bf16 v[82:85], v[22:25], v[46:49], 0
	v_mfma_f32_16x16x32_bf16 v[86:89], v[14:17], v[54:57], 0
	v_mfma_f32_16x16x32_bf16 v[90:93], v[22:25], v[54:57], 0
	v_mfma_f32_16x16x32_bf16 v[62:65], v[18:21], v[34:37], v[62:65]
	v_mfma_f32_16x16x32_bf16 v[66:69], v[26:29], v[34:37], v[66:69]
	v_mfma_f32_16x16x32_bf16 v[70:73], v[18:21], v[42:45], v[70:73]
	v_mfma_f32_16x16x32_bf16 v[74:77], v[26:29], v[42:45], v[74:77]
	v_mfma_f32_16x16x32_bf16 v[78:81], v[18:21], v[50:53], v[78:81]
	v_mfma_f32_16x16x32_bf16 v[82:85], v[26:29], v[50:53], v[82:85]
	v_mfma_f32_16x16x32_bf16 v[86:89], v[18:21], v[58:61], v[86:89]
	v_mfma_f32_16x16x32_bf16 v[90:93], v[26:29], v[58:61], v[90:93]
	s_barrier
	v_readfirstlane_b32 s54, v112
	v_lshl_add_u64 v[110:111], v[6:7], 0, s[36:37]
	s_mov_b32 m0, s54
	v_readfirstlane_b32 s54, v113
	ds_read_b128 v[94:97], v207
	ds_read_b128 v[98:101], v207 offset:1024
	ds_read_b128 v[102:105], v207 offset:2048
	ds_read_b128 v[106:109], v207 offset:3072
	global_load_lds_dwordx4 v[110:111], off
	v_lshl_add_u64 v[110:111], v[8:9], 0, s[36:37]
	s_mov_b32 m0, s54
	s_nop 0
	global_load_lds_dwordx4 v[110:111], off
	s_barrier
	s_waitcnt lgkmcnt(0)
	s_waitcnt lgkmcnt(0)
	v_mfma_f32_16x16x32_bf16 v[110:113], v[94:97], v[30:33], 0
	v_mfma_f32_16x16x32_bf16 v[30:33], v[102:105], v[30:33], 0
	v_mfma_f32_16x16x32_bf16 v[110:113], v[98:101], v[34:37], v[110:113]
	v_mfma_f32_16x16x32_bf16 v[30:33], v[106:109], v[34:37], v[30:33]
	v_mfma_f32_16x16x32_bf16 v[34:37], v[94:97], v[38:41], 0
	v_mfma_f32_16x16x32_bf16 v[38:41], v[102:105], v[38:41], 0
	v_mfma_f32_16x16x32_bf16 v[34:37], v[98:101], v[42:45], v[34:37]
	v_mfma_f32_16x16x32_bf16 v[38:41], v[106:109], v[42:45], v[38:41]
	v_mfma_f32_16x16x32_bf16 v[42:45], v[94:97], v[46:49], 0
	v_mfma_f32_16x16x32_bf16 v[46:49], v[102:105], v[46:49], 0
	v_mfma_f32_16x16x32_bf16 v[42:45], v[98:101], v[50:53], v[42:45]
	v_mfma_f32_16x16x32_bf16 v[46:49], v[106:109], v[50:53], v[46:49]
	v_mfma_f32_16x16x32_bf16 v[50:53], v[94:97], v[54:57], 0
	v_mfma_f32_16x16x32_bf16 v[54:57], v[102:105], v[54:57], 0
	v_mfma_f32_16x16x32_bf16 v[50:53], v[98:101], v[58:61], v[50:53]
	v_mfma_f32_16x16x32_bf16 v[54:57], v[106:109], v[58:61], v[54:57]
	s_add_u32 s54, s29, s23
	v_readfirstlane_b32 s56, v131
	s_addc_u32 s55, s31, s9
	s_mov_b32 m0, s56
	v_readfirstlane_b32 s56, v144
	s_barrier
	ds_read_b128 v[58:61], v12 offset:16384
	ds_read_b128 v[114:117], v12 offset:17408
	ds_read_b128 v[118:121], v0 offset:18432
	ds_read_b128 v[122:125], v0 offset:19456
	ds_read_b128 v[126:129], v0 offset:20480
	ds_read_b128 v[132:135], v0 offset:21504
	ds_read_b128 v[136:139], v0 offset:22528
	ds_read_b128 v[140:143], v0 offset:23552
	global_load_lds_dwordx4 v11, s[54:55]
	s_mov_b32 m0, s56
	s_nop 0
	global_load_lds_dwordx4 v10, s[54:55]
	s_barrier
	s_waitcnt lgkmcnt(0)
	s_waitcnt lgkmcnt(0)
	v_mfma_f32_16x16x32_bf16 v[144:147], v[14:17], v[58:61], 0
	v_mfma_f32_16x16x32_bf16 v[152:155], v[14:17], v[118:121], 0
	v_mfma_f32_16x16x32_bf16 v[160:163], v[14:17], v[126:129], 0
	v_mfma_f32_16x16x32_bf16 v[14:17], v[14:17], v[136:139], 0
	v_mfma_f32_16x16x32_bf16 v[144:147], v[18:21], v[114:117], v[144:147]
	v_mfma_f32_16x16x32_bf16 v[152:155], v[18:21], v[122:125], v[152:155]
	v_mfma_f32_16x16x32_bf16 v[160:163], v[18:21], v[132:135], v[160:163]
	v_mfma_f32_16x16x32_bf16 v[14:17], v[18:21], v[140:143], v[14:17]
	v_mfma_f32_16x16x32_bf16 v[18:21], v[22:25], v[136:139], 0
	v_mfma_f32_16x16x32_bf16 v[148:151], v[22:25], v[58:61], 0
	v_mfma_f32_16x16x32_bf16 v[156:159], v[22:25], v[118:121], 0
	v_mfma_f32_16x16x32_bf16 v[164:167], v[22:25], v[126:129], 0
	v_mfma_f32_16x16x32_bf16 v[18:21], v[26:29], v[140:143], v[18:21]
	v_mfma_f32_16x16x32_bf16 v[148:151], v[26:29], v[114:117], v[148:151]
	v_mfma_f32_16x16x32_bf16 v[156:159], v[26:29], v[122:125], v[156:159]
	v_mfma_f32_16x16x32_bf16 v[164:167], v[26:29], v[132:135], v[164:167]
	s_barrier
	v_readfirstlane_b32 s54, v168
	v_lshl_add_u64 v[22:23], v[4:5], 0, s[36:37]
	s_mov_b32 m0, s54
	v_readfirstlane_b32 s54, v13
	global_load_lds_dwordx4 v[22:23], off
	v_lshl_add_u64 v[22:23], v[2:3], 0, s[36:37]
	s_mov_b32 m0, s54
	s_nop 0
	global_load_lds_dwordx4 v[22:23], off
	s_waitcnt vmcnt(6)
	s_barrier
	v_mfma_f32_16x16x32_bf16 v[22:25], v[94:97], v[58:61], 0
	v_mfma_f32_16x16x32_bf16 v[26:29], v[102:105], v[58:61], 0
	v_mfma_f32_16x16x32_bf16 v[22:25], v[98:101], v[114:117], v[22:25]
	v_mfma_f32_16x16x32_bf16 v[26:29], v[106:109], v[114:117], v[26:29]
	v_mfma_f32_16x16x32_bf16 v[58:61], v[94:97], v[118:121], 0
	v_mfma_f32_16x16x32_bf16 v[114:117], v[102:105], v[118:121], 0
	v_mfma_f32_16x16x32_bf16 v[118:121], v[94:97], v[126:129], 0
	v_mfma_f32_16x16x32_bf16 v[94:97], v[94:97], v[136:139], 0
	v_mfma_f32_16x16x32_bf16 v[58:61], v[98:101], v[122:125], v[58:61]
	v_mfma_f32_16x16x32_bf16 v[114:117], v[106:109], v[122:125], v[114:117]
	v_mfma_f32_16x16x32_bf16 v[118:121], v[98:101], v[132:135], v[118:121]
	v_mfma_f32_16x16x32_bf16 v[122:125], v[102:105], v[126:129], 0
	v_mfma_f32_16x16x32_bf16 v[94:97], v[98:101], v[140:143], v[94:97]
	v_mfma_f32_16x16x32_bf16 v[98:101], v[102:105], v[136:139], 0
	v_mfma_f32_16x16x32_bf16 v[122:125], v[106:109], v[132:135], v[122:125]
	v_mfma_f32_16x16x32_bf16 v[98:101], v[106:109], v[140:143], v[98:101]
	s_barrier
	ds_read_b128 v[102:105], v208
	ds_read_b128 v[106:109], v208 offset:1024
	ds_read_b128 v[126:129], v208 offset:2048
	ds_read_b128 v[132:135], v208 offset:3072
	s_add_u32 s54, s29, s47
	v_readfirstlane_b32 s56, v184
	s_addc_u32 s55, s31, s46
	s_mov_b32 m0, s56
	v_readfirstlane_b32 s56, v194
	ds_read_b128 v[136:139], v12 offset:32768
	ds_read_b128 v[140:143], v12 offset:33792
	ds_read_b128 v[168:171], v0 offset:34816
	ds_read_b128 v[172:175], v0 offset:35840
	ds_read_b128 v[176:179], v0 offset:36864
	ds_read_b128 v[180:183], v0 offset:37888
	ds_read_b128 v[186:189], v0 offset:38912
	ds_read_b128 v[190:193], v0 offset:39936
	global_load_lds_dwordx4 v11, s[54:55]
	s_mov_b32 m0, s56
	s_nop 0
	global_load_lds_dwordx4 v10, s[54:55]
	s_waitcnt lgkmcnt(8)
	s_barrier
	s_waitcnt lgkmcnt(0)
	s_waitcnt lgkmcnt(0)
	v_mfma_f32_16x16x32_bf16 v[62:65], v[102:105], v[136:139], v[62:65]
	v_mfma_f32_16x16x32_bf16 v[66:69], v[126:129], v[136:139], v[66:69]
	v_mfma_f32_16x16x32_bf16 v[70:73], v[102:105], v[168:171], v[70:73]
	v_mfma_f32_16x16x32_bf16 v[74:77], v[126:129], v[168:171], v[74:77]
	v_mfma_f32_16x16x32_bf16 v[78:81], v[102:105], v[176:179], v[78:81]
	v_mfma_f32_16x16x32_bf16 v[82:85], v[126:129], v[176:179], v[82:85]
	v_mfma_f32_16x16x32_bf16 v[86:89], v[102:105], v[186:189], v[86:89]
	v_mfma_f32_16x16x32_bf16 v[90:93], v[126:129], v[186:189], v[90:93]
	v_mfma_f32_16x16x32_bf16 v[62:65], v[106:109], v[140:143], v[62:65]
	v_mfma_f32_16x16x32_bf16 v[66:69], v[132:135], v[140:143], v[66:69]
	v_mfma_f32_16x16x32_bf16 v[70:73], v[106:109], v[172:175], v[70:73]
	v_mfma_f32_16x16x32_bf16 v[74:77], v[132:135], v[172:175], v[74:77]
	v_mfma_f32_16x16x32_bf16 v[78:81], v[106:109], v[180:183], v[78:81]
	v_mfma_f32_16x16x32_bf16 v[82:85], v[132:135], v[180:183], v[82:85]
	v_mfma_f32_16x16x32_bf16 v[86:89], v[106:109], v[190:193], v[86:89]
	v_mfma_f32_16x16x32_bf16 v[90:93], v[132:135], v[190:193], v[90:93]
	s_barrier
	s_mov_b32 m0, s45
	v_lshl_add_u64 v[6:7], v[6:7], 0, s[60:61]
	ds_read_b128 v[194:197], v209
	ds_read_b128 v[198:201], v209 offset:1024
	ds_read_b128 v[202:205], v209 offset:2048
	ds_read_b128 v[218:221], v209 offset:3072
	global_load_lds_dwordx4 v[6:7], off
	v_lshl_add_u64 v[6:7], v[8:9], 0, s[60:61]
	s_mov_b32 m0, s44
	s_nop 0
	global_load_lds_dwordx4 v[6:7], off
	s_barrier
	s_waitcnt lgkmcnt(0)
	s_waitcnt lgkmcnt(0)
	v_mfma_f32_16x16x32_bf16 v[6:9], v[194:197], v[136:139], v[110:113]
	v_mfma_f32_16x16x32_bf16 v[30:33], v[202:205], v[136:139], v[30:33]
	v_mfma_f32_16x16x32_bf16 v[34:37], v[194:197], v[168:171], v[34:37]
	v_mfma_f32_16x16x32_bf16 v[38:41], v[202:205], v[168:171], v[38:41]
	v_mfma_f32_16x16x32_bf16 v[42:45], v[194:197], v[176:179], v[42:45]
	v_mfma_f32_16x16x32_bf16 v[46:49], v[202:205], v[176:179], v[46:49]
	v_mfma_f32_16x16x32_bf16 v[50:53], v[194:197], v[186:189], v[50:53]
	v_mfma_f32_16x16x32_bf16 v[54:57], v[202:205], v[186:189], v[54:57]
	v_mfma_f32_16x16x32_bf16 v[6:9], v[198:201], v[140:143], v[6:9]
	v_mfma_f32_16x16x32_bf16 v[30:33], v[218:221], v[140:143], v[30:33]
	v_mfma_f32_16x16x32_bf16 v[34:37], v[198:201], v[172:175], v[34:37]
	v_mfma_f32_16x16x32_bf16 v[38:41], v[218:221], v[172:175], v[38:41]
	v_mfma_f32_16x16x32_bf16 v[42:45], v[198:201], v[180:183], v[42:45]
	v_mfma_f32_16x16x32_bf16 v[46:49], v[218:221], v[180:183], v[46:49]
	v_mfma_f32_16x16x32_bf16 v[50:53], v[198:201], v[190:193], v[50:53]
	v_mfma_f32_16x16x32_bf16 v[54:57], v[218:221], v[190:193], v[54:57]
	s_add_u32 s44, s40, s23
	s_addc_u32 s45, s41, s9
	s_mov_b32 m0, s38
	s_barrier
	ds_read_b128 v[110:113], v12 offset:49152
	ds_read_b128 v[136:139], v12 offset:50176
	ds_read_b128 v[140:143], v0 offset:51200
	ds_read_b128 v[168:171], v0 offset:52224
	ds_read_b128 v[172:175], v0 offset:53248
	ds_read_b128 v[176:179], v0 offset:54272
	ds_read_b128 v[180:183], v0 offset:55296
	ds_read_b128 v[186:189], v0 offset:56320
	global_load_lds_dwordx4 v11, s[44:45]
	s_mov_b32 m0, s39
	s_nop 0
	global_load_lds_dwordx4 v10, s[44:45]
	s_barrier
	s_waitcnt lgkmcnt(0)
	s_waitcnt lgkmcnt(0)
	v_mfma_f32_16x16x32_bf16 v[14:17], v[102:105], v[180:183], v[14:17]
	v_mfma_f32_16x16x32_bf16 v[18:21], v[126:129], v[180:183], v[18:21]
	v_mfma_f32_16x16x32_bf16 v[144:147], v[102:105], v[110:113], v[144:147]
	v_mfma_f32_16x16x32_bf16 v[148:151], v[126:129], v[110:113], v[148:151]
	v_mfma_f32_16x16x32_bf16 v[152:155], v[102:105], v[140:143], v[152:155]
	v_mfma_f32_16x16x32_bf16 v[156:159], v[126:129], v[140:143], v[156:159]
	v_mfma_f32_16x16x32_bf16 v[160:163], v[102:105], v[172:175], v[160:163]
	v_mfma_f32_16x16x32_bf16 v[164:167], v[126:129], v[172:175], v[164:167]
	v_mfma_f32_16x16x32_bf16 v[14:17], v[106:109], v[186:189], v[14:17]
	v_mfma_f32_16x16x32_bf16 v[18:21], v[132:135], v[186:189], v[18:21]
	v_mfma_f32_16x16x32_bf16 v[144:147], v[106:109], v[136:139], v[144:147]
	v_mfma_f32_16x16x32_bf16 v[148:151], v[132:135], v[136:139], v[148:151]
	v_mfma_f32_16x16x32_bf16 v[152:155], v[106:109], v[168:171], v[152:155]
	v_mfma_f32_16x16x32_bf16 v[156:159], v[132:135], v[168:171], v[156:159]
	v_mfma_f32_16x16x32_bf16 v[160:163], v[106:109], v[176:179], v[160:163]
	v_mfma_f32_16x16x32_bf16 v[164:167], v[132:135], v[176:179], v[164:167]
	s_barrier
	s_mov_b32 m0, s8
	v_lshl_add_u64 v[4:5], v[4:5], 0, s[60:61]
	global_load_lds_dwordx4 v[4:5], off
	v_lshl_add_u64 v[2:3], v[2:3], 0, s[60:61]
	s_mov_b32 m0, s22
	s_nop 0
	global_load_lds_dwordx4 v[2:3], off
	s_waitcnt vmcnt(6)
	s_barrier
	v_mfma_f32_16x16x32_bf16 v[2:5], v[194:197], v[110:113], v[22:25]
	v_mfma_f32_16x16x32_bf16 v[22:25], v[202:205], v[110:113], v[26:29]
	v_mfma_f32_16x16x32_bf16 v[26:29], v[194:197], v[140:143], v[58:61]
	v_mfma_f32_16x16x32_bf16 v[58:61], v[202:205], v[140:143], v[114:117]
	v_mfma_f32_16x16x32_bf16 v[102:105], v[194:197], v[172:175], v[118:121]
	v_mfma_f32_16x16x32_bf16 v[106:109], v[202:205], v[172:175], v[122:125]
	v_mfma_f32_16x16x32_bf16 v[94:97], v[194:197], v[180:183], v[94:97]
	v_mfma_f32_16x16x32_bf16 v[98:101], v[202:205], v[180:183], v[98:101]
	v_mfma_f32_16x16x32_bf16 v[2:5], v[198:201], v[136:139], v[2:5]
	v_mfma_f32_16x16x32_bf16 v[22:25], v[218:221], v[136:139], v[22:25]
	v_mfma_f32_16x16x32_bf16 v[26:29], v[198:201], v[168:171], v[26:29]
	v_mfma_f32_16x16x32_bf16 v[58:61], v[218:221], v[168:171], v[58:61]
	v_mfma_f32_16x16x32_bf16 v[102:105], v[198:201], v[176:179], v[102:105]
	v_mfma_f32_16x16x32_bf16 v[106:109], v[218:221], v[176:179], v[106:109]
	v_mfma_f32_16x16x32_bf16 v[94:97], v[198:201], v[186:189], v[94:97]
	v_mfma_f32_16x16x32_bf16 v[98:101], v[218:221], v[186:189], v[98:101]
	s_add_u32 s8, s40, s47
	s_addc_u32 s9, s41, s46
	s_mov_b32 m0, s52
	s_barrier
	ds_read_b128 v[110:113], v206
	ds_read_b128 v[114:117], v206 offset:1024
	ds_read_b128 v[118:121], v206 offset:2048
	ds_read_b128 v[122:125], v206 offset:3072
	ds_read_b128 v[126:129], v12
	ds_read_b128 v[132:135], v12 offset:1024
	ds_read_b128 v[136:139], v0 offset:2048
	ds_read_b128 v[140:143], v0 offset:3072
	ds_read_b128 v[168:171], v0 offset:4096
	ds_read_b128 v[172:175], v0 offset:5120
	ds_read_b128 v[176:179], v0 offset:6144
	ds_read_b128 v[180:183], v0 offset:7168
	global_load_lds_dwordx4 v11, s[8:9]
	s_mov_b32 m0, s53
	s_nop 0
	global_load_lds_dwordx4 v10, s[8:9]
	s_barrier
	s_waitcnt lgkmcnt(0)
	s_waitcnt lgkmcnt(0)
	v_mfma_f32_16x16x32_bf16 v[62:65], v[110:113], v[126:129], v[62:65]
	v_mfma_f32_16x16x32_bf16 v[66:69], v[118:121], v[126:129], v[66:69]
	v_mfma_f32_16x16x32_bf16 v[70:73], v[110:113], v[136:139], v[70:73]
	v_mfma_f32_16x16x32_bf16 v[74:77], v[118:121], v[136:139], v[74:77]
	v_mfma_f32_16x16x32_bf16 v[78:81], v[110:113], v[168:171], v[78:81]
	v_mfma_f32_16x16x32_bf16 v[82:85], v[118:121], v[168:171], v[82:85]
	v_mfma_f32_16x16x32_bf16 v[86:89], v[110:113], v[176:179], v[86:89]
	v_mfma_f32_16x16x32_bf16 v[62:65], v[114:117], v[132:135], v[62:65]
	v_mfma_f32_16x16x32_bf16 v[66:69], v[122:125], v[132:135], v[66:69]
	v_mfma_f32_16x16x32_bf16 v[70:73], v[114:117], v[140:143], v[70:73]
	v_mfma_f32_16x16x32_bf16 v[74:77], v[122:125], v[140:143], v[74:77]
	v_mfma_f32_16x16x32_bf16 v[78:81], v[114:117], v[172:175], v[78:81]
	v_mfma_f32_16x16x32_bf16 v[82:85], v[122:125], v[172:175], v[82:85]
	v_mfma_f32_16x16x32_bf16 v[86:89], v[114:117], v[180:183], v[86:89]
	v_mfma_f32_16x16x32_bf16 v[90:93], v[118:121], v[176:179], v[90:93]
	v_mfma_f32_16x16x32_bf16 v[186:189], v[122:125], v[180:183], v[90:93]
	s_barrier
	s_nop 4
	ds_read_b128 v[90:93], v207
	ds_read_b128 v[190:193], v207 offset:1024
	ds_read_b128 v[194:197], v207 offset:2048
	ds_read_b128 v[198:201], v207 offset:3072
	s_barrier
	s_waitcnt lgkmcnt(0)
	s_waitcnt lgkmcnt(0)
	v_mfma_f32_16x16x32_bf16 v[6:9], v[90:93], v[126:129], v[6:9]
	v_mfma_f32_16x16x32_bf16 v[30:33], v[194:197], v[126:129], v[30:33]
	v_mfma_f32_16x16x32_bf16 v[34:37], v[90:93], v[136:139], v[34:37]
	v_mfma_f32_16x16x32_bf16 v[38:41], v[194:197], v[136:139], v[38:41]
	v_mfma_f32_16x16x32_bf16 v[42:45], v[90:93], v[168:171], v[42:45]
	v_mfma_f32_16x16x32_bf16 v[46:49], v[194:197], v[168:171], v[46:49]
	v_mfma_f32_16x16x32_bf16 v[50:53], v[90:93], v[176:179], v[50:53]
	v_mfma_f32_16x16x32_bf16 v[54:57], v[194:197], v[176:179], v[54:57]
	v_mfma_f32_16x16x32_bf16 v[6:9], v[190:193], v[132:135], v[6:9]
	v_mfma_f32_16x16x32_bf16 v[30:33], v[198:201], v[132:135], v[30:33]
	v_mfma_f32_16x16x32_bf16 v[34:37], v[190:193], v[140:143], v[34:37]
	v_mfma_f32_16x16x32_bf16 v[38:41], v[198:201], v[140:143], v[38:41]
	v_mfma_f32_16x16x32_bf16 v[42:45], v[190:193], v[172:175], v[42:45]
	v_mfma_f32_16x16x32_bf16 v[46:49], v[198:201], v[172:175], v[46:49]
	v_mfma_f32_16x16x32_bf16 v[50:53], v[190:193], v[180:183], v[50:53]
	v_mfma_f32_16x16x32_bf16 v[54:57], v[198:201], v[180:183], v[54:57]
	s_barrier
	ds_read_b128 v[126:129], v12 offset:16384
	ds_read_b128 v[132:135], v12 offset:17408
	ds_read_b128 v[136:139], v0 offset:18432
	ds_read_b128 v[140:143], v0 offset:19456
	ds_read_b128 v[168:171], v0 offset:20480
	ds_read_b128 v[172:175], v0 offset:21504
	ds_read_b128 v[176:179], v0 offset:22528
	ds_read_b128 v[180:183], v0 offset:23552
	s_waitcnt vmcnt(4)
	s_barrier
	s_waitcnt lgkmcnt(0)
	s_waitcnt lgkmcnt(0)
	v_mfma_f32_16x16x32_bf16 v[14:17], v[110:113], v[176:179], v[14:17]
	v_mfma_f32_16x16x32_bf16 v[18:21], v[118:121], v[176:179], v[18:21]
	v_mfma_f32_16x16x32_bf16 v[144:147], v[110:113], v[126:129], v[144:147]
	v_mfma_f32_16x16x32_bf16 v[148:151], v[118:121], v[126:129], v[148:151]
	v_mfma_f32_16x16x32_bf16 v[152:155], v[110:113], v[136:139], v[152:155]
	v_mfma_f32_16x16x32_bf16 v[156:159], v[118:121], v[136:139], v[156:159]
	v_mfma_f32_16x16x32_bf16 v[160:163], v[110:113], v[168:171], v[160:163]
	v_mfma_f32_16x16x32_bf16 v[164:167], v[118:121], v[168:171], v[164:167]
	v_mfma_f32_16x16x32_bf16 v[14:17], v[114:117], v[180:183], v[14:17]
	v_mfma_f32_16x16x32_bf16 v[18:21], v[122:125], v[180:183], v[18:21]
	v_mfma_f32_16x16x32_bf16 v[144:147], v[114:117], v[132:135], v[144:147]
	v_mfma_f32_16x16x32_bf16 v[148:151], v[122:125], v[132:135], v[148:151]
	v_mfma_f32_16x16x32_bf16 v[152:155], v[114:117], v[140:143], v[152:155]
	v_mfma_f32_16x16x32_bf16 v[156:159], v[122:125], v[140:143], v[156:159]
	v_mfma_f32_16x16x32_bf16 v[160:163], v[114:117], v[172:175], v[160:163]
	v_mfma_f32_16x16x32_bf16 v[164:167], v[122:125], v[172:175], v[164:167]
	v_mfma_f32_16x16x32_bf16 v[2:5], v[90:93], v[126:129], v[2:5]
	v_mfma_f32_16x16x32_bf16 v[22:25], v[194:197], v[126:129], v[22:25]
	v_mfma_f32_16x16x32_bf16 v[26:29], v[90:93], v[136:139], v[26:29]
	v_mfma_f32_16x16x32_bf16 v[2:5], v[190:193], v[132:135], v[2:5]
	v_mfma_f32_16x16x32_bf16 v[22:25], v[198:201], v[132:135], v[22:25]
	v_mfma_f32_16x16x32_bf16 v[132:135], v[190:193], v[140:143], v[26:29]
	v_mfma_f32_16x16x32_bf16 v[26:29], v[194:197], v[136:139], v[58:61]
	v_mfma_f32_16x16x32_bf16 v[136:139], v[198:201], v[140:143], v[26:29]
	v_mfma_f32_16x16x32_bf16 v[26:29], v[90:93], v[168:171], v[102:105]
	v_mfma_f32_16x16x32_bf16 v[140:143], v[190:193], v[172:175], v[26:29]
	v_mfma_f32_16x16x32_bf16 v[26:29], v[194:197], v[168:171], v[106:109]
	v_mfma_f32_16x16x32_bf16 v[168:171], v[198:201], v[172:175], v[26:29]
	v_mfma_f32_16x16x32_bf16 v[26:29], v[90:93], v[176:179], v[94:97]
	v_mfma_f32_16x16x32_bf16 v[172:175], v[190:193], v[180:183], v[26:29]
	v_mfma_f32_16x16x32_bf16 v[26:29], v[194:197], v[176:179], v[98:101]
	v_mfma_f32_16x16x32_bf16 v[176:179], v[198:201], v[180:183], v[26:29]
	s_barrier
	ds_read_b128 v[180:183], v208
	ds_read_b128 v[190:193], v208 offset:1024
	ds_read_b128 v[194:197], v208 offset:2048
	ds_read_b128 v[198:201], v208 offset:3072
	s_nop 0
	ds_read_b128 v[26:29], v12 offset:32768
	ds_read_b128 v[58:61], v12 offset:33792
	ds_read_b128 v[98:101], v0 offset:34816
	ds_read_b128 v[202:205], v0 offset:35840
	ds_read_b128 v[218:221], v0 offset:36864
	ds_read_b128 v[222:225], v0 offset:37888
	ds_read_b128 v[226:229], v0 offset:38912
	ds_read_b128 v[230:233], v0 offset:39936
	s_waitcnt vmcnt(2)
	s_barrier
	s_waitcnt lgkmcnt(0)
	s_waitcnt lgkmcnt(0)
	v_mfma_f32_16x16x32_bf16 v[62:65], v[180:183], v[26:29], v[62:65]
	v_mfma_f32_16x16x32_bf16 v[126:129], v[190:193], v[58:61], v[62:65]
	v_mfma_f32_16x16x32_bf16 v[62:65], v[194:197], v[26:29], v[66:69]
	v_mfma_f32_16x16x32_bf16 v[122:125], v[198:201], v[58:61], v[62:65]
	v_mfma_f32_16x16x32_bf16 v[62:65], v[180:183], v[98:101], v[70:73]
	v_mfma_f32_16x16x32_bf16 v[110:113], v[190:193], v[202:205], v[62:65]
	v_mfma_f32_16x16x32_bf16 v[62:65], v[194:197], v[98:101], v[74:77]
	v_mfma_f32_16x16x32_bf16 v[106:109], v[198:201], v[202:205], v[62:65]
	v_mfma_f32_16x16x32_bf16 v[62:65], v[180:183], v[218:221], v[78:81]
	v_mfma_f32_16x16x32_bf16 v[94:97], v[190:193], v[222:225], v[62:65]
	v_mfma_f32_16x16x32_bf16 v[62:65], v[194:197], v[218:221], v[82:85]
	v_mfma_f32_16x16x32_bf16 v[90:93], v[198:201], v[222:225], v[62:65]
	v_mfma_f32_16x16x32_bf16 v[62:65], v[180:183], v[226:229], v[86:89]
	v_mfma_f32_16x16x32_bf16 v[78:81], v[190:193], v[230:233], v[62:65]
	v_mfma_f32_16x16x32_bf16 v[62:65], v[194:197], v[226:229], v[186:189]
	v_mfma_f32_16x16x32_bf16 v[74:77], v[198:201], v[230:233], v[62:65]
	s_barrier
	ds_read_b128 v[186:189], v209
	ds_read_b128 v[234:237], v209 offset:1024
	ds_read_b128 v[238:241], v209 offset:2048
	ds_read_b128 v[242:245], v209 offset:3072
	s_waitcnt vmcnt(0)
	s_barrier
	s_waitcnt lgkmcnt(0)
	s_waitcnt lgkmcnt(0)
	v_mfma_f32_16x16x32_bf16 v[6:9], v[186:189], v[26:29], v[6:9]
	v_mfma_f32_16x16x32_bf16 v[118:121], v[234:237], v[58:61], v[6:9]
	v_mfma_f32_16x16x32_bf16 v[6:9], v[238:241], v[26:29], v[30:33]
	v_mfma_f32_16x16x32_bf16 v[114:117], v[242:245], v[58:61], v[6:9]
	v_mfma_f32_16x16x32_bf16 v[6:9], v[186:189], v[98:101], v[34:37]
	v_mfma_f32_16x16x32_bf16 v[102:105], v[234:237], v[202:205], v[6:9]
	v_mfma_f32_16x16x32_bf16 v[6:9], v[238:241], v[98:101], v[38:41]
	v_mfma_f32_16x16x32_bf16 v[98:101], v[242:245], v[202:205], v[6:9]
	v_mfma_f32_16x16x32_bf16 v[6:9], v[186:189], v[218:221], v[42:45]
	v_mfma_f32_16x16x32_bf16 v[86:89], v[234:237], v[222:225], v[6:9]
	v_mfma_f32_16x16x32_bf16 v[6:9], v[238:241], v[218:221], v[46:49]
	v_mfma_f32_16x16x32_bf16 v[82:85], v[242:245], v[222:225], v[6:9]
	v_mfma_f32_16x16x32_bf16 v[6:9], v[186:189], v[226:229], v[50:53]
	v_mfma_f32_16x16x32_bf16 v[70:73], v[234:237], v[230:233], v[6:9]
	v_mfma_f32_16x16x32_bf16 v[6:9], v[238:241], v[226:229], v[54:57]
	v_mfma_f32_16x16x32_bf16 v[66:69], v[242:245], v[230:233], v[6:9]
	s_barrier
	s_nop 4
	ds_read_b128 v[6:9], v12 offset:49152
	ds_read_b128 v[34:37], v12 offset:50176
	ds_read_b128 v[202:205], v0 offset:51200
	ds_read_b128 v[218:221], v0 offset:52224
	ds_read_b128 v[222:225], v0 offset:53248
	ds_read_b128 v[226:229], v0 offset:54272
	ds_read_b128 v[230:233], v0 offset:55296
	ds_read_b128 v[246:249], v0 offset:56320
	s_barrier
	s_waitcnt lgkmcnt(0)
	s_waitcnt lgkmcnt(0)
	v_mfma_f32_16x16x32_bf16 v[10:13], v[180:183], v[6:9], v[144:147]
	v_mfma_f32_16x16x32_bf16 v[62:65], v[190:193], v[34:37], v[10:13]
	v_mfma_f32_16x16x32_bf16 v[10:13], v[194:197], v[6:9], v[148:151]
	v_mfma_f32_16x16x32_bf16 v[58:61], v[198:201], v[34:37], v[10:13]
	v_mfma_f32_16x16x32_bf16 v[10:13], v[180:183], v[202:205], v[152:155]
	v_mfma_f32_16x16x32_bf16 v[46:49], v[190:193], v[218:221], v[10:13]
	v_mfma_f32_16x16x32_bf16 v[10:13], v[194:197], v[202:205], v[156:159]
	v_mfma_f32_16x16x32_bf16 v[42:45], v[198:201], v[218:221], v[10:13]
	v_mfma_f32_16x16x32_bf16 v[10:13], v[180:183], v[222:225], v[160:163]
	v_mfma_f32_16x16x32_bf16 v[30:33], v[190:193], v[226:229], v[10:13]
	v_mfma_f32_16x16x32_bf16 v[10:13], v[194:197], v[222:225], v[164:167]
	v_mfma_f32_16x16x32_bf16 v[26:29], v[198:201], v[226:229], v[10:13]
	v_mfma_f32_16x16x32_bf16 v[10:13], v[180:183], v[230:233], v[14:17]
	v_mfma_f32_16x16x32_bf16 v[14:17], v[190:193], v[246:249], v[10:13]
	v_mfma_f32_16x16x32_bf16 v[10:13], v[194:197], v[230:233], v[18:21]
	v_mfma_f32_16x16x32_bf16 v[10:13], v[198:201], v[246:249], v[10:13]
	v_mfma_f32_16x16x32_bf16 v[2:5], v[186:189], v[6:9], v[2:5]
	v_mfma_f32_16x16x32_bf16 v[54:57], v[234:237], v[34:37], v[2:5]
	v_mfma_f32_16x16x32_bf16 v[2:5], v[238:241], v[6:9], v[22:25]
	v_mfma_f32_16x16x32_bf16 v[50:53], v[242:245], v[34:37], v[2:5]
	v_mfma_f32_16x16x32_bf16 v[2:5], v[186:189], v[202:205], v[132:135]
	v_mfma_f32_16x16x32_bf16 v[38:41], v[234:237], v[218:221], v[2:5]
	v_mfma_f32_16x16x32_bf16 v[2:5], v[238:241], v[202:205], v[136:139]
	v_mfma_f32_16x16x32_bf16 v[34:37], v[242:245], v[218:221], v[2:5]
	v_mfma_f32_16x16x32_bf16 v[2:5], v[186:189], v[222:225], v[140:143]
	v_mfma_f32_16x16x32_bf16 v[22:25], v[234:237], v[226:229], v[2:5]
	v_mfma_f32_16x16x32_bf16 v[2:5], v[238:241], v[222:225], v[168:171]
	v_mfma_f32_16x16x32_bf16 v[18:21], v[242:245], v[226:229], v[2:5]
	v_mfma_f32_16x16x32_bf16 v[2:5], v[186:189], v[230:233], v[172:175]
	v_mfma_f32_16x16x32_bf16 v[6:9], v[234:237], v[246:249], v[2:5]
	v_mfma_f32_16x16x32_bf16 v[2:5], v[238:241], v[230:233], v[176:179]
	v_mfma_f32_16x16x32_bf16 v[2:5], v[242:245], v[246:249], v[2:5]
	s_movk_i32 s1, 0x100
	v_cmp_gt_u32_e32 vcc, s1, v130
	s_barrier
	s_and_saveexec_b64 s[8:9], vcc
	s_cbranch_execz .LBB0_78
	s_barrier

.LBB0_121:
	s_and_saveexec_b64 s[44:45], s[8:9]
	s_cbranch_execz .LBB0_131
	s_bitcmp1_b32 s49, 0
	s_cselect_b32 s8, 0x4800, 0
	s_add_i32 s8, s8, 16
	v_add3_u32 v0, s8, v186, v224
	ds_read_b128 v[2:5], v0
	s_and_b64 s[2:3], s[16:17], s[2:3]
	v_cndmask_b32_e64 v6, 0, 1, s[2:3]
	v_cmp_ne_u32_e64 s[38:39], 1, v6
	s_andn2_b64 vcc, exec, s[2:3]
	ds_read_b128 v[6:9], v0 offset:32
	ds_read_b128 v[10:13], v0 offset:64
	s_waitcnt lgkmcnt(2)
	v_mfma_f32_32x32x16_bf16 v[112:127], v[2:5], v[144:147], 0
	v_mfma_f32_32x32x16_bf16 v[96:111], v[2:5], v[160:163], 0
	ds_read_b128 v[2:5], v0 offset:96
	s_waitcnt lgkmcnt(2)
	v_mfma_f32_32x32x16_bf16 v[112:127], v[6:9], v[148:151], v[112:127]
	v_mfma_f32_32x32x16_bf16 v[96:111], v[6:9], v[164:167], v[96:111]
	ds_read_b128 v[6:9], v0 offset:4608
	s_waitcnt lgkmcnt(2)
	v_mfma_f32_32x32x16_bf16 v[112:127], v[10:13], v[152:155], v[112:127]
	v_mfma_f32_32x32x16_bf16 v[96:111], v[10:13], v[168:171], v[96:111]
	ds_read_b128 v[10:13], v0 offset:4640
	s_waitcnt lgkmcnt(2)
	v_mfma_f32_32x32x16_bf16 v[112:127], v[2:5], v[156:159], v[112:127]
	v_mfma_f32_32x32x16_bf16 v[96:111], v[2:5], v[172:175], v[96:111]
	ds_read_b128 v[2:5], v0 offset:4672
	s_waitcnt lgkmcnt(2)
	v_mfma_f32_32x32x16_bf16 v[128:143], v[6:9], v[144:147], 0
	v_mfma_f32_32x32x16_bf16 v[80:95], v[6:9], v[160:163], 0
	ds_read_b128 v[6:9], v0 offset:4704
	v_add_u32_e32 v0, s48, v221
	s_waitcnt lgkmcnt(2)
	v_mfma_f32_32x32x16_bf16 v[128:143], v[10:13], v[148:151], v[128:143]
	v_mfma_f32_32x32x16_bf16 v[80:95], v[10:13], v[164:167], v[80:95]
	s_waitcnt lgkmcnt(1)
	v_mfma_f32_32x32x16_bf16 v[128:143], v[2:5], v[152:155], v[128:143]
	v_mfma_f32_32x32x16_bf16 v[80:95], v[2:5], v[168:171], v[80:95]
	s_waitcnt lgkmcnt(0)
	v_mfma_f32_32x32x16_bf16 v[128:143], v[6:9], v[156:159], v[128:143]
	v_mfma_f32_32x32x16_bf16 v[80:95], v[6:9], v[172:175], v[80:95]
	s_cbranch_vccnz .LBB0_124
	v_sub_u32_e32 v2, v0, v229
	s_movk_i32 s0, 0xfefe
	v_cmp_lt_u32_e32 vcc, s0, v2
	v_add_u32_e32 v3, 1, v2
	s_nop 0
	v_cndmask_b32_e32 v112, v210, v112, vcc
	v_cmp_lt_u32_e32 vcc, s0, v3
	v_add_u32_e32 v3, 2, v2
	s_nop 0
	v_cndmask_b32_e32 v113, v210, v113, vcc
	v_cmp_lt_u32_e32 vcc, s0, v3
	v_add_u32_e32 v3, 3, v2
	s_nop 0
	v_cndmask_b32_e32 v114, v210, v114, vcc
	v_cmp_lt_u32_e32 vcc, s0, v3
	v_add_u32_e32 v3, 8, v2
	s_nop 0
	v_cndmask_b32_e32 v115, v210, v115, vcc
	v_cmp_lt_u32_e32 vcc, s0, v3
	v_add_u32_e32 v3, 9, v2
	s_nop 0
	v_cndmask_b32_e32 v116, v210, v116, vcc
	v_cmp_lt_u32_e32 vcc, s0, v3
	v_add_u32_e32 v3, 10, v2
	s_nop 0
	v_cndmask_b32_e32 v117, v210, v117, vcc
	v_cmp_lt_u32_e32 vcc, s0, v3
	v_add_u32_e32 v3, 11, v2
	s_nop 0
	v_cndmask_b32_e32 v118, v210, v118, vcc
	v_cmp_lt_u32_e32 vcc, s0, v3
	v_add_u32_e32 v3, 16, v2
	s_nop 0
	v_cndmask_b32_e32 v119, v210, v119, vcc
	v_cmp_lt_u32_e32 vcc, s0, v3
	v_add_u32_e32 v3, 17, v2
	s_nop 0
	v_cndmask_b32_e32 v120, v210, v120, vcc
	v_cmp_lt_u32_e32 vcc, s0, v3
	v_add_u32_e32 v3, 18, v2
	s_nop 0
	v_cndmask_b32_e32 v121, v210, v121, vcc
	v_cmp_lt_u32_e32 vcc, s0, v3
	v_add_u32_e32 v3, 19, v2
	s_nop 0
	v_cndmask_b32_e32 v122, v210, v122, vcc
	v_cmp_lt_u32_e32 vcc, s0, v3
	v_add_u32_e32 v3, 24, v2
	s_nop 0
	v_cndmask_b32_e32 v123, v210, v123, vcc
	v_cmp_lt_u32_e32 vcc, s0, v3
	v_add_u32_e32 v3, 25, v2
	s_nop 0
	v_cndmask_b32_e32 v124, v210, v124, vcc
	v_cmp_lt_u32_e32 vcc, s0, v3
	v_add_u32_e32 v3, 26, v2
	s_nop 0
	v_cndmask_b32_e32 v125, v210, v125, vcc
	v_cmp_lt_u32_e32 vcc, s0, v3
	v_add_u32_e32 v3, 27, v2
	s_nop 0
	v_cndmask_b32_e32 v126, v210, v126, vcc
	v_cmp_lt_u32_e32 vcc, s0, v3
	v_add_u32_e32 v3, 32, v2
	s_nop 0
	v_cndmask_b32_e32 v127, v210, v127, vcc
	v_cmp_lt_u32_e32 vcc, s0, v3
	v_add_u32_e32 v3, 33, v2
	s_nop 0
	v_cndmask_b32_e32 v128, v210, v128, vcc
	v_cmp_lt_u32_e32 vcc, s0, v3
	v_add_u32_e32 v3, 34, v2
	s_nop 0
	v_cndmask_b32_e32 v129, v210, v129, vcc
	v_cmp_lt_u32_e32 vcc, s0, v3
	v_add_u32_e32 v3, 35, v2
	s_nop 0
	v_cndmask_b32_e32 v130, v210, v130, vcc
	v_cmp_lt_u32_e32 vcc, s0, v3
	v_add_u32_e32 v3, 40, v2
	s_nop 0
	v_cndmask_b32_e32 v131, v210, v131, vcc
	v_cmp_lt_u32_e32 vcc, s0, v3
	v_add_u32_e32 v3, 41, v2
	s_nop 0
	v_cndmask_b32_e32 v132, v210, v132, vcc
	v_cmp_lt_u32_e32 vcc, s0, v3
	v_add_u32_e32 v3, 42, v2
	s_nop 0
	v_cndmask_b32_e32 v133, v210, v133, vcc
	v_cmp_lt_u32_e32 vcc, s0, v3
	v_add_u32_e32 v3, 43, v2
	s_nop 0
	v_cndmask_b32_e32 v134, v210, v134, vcc
	v_cmp_lt_u32_e32 vcc, s0, v3
	v_add_u32_e32 v3, 48, v2
	s_nop 0
	v_cndmask_b32_e32 v135, v210, v135, vcc
	v_cmp_lt_u32_e32 vcc, s0, v3
	v_add_u32_e32 v3, 49, v2
	s_nop 0
	v_cndmask_b32_e32 v136, v210, v136, vcc
	v_cmp_lt_u32_e32 vcc, s0, v3
	v_add_u32_e32 v3, 50, v2
	s_nop 0
	v_cndmask_b32_e32 v137, v210, v137, vcc
	v_cmp_lt_u32_e32 vcc, s0, v3
	v_add_u32_e32 v3, 51, v2
	s_nop 0
	v_cndmask_b32_e32 v138, v210, v138, vcc
	v_cmp_lt_u32_e32 vcc, s0, v3
	v_add_u32_e32 v3, 56, v2
	s_nop 0
	v_cndmask_b32_e32 v139, v210, v139, vcc
	v_cmp_lt_u32_e32 vcc, s0, v3
	v_add_u32_e32 v3, 57, v2
	s_nop 0
	v_cndmask_b32_e32 v140, v210, v140, vcc
	v_cmp_lt_u32_e32 vcc, s0, v3
	v_add_u32_e32 v3, 58, v2
	v_add_u32_e32 v2, 59, v2
	v_cndmask_b32_e32 v141, v210, v141, vcc
	v_cmp_lt_u32_e32 vcc, s0, v3
	s_nop 1
	v_cndmask_b32_e32 v142, v210, v142, vcc
	v_cmp_lt_u32_e32 vcc, s0, v2
	s_nop 1
	v_cndmask_b32_e32 v143, v210, v143, vcc

.LBB0_258:
	ds_read_b128 v[172:175], v0
	ds_read_b128 v[176:179], v0 offset:1024
	ds_read_b128 v[180:183], v0 offset:2048
	ds_read_b128 v[186:189], v0 offset:3072
	s_add_i32 s40, s2, 0xffffff80
	s_ashr_i32 s41, s40, 31
	s_add_i32 s38, s2, 0xffffff40
	s_lshl_b64 s[46:47], s[40:41], 1
	s_add_u32 s3, s12, s46
	s_addc_u32 s17, s13, s47
	s_ashr_i32 s39, s38, 31
	s_lshl_b64 s[38:39], s[38:39], 1
	s_add_u32 s25, s84, s38
	s_addc_u32 s38, s85, s39
	s_add_u32 s25, s25, 0xfffff880
	s_addc_u32 s38, s38, -1
	s_cmpk_lt_i32 s40, 0x400
	s_cselect_b32 s3, s3, s25
	s_cselect_b32 s17, s17, s38
	s_add_u32 s38, s3, s10
	v_add_u32_e32 v184, 0xc000, v144
	s_addc_u32 s39, s17, s11
	v_readfirstlane_b32 s3, v184
	v_add_u32_e32 v184, 0xc000, v145
	v_add_u32_e32 v171, v164, v156
	v_lshl_add_u64 v[194:195], s[38:39], 0, v[132:133]
	s_mov_b32 m0, s3
	v_readfirstlane_b32 s3, v184
	ds_read_b128 v[190:193], v171
	ds_read_b128 v[198:201], v171 offset:1024
	ds_read_b128 v[202:205], v165
	ds_read_b128 v[218:221], v165 offset:1024
	ds_read_b128 v[222:225], v166
	ds_read_b128 v[226:229], v166 offset:1024
	ds_read_b128 v[230:233], v167
	ds_read_b128 v[234:237], v167 offset:1024
	global_load_lds_dwordx4 v[194:195], off
	v_lshl_add_u64 v[194:195], s[38:39], 0, v[130:131]
	s_mov_b32 m0, s3
	s_nop 0
	global_load_lds_dwordx4 v[194:195], off
	s_waitcnt lgkmcnt(8)
	s_barrier
	s_waitcnt lgkmcnt(0)
	s_waitcnt lgkmcnt(0)
	v_mfma_f32_16x16x32_bf16 v[118:121], v[172:175], v[190:193], v[118:121]
	v_mfma_f32_16x16x32_bf16 v[126:129], v[180:183], v[190:193], v[126:129]
	v_mfma_f32_16x16x32_bf16 v[122:125], v[172:175], v[202:205], v[122:125]
	v_mfma_f32_16x16x32_bf16 v[114:117], v[180:183], v[202:205], v[114:117]
	v_mfma_f32_16x16x32_bf16 v[110:113], v[172:175], v[222:225], v[110:113]
	v_mfma_f32_16x16x32_bf16 v[106:109], v[180:183], v[222:225], v[106:109]
	v_mfma_f32_16x16x32_bf16 v[102:105], v[172:175], v[230:233], v[102:105]
	v_mfma_f32_16x16x32_bf16 v[98:101], v[180:183], v[230:233], v[98:101]
	v_mfma_f32_16x16x32_bf16 v[118:121], v[176:179], v[198:201], v[118:121]
	v_mfma_f32_16x16x32_bf16 v[126:129], v[186:189], v[198:201], v[126:129]
	v_mfma_f32_16x16x32_bf16 v[122:125], v[176:179], v[218:221], v[122:125]
	v_mfma_f32_16x16x32_bf16 v[114:117], v[186:189], v[218:221], v[114:117]
	v_mfma_f32_16x16x32_bf16 v[110:113], v[176:179], v[226:229], v[110:113]
	v_mfma_f32_16x16x32_bf16 v[106:109], v[186:189], v[226:229], v[106:109]
	v_mfma_f32_16x16x32_bf16 v[102:105], v[176:179], v[234:237], v[102:105]
	v_mfma_f32_16x16x32_bf16 v[98:101], v[186:189], v[234:237], v[98:101]
	s_barrier
	v_add_u32_e32 v184, s33, v154
	v_lshl_add_u64 v[206:207], s[30:31], 0, v[140:141]
	v_readfirstlane_b32 s3, v184
	v_lshl_add_u64 v[214:215], v[206:207], 0, s[20:21]
	s_mov_b32 m0, s3
	v_add_u32_e32 v184, s33, v155
	ds_read_b128 v[238:241], v168
	ds_read_b128 v[242:245], v168 offset:1024
	ds_read_b128 v[246:249], v168 offset:2048
	ds_read_b128 v[194:197], v168 offset:3072
	global_load_lds_dwordx4 v[214:215], off
	v_lshl_add_u64 v[214:215], s[30:31], 0, v[138:139]
	v_readfirstlane_b32 s3, v184
	v_lshl_add_u64 v[250:251], v[214:215], 0, s[20:21]
	s_mov_b32 m0, s3
	s_add_i32 s9, s9, 2
	global_load_lds_dwordx4 v[250:251], off
	s_barrier
	s_waitcnt lgkmcnt(0)
	s_waitcnt lgkmcnt(0)
	v_mfma_f32_16x16x32_bf16 v[94:97], v[238:241], v[190:193], v[94:97]
	v_mfma_f32_16x16x32_bf16 v[90:93], v[246:249], v[190:193], v[90:93]
	v_mfma_f32_16x16x32_bf16 v[86:89], v[238:241], v[202:205], v[86:89]
	v_mfma_f32_16x16x32_bf16 v[82:85], v[246:249], v[202:205], v[82:85]
	v_mfma_f32_16x16x32_bf16 v[78:81], v[238:241], v[222:225], v[78:81]
	v_mfma_f32_16x16x32_bf16 v[74:77], v[246:249], v[222:225], v[74:77]
	v_mfma_f32_16x16x32_bf16 v[70:73], v[238:241], v[230:233], v[70:73]
	v_mfma_f32_16x16x32_bf16 v[66:69], v[246:249], v[230:233], v[66:69]
	v_mfma_f32_16x16x32_bf16 v[94:97], v[242:245], v[198:201], v[94:97]
	v_mfma_f32_16x16x32_bf16 v[90:93], v[194:197], v[198:201], v[90:93]
	v_mfma_f32_16x16x32_bf16 v[86:89], v[242:245], v[218:221], v[86:89]
	v_mfma_f32_16x16x32_bf16 v[82:85], v[194:197], v[218:221], v[82:85]
	v_mfma_f32_16x16x32_bf16 v[78:81], v[242:245], v[226:229], v[78:81]
	v_mfma_f32_16x16x32_bf16 v[74:77], v[194:197], v[226:229], v[74:77]
	v_mfma_f32_16x16x32_bf16 v[70:73], v[242:245], v[234:237], v[70:73]
	v_mfma_f32_16x16x32_bf16 v[66:69], v[194:197], v[234:237], v[66:69]
	s_sub_i32 s94, s2, 64
	s_lshl_b64 s[38:39], s[94:95], 1
	s_add_u32 s3, s12, s38
	s_addc_u32 s17, s13, s39
	s_add_u32 s25, s84, s38
	s_addc_u32 s38, s85, s39
	s_add_u32 s25, s25, 0xfffff800
	s_addc_u32 s38, s38, -1
	s_cmpk_lt_u32 s94, 0x400
	s_cselect_b32 s3, s3, s25
	s_cselect_b32 s17, s17, s38
	s_add_u32 s38, s3, s28
	s_addc_u32 s39, s17, s29
	v_readfirstlane_b32 s25, v144
	v_lshl_add_u64 v[250:251], s[38:39], 0, v[132:133]
	s_mov_b32 m0, s25
	v_readfirstlane_b32 s25, v145
	s_barrier
	ds_read_b128 v[190:193], v171 offset:16384
	ds_read_b128 v[198:201], v171 offset:17408
	ds_read_b128 v[202:205], v165 offset:16384
	ds_read_b128 v[218:221], v165 offset:17408
	ds_read_b128 v[222:225], v166 offset:16384
	ds_read_b128 v[226:229], v166 offset:17408
	ds_read_b128 v[230:233], v167 offset:16384
	ds_read_b128 v[234:237], v167 offset:17408
	global_load_lds_dwordx4 v[250:251], off
	v_lshl_add_u64 v[250:251], s[38:39], 0, v[130:131]
	s_mov_b32 m0, s25
	s_nop 0
	global_load_lds_dwordx4 v[250:251], off
	s_barrier
	s_waitcnt lgkmcnt(0)
	s_waitcnt lgkmcnt(0)
	v_mfma_f32_16x16x32_bf16 v[62:65], v[172:175], v[190:193], v[62:65]
	v_mfma_f32_16x16x32_bf16 v[58:61], v[180:183], v[190:193], v[58:61]
	v_mfma_f32_16x16x32_bf16 v[54:57], v[172:175], v[202:205], v[54:57]
	v_mfma_f32_16x16x32_bf16 v[50:53], v[180:183], v[202:205], v[50:53]
	v_mfma_f32_16x16x32_bf16 v[46:49], v[172:175], v[222:225], v[46:49]
	v_mfma_f32_16x16x32_bf16 v[42:45], v[180:183], v[222:225], v[42:45]
	v_mfma_f32_16x16x32_bf16 v[38:41], v[172:175], v[230:233], v[38:41]
	v_mfma_f32_16x16x32_bf16 v[34:37], v[180:183], v[230:233], v[34:37]
	v_mfma_f32_16x16x32_bf16 v[62:65], v[176:179], v[198:201], v[62:65]
	v_mfma_f32_16x16x32_bf16 v[58:61], v[186:189], v[198:201], v[58:61]
	v_mfma_f32_16x16x32_bf16 v[54:57], v[176:179], v[218:221], v[54:57]
	v_mfma_f32_16x16x32_bf16 v[50:53], v[186:189], v[218:221], v[50:53]
	v_mfma_f32_16x16x32_bf16 v[46:49], v[176:179], v[226:229], v[46:49]
	v_mfma_f32_16x16x32_bf16 v[42:45], v[186:189], v[226:229], v[42:45]
	v_mfma_f32_16x16x32_bf16 v[38:41], v[176:179], v[234:237], v[38:41]
	v_mfma_f32_16x16x32_bf16 v[34:37], v[186:189], v[234:237], v[34:37]
	s_barrier
	v_add_u32_e32 v174, s86, v154
	v_lshl_add_u64 v[250:251], s[30:31], 0, v[136:137]
	v_readfirstlane_b32 s25, v174
	v_add_u32_e32 v174, s86, v155
	v_lshl_add_u64 v[172:173], v[250:251], 0, s[20:21]
	s_mov_b32 m0, s25
	v_lshl_add_u64 v[208:209], s[30:31], 0, v[134:135]
	v_readfirstlane_b32 s25, v174
	global_load_lds_dwordx4 v[172:173], off
	v_lshl_add_u64 v[172:173], v[208:209], 0, s[20:21]
	s_mov_b32 m0, s25
	s_nop 0
	global_load_lds_dwordx4 v[172:173], off
	s_waitcnt vmcnt(6)
	s_barrier
	v_mfma_f32_16x16x32_bf16 v[30:33], v[238:241], v[190:193], v[30:33]
	v_mfma_f32_16x16x32_bf16 v[26:29], v[246:249], v[190:193], v[26:29]
	v_mfma_f32_16x16x32_bf16 v[22:25], v[238:241], v[202:205], v[22:25]
	v_mfma_f32_16x16x32_bf16 v[18:21], v[246:249], v[202:205], v[18:21]
	v_mfma_f32_16x16x32_bf16 v[14:17], v[238:241], v[222:225], v[14:17]
	v_mfma_f32_16x16x32_bf16 v[10:13], v[246:249], v[222:225], v[10:13]
	v_mfma_f32_16x16x32_bf16 v[6:9], v[238:241], v[230:233], v[6:9]
	v_mfma_f32_16x16x32_bf16 v[2:5], v[246:249], v[230:233], v[2:5]
	v_mfma_f32_16x16x32_bf16 v[30:33], v[242:245], v[198:201], v[30:33]
	v_mfma_f32_16x16x32_bf16 v[26:29], v[194:197], v[198:201], v[26:29]
	v_mfma_f32_16x16x32_bf16 v[22:25], v[242:245], v[218:221], v[22:25]
	v_mfma_f32_16x16x32_bf16 v[18:21], v[194:197], v[218:221], v[18:21]
	v_mfma_f32_16x16x32_bf16 v[14:17], v[242:245], v[226:229], v[14:17]
	v_mfma_f32_16x16x32_bf16 v[10:13], v[194:197], v[226:229], v[10:13]
	v_mfma_f32_16x16x32_bf16 v[6:9], v[242:245], v[234:237], v[6:9]
	v_mfma_f32_16x16x32_bf16 v[2:5], v[194:197], v[234:237], v[2:5]
	s_barrier
	ds_read_b128 v[172:175], v169
	ds_read_b128 v[176:179], v169 offset:1024
	ds_read_b128 v[180:183], v169 offset:2048
	ds_read_b128 v[186:189], v169 offset:3072
	s_add_u32 s38, s3, s10
	v_add_u32_e32 v184, 0x4000, v144
	s_addc_u32 s39, s17, s11
	v_readfirstlane_b32 s3, v184
	v_add_u32_e32 v184, 0x4000, v145
	v_lshl_add_u64 v[234:235], s[38:39], 0, v[132:133]
	s_mov_b32 m0, s3
	v_readfirstlane_b32 s3, v184
	ds_read_b128 v[190:193], v171 offset:32768
	ds_read_b128 v[194:197], v171 offset:33792
	ds_read_b128 v[198:201], v165 offset:32768
	ds_read_b128 v[202:205], v165 offset:33792
	ds_read_b128 v[218:221], v166 offset:32768
	ds_read_b128 v[222:225], v166 offset:33792
	ds_read_b128 v[226:229], v167 offset:32768
	ds_read_b128 v[230:233], v167 offset:33792
	global_load_lds_dwordx4 v[234:235], off
	v_lshl_add_u64 v[234:235], s[38:39], 0, v[130:131]
	s_mov_b32 m0, s3
	s_nop 0
	global_load_lds_dwordx4 v[234:235], off
	s_waitcnt lgkmcnt(8)
	s_barrier
	s_waitcnt lgkmcnt(0)
	s_waitcnt lgkmcnt(0)
	v_mfma_f32_16x16x32_bf16 v[118:121], v[172:175], v[190:193], v[118:121]
	v_mfma_f32_16x16x32_bf16 v[126:129], v[180:183], v[190:193], v[126:129]
	v_mfma_f32_16x16x32_bf16 v[122:125], v[172:175], v[198:201], v[122:125]
	v_mfma_f32_16x16x32_bf16 v[114:117], v[180:183], v[198:201], v[114:117]
	v_mfma_f32_16x16x32_bf16 v[110:113], v[172:175], v[218:221], v[110:113]
	v_mfma_f32_16x16x32_bf16 v[106:109], v[180:183], v[218:221], v[106:109]
	v_mfma_f32_16x16x32_bf16 v[102:105], v[172:175], v[226:229], v[102:105]
	v_mfma_f32_16x16x32_bf16 v[98:101], v[180:183], v[226:229], v[98:101]
	v_mfma_f32_16x16x32_bf16 v[118:121], v[176:179], v[194:197], v[118:121]
	v_mfma_f32_16x16x32_bf16 v[126:129], v[186:189], v[194:197], v[126:129]
	v_mfma_f32_16x16x32_bf16 v[122:125], v[176:179], v[202:205], v[122:125]
	v_mfma_f32_16x16x32_bf16 v[114:117], v[186:189], v[202:205], v[114:117]
	v_mfma_f32_16x16x32_bf16 v[110:113], v[176:179], v[222:225], v[110:113]
	v_mfma_f32_16x16x32_bf16 v[106:109], v[186:189], v[222:225], v[106:109]
	v_mfma_f32_16x16x32_bf16 v[102:105], v[176:179], v[230:233], v[102:105]
	v_mfma_f32_16x16x32_bf16 v[98:101], v[186:189], v[230:233], v[98:101]
	s_barrier
	v_readfirstlane_b32 s3, v158
	v_lshl_add_u64 v[206:207], v[206:207], 0, s[52:53]
	s_mov_b32 m0, s3
	v_readfirstlane_b32 s3, v159
	ds_read_b128 v[234:237], v170
	ds_read_b128 v[238:241], v170 offset:1024
	ds_read_b128 v[242:245], v170 offset:2048
	ds_read_b128 v[246:249], v170 offset:3072
	global_load_lds_dwordx4 v[206:207], off
	v_lshl_add_u64 v[206:207], v[214:215], 0, s[52:53]
	s_mov_b32 m0, s3
	s_nop 0
	global_load_lds_dwordx4 v[206:207], off
	s_barrier
	s_waitcnt lgkmcnt(0)
	s_waitcnt lgkmcnt(0)
	v_mfma_f32_16x16x32_bf16 v[94:97], v[234:237], v[190:193], v[94:97]
	v_mfma_f32_16x16x32_bf16 v[90:93], v[242:245], v[190:193], v[90:93]
	v_mfma_f32_16x16x32_bf16 v[86:89], v[234:237], v[198:201], v[86:89]
	v_mfma_f32_16x16x32_bf16 v[82:85], v[242:245], v[198:201], v[82:85]
	v_mfma_f32_16x16x32_bf16 v[78:81], v[234:237], v[218:221], v[78:81]
	v_mfma_f32_16x16x32_bf16 v[74:77], v[242:245], v[218:221], v[74:77]
	v_mfma_f32_16x16x32_bf16 v[70:73], v[234:237], v[226:229], v[70:73]
	v_mfma_f32_16x16x32_bf16 v[66:69], v[242:245], v[226:229], v[66:69]
	v_mfma_f32_16x16x32_bf16 v[94:97], v[238:241], v[194:197], v[94:97]
	v_mfma_f32_16x16x32_bf16 v[90:93], v[246:249], v[194:197], v[90:93]
	v_mfma_f32_16x16x32_bf16 v[86:89], v[238:241], v[202:205], v[86:89]
	v_mfma_f32_16x16x32_bf16 v[82:85], v[246:249], v[202:205], v[82:85]
	v_mfma_f32_16x16x32_bf16 v[78:81], v[238:241], v[222:225], v[78:81]
	v_mfma_f32_16x16x32_bf16 v[74:77], v[246:249], v[222:225], v[74:77]
	v_mfma_f32_16x16x32_bf16 v[70:73], v[238:241], v[230:233], v[70:73]
	v_mfma_f32_16x16x32_bf16 v[66:69], v[246:249], v[230:233], v[66:69]
	s_mov_b32 s3, s95
	s_lshl_b64 s[38:39], s[2:3], 1
	s_add_u32 s3, s12, s38
	s_addc_u32 s17, s13, s39
	s_add_u32 s25, s84, s38
	s_addc_u32 s38, s85, s39
	s_add_u32 s25, s25, 0xfffff800
	s_addc_u32 s38, s38, -1
	s_cmpk_lt_u32 s2, 0x400
	s_cselect_b32 s3, s3, s25
	s_cselect_b32 s17, s17, s38
	s_add_u32 s38, s3, s28
	s_addc_u32 s39, s17, s29
	v_readfirstlane_b32 s3, v160
	v_lshl_add_u64 v[206:207], s[38:39], 0, v[132:133]
	s_mov_b32 m0, s3
	v_readfirstlane_b32 s3, v161
	s_barrier
	ds_read_b128 v[190:193], v171 offset:49152
	ds_read_b128 v[194:197], v171 offset:50176
	ds_read_b128 v[198:201], v165 offset:49152
	ds_read_b128 v[202:205], v165 offset:50176
	ds_read_b128 v[218:221], v166 offset:49152
	ds_read_b128 v[222:225], v166 offset:50176
	ds_read_b128 v[226:229], v167 offset:49152
	ds_read_b128 v[230:233], v167 offset:50176
	global_load_lds_dwordx4 v[206:207], off
	v_lshl_add_u64 v[206:207], s[38:39], 0, v[130:131]
	s_mov_b32 m0, s3
	s_nop 0
	global_load_lds_dwordx4 v[206:207], off
	s_barrier
	s_waitcnt lgkmcnt(0)
	s_waitcnt lgkmcnt(0)
	v_mfma_f32_16x16x32_bf16 v[62:65], v[172:175], v[190:193], v[62:65]
	v_mfma_f32_16x16x32_bf16 v[58:61], v[180:183], v[190:193], v[58:61]
	v_mfma_f32_16x16x32_bf16 v[54:57], v[172:175], v[198:201], v[54:57]
	v_mfma_f32_16x16x32_bf16 v[50:53], v[180:183], v[198:201], v[50:53]
	v_mfma_f32_16x16x32_bf16 v[46:49], v[172:175], v[218:221], v[46:49]
	v_mfma_f32_16x16x32_bf16 v[42:45], v[180:183], v[218:221], v[42:45]
	v_mfma_f32_16x16x32_bf16 v[38:41], v[172:175], v[226:229], v[38:41]
	v_mfma_f32_16x16x32_bf16 v[34:37], v[180:183], v[226:229], v[34:37]
	v_mfma_f32_16x16x32_bf16 v[62:65], v[176:179], v[194:197], v[62:65]
	v_mfma_f32_16x16x32_bf16 v[58:61], v[186:189], v[194:197], v[58:61]
	v_mfma_f32_16x16x32_bf16 v[54:57], v[176:179], v[202:205], v[54:57]
	v_mfma_f32_16x16x32_bf16 v[50:53], v[186:189], v[202:205], v[50:53]
	v_mfma_f32_16x16x32_bf16 v[46:49], v[176:179], v[222:225], v[46:49]
	v_mfma_f32_16x16x32_bf16 v[42:45], v[186:189], v[222:225], v[42:45]
	v_mfma_f32_16x16x32_bf16 v[38:41], v[176:179], v[230:233], v[38:41]
	v_mfma_f32_16x16x32_bf16 v[34:37], v[186:189], v[230:233], v[34:37]
	s_barrier
	v_readfirstlane_b32 s3, v162
	v_lshl_add_u64 v[172:173], v[250:251], 0, s[52:53]
	s_mov_b32 m0, s3
	v_readfirstlane_b32 s3, v163
	global_load_lds_dwordx4 v[172:173], off
	v_lshl_add_u64 v[172:173], v[208:209], 0, s[52:53]
	s_mov_b32 m0, s3
	s_nop 0
	global_load_lds_dwordx4 v[172:173], off
	s_waitcnt vmcnt(6)
	s_barrier
	v_mfma_f32_16x16x32_bf16 v[30:33], v[234:237], v[190:193], v[30:33]
	v_mfma_f32_16x16x32_bf16 v[26:29], v[242:245], v[190:193], v[26:29]
	v_mfma_f32_16x16x32_bf16 v[22:25], v[234:237], v[198:201], v[22:25]
	v_mfma_f32_16x16x32_bf16 v[18:21], v[242:245], v[198:201], v[18:21]
	v_mfma_f32_16x16x32_bf16 v[14:17], v[234:237], v[218:221], v[14:17]
	v_mfma_f32_16x16x32_bf16 v[10:13], v[242:245], v[218:221], v[10:13]
	v_mfma_f32_16x16x32_bf16 v[6:9], v[234:237], v[226:229], v[6:9]
	v_mfma_f32_16x16x32_bf16 v[2:5], v[242:245], v[226:229], v[2:5]
	v_mfma_f32_16x16x32_bf16 v[30:33], v[238:241], v[194:197], v[30:33]
	v_mfma_f32_16x16x32_bf16 v[26:29], v[246:249], v[194:197], v[26:29]
	v_mfma_f32_16x16x32_bf16 v[22:25], v[238:241], v[202:205], v[22:25]
	v_mfma_f32_16x16x32_bf16 v[18:21], v[246:249], v[202:205], v[18:21]
	v_mfma_f32_16x16x32_bf16 v[14:17], v[238:241], v[222:225], v[14:17]
	v_mfma_f32_16x16x32_bf16 v[10:13], v[246:249], v[222:225], v[10:13]
	v_mfma_f32_16x16x32_bf16 v[6:9], v[238:241], v[230:233], v[6:9]
	v_mfma_f32_16x16x32_bf16 v[2:5], v[246:249], v[230:233], v[2:5]
	s_addk_i32 s2, 0x80
	s_add_u32 s30, s30, 0x100
	s_addc_u32 s31, s31, 0
	s_cmp_ge_i32 s9, s8
	s_barrier
	s_cbranch_scc0 .LBB0_258
	v_mov_b32_e32 v134, v157
	v_or_b32_e32 v135, 0x400, v143
	v_or_b32_e32 v136, 0x800, v143
	v_or_b32_e32 v137, 0xc00, v143
	v_mov_b32_e32 v140, v156
	s_mov_b32 s84, 0x8000
	v_readlane_b32 s85, v255, 4
	v_readlane_b32 s94, v255, 5
	v_mov_b32_e32 v250, 0x3a27c5ac
	v_mov_b32_e32 v251, 0x260
.LBB0_260:
	s_lshl_b32 s2, s49, 7
	s_add_u32 s3, s12, s2
	s_addc_u32 s8, s13, 0
	s_add_u32 s3, s3, 0xffffff80
	s_addc_u32 s8, s8, -1
	v_readlane_b32 s10, v255, 16
	v_readlane_b32 s11, v255, 17
	s_add_u32 s2, s10, s2
	s_addc_u32 s9, s11, 0
	v_add_u32_e32 v0, s33, v134
	s_add_u32 s2, s2, 0xfffff780
	v_add_u32_e32 v138, v0, v143
	s_addc_u32 s9, s9, -1
	v_add_u32_e32 v139, v0, v135
	ds_read_b128 v[154:157], v138
	ds_read_b128 v[158:161], v139
	v_add_u32_e32 v138, v0, v136
	v_add_u32_e32 v0, v0, v137
	s_cmp_lt_u32 s49, 17
	ds_read_b128 v[162:165], v138
	ds_read_b128 v[166:169], v0
	v_add_u32_e32 v0, 16, v146
	s_cselect_b32 s8, s8, s9
	s_cselect_b32 s9, s3, s2
	s_lshl_b64 s[2:3], s[18:19], 11
	v_add_u32_e32 v184, v0, v140
	v_add_u32_e32 v0, v0, v148
	v_add_u32_e32 v148, 16, v146
	s_add_u32 s2, s9, s2
	v_add_u32_e32 v144, 0xc000, v144
	v_add_u32_e32 v194, v148, v147
	v_add_u32_e32 v147, 16, v146
	v_add_u32_e32 v146, 16, v146
	s_addc_u32 s3, s8, s3
	v_readfirstlane_b32 s8, v144
	v_add_u32_e32 v196, v147, v149
	v_add_u32_e32 v206, v146, v151
	v_lshl_add_u64 v[132:133], s[2:3], 0, v[132:133]
	s_mov_b32 m0, s8
	ds_read_b128 v[138:141], v184
	ds_read_b128 v[170:173], v0
	v_add_u32_e32 v195, v148, v150
	ds_read_b128 v[174:177], v194
	ds_read_b128 v[178:181], v195
	v_add_u32_e32 v197, v147, v152
	ds_read_b128 v[186:189], v196
	ds_read_b128 v[190:193], v197
	v_add_u32_e32 v207, v146, v153
	ds_read_b128 v[146:149], v206
	ds_read_b128 v[150:153], v207
	global_load_lds_dwordx4 v[132:133], off
	v_add_u32_e32 v132, 0xc000, v145
	v_lshl_add_u64 v[130:131], s[2:3], 0, v[130:131]
	v_readfirstlane_b32 s2, v132
	s_mov_b32 m0, s2
	s_nop 0
	global_load_lds_dwordx4 v[130:131], off
	s_barrier
	s_waitcnt lgkmcnt(0)
	s_waitcnt lgkmcnt(0)
	v_mfma_f32_16x16x32_bf16 v[118:121], v[154:157], v[138:141], v[118:121]
	v_mfma_f32_16x16x32_bf16 v[126:129], v[162:165], v[138:141], v[126:129]
	v_mfma_f32_16x16x32_bf16 v[110:113], v[154:157], v[186:189], v[110:113]
	v_mfma_f32_16x16x32_bf16 v[102:105], v[154:157], v[146:149], v[102:105]
	v_mfma_f32_16x16x32_bf16 v[118:121], v[158:161], v[170:173], v[118:121]
	v_mfma_f32_16x16x32_bf16 v[126:129], v[166:169], v[170:173], v[126:129]
	v_mfma_f32_16x16x32_bf16 v[122:125], v[154:157], v[174:177], v[122:125]
	v_mfma_f32_16x16x32_bf16 v[114:117], v[162:165], v[174:177], v[114:117]
	v_mfma_f32_16x16x32_bf16 v[110:113], v[158:161], v[190:193], v[110:113]
	v_mfma_f32_16x16x32_bf16 v[106:109], v[162:165], v[186:189], v[106:109]
	v_mfma_f32_16x16x32_bf16 v[102:105], v[158:161], v[150:153], v[102:105]
	v_mfma_f32_16x16x32_bf16 v[98:101], v[162:165], v[146:149], v[98:101]
	v_mfma_f32_16x16x32_bf16 v[130:133], v[158:161], v[178:181], v[122:125]
	v_mfma_f32_16x16x32_bf16 v[198:201], v[166:169], v[178:181], v[114:117]
	v_mfma_f32_16x16x32_bf16 v[202:205], v[166:169], v[190:193], v[106:109]
	v_mfma_f32_16x16x32_bf16 v[218:221], v[166:169], v[150:153], v[98:101]
	v_add_u32_e32 v114, s86, v134
	s_nop 1
	v_add_u32_e32 v98, v114, v143
	v_add_u32_e32 v106, v114, v135
	v_add_u32_e32 v115, v114, v136
	v_add_u32_e32 v122, v114, v137
	s_barrier
	ds_read_b128 v[98:101], v98
	ds_read_b128 v[106:109], v106
	ds_read_b128 v[114:117], v115
	ds_read_b128 v[122:125], v122
	s_barrier
	s_waitcnt lgkmcnt(0)
	s_waitcnt lgkmcnt(0)
	v_mfma_f32_16x16x32_bf16 v[94:97], v[98:101], v[138:141], v[94:97]
	v_mfma_f32_16x16x32_bf16 v[90:93], v[114:117], v[138:141], v[90:93]
	v_mfma_f32_16x16x32_bf16 v[86:89], v[98:101], v[174:177], v[86:89]
	v_mfma_f32_16x16x32_bf16 v[82:85], v[114:117], v[174:177], v[82:85]
	v_mfma_f32_16x16x32_bf16 v[78:81], v[98:101], v[186:189], v[78:81]
	v_mfma_f32_16x16x32_bf16 v[74:77], v[114:117], v[186:189], v[74:77]
	v_mfma_f32_16x16x32_bf16 v[70:73], v[98:101], v[146:149], v[70:73]
	v_mfma_f32_16x16x32_bf16 v[66:69], v[114:117], v[146:149], v[66:69]
	v_mfma_f32_16x16x32_bf16 v[94:97], v[106:109], v[170:173], v[94:97]
	v_mfma_f32_16x16x32_bf16 v[90:93], v[122:125], v[170:173], v[90:93]
	v_mfma_f32_16x16x32_bf16 v[86:89], v[106:109], v[178:181], v[86:89]
	v_mfma_f32_16x16x32_bf16 v[82:85], v[122:125], v[178:181], v[82:85]
	v_mfma_f32_16x16x32_bf16 v[78:81], v[106:109], v[190:193], v[78:81]
	v_mfma_f32_16x16x32_bf16 v[74:77], v[122:125], v[190:193], v[74:77]
	v_mfma_f32_16x16x32_bf16 v[70:73], v[106:109], v[150:153], v[70:73]
	v_mfma_f32_16x16x32_bf16 v[66:69], v[122:125], v[150:153], v[66:69]
	s_barrier
	ds_read_b128 v[138:141], v184 offset:16384
	ds_read_b128 v[144:147], v0 offset:16384
	ds_read_b128 v[148:151], v194 offset:16384
	ds_read_b128 v[170:173], v195 offset:16384
	ds_read_b128 v[174:177], v196 offset:16384
	ds_read_b128 v[178:181], v197 offset:16384
	ds_read_b128 v[186:189], v206 offset:16384
	ds_read_b128 v[190:193], v207 offset:16384
	s_waitcnt vmcnt(4)
	s_barrier
	s_waitcnt lgkmcnt(0)
	s_waitcnt lgkmcnt(0)
	v_mfma_f32_16x16x32_bf16 v[62:65], v[154:157], v[138:141], v[62:65]
	v_mfma_f32_16x16x32_bf16 v[58:61], v[162:165], v[138:141], v[58:61]
	v_mfma_f32_16x16x32_bf16 v[54:57], v[154:157], v[148:151], v[54:57]
	v_mfma_f32_16x16x32_bf16 v[50:53], v[162:165], v[148:151], v[50:53]
	v_mfma_f32_16x16x32_bf16 v[46:49], v[154:157], v[174:177], v[46:49]
	v_mfma_f32_16x16x32_bf16 v[42:45], v[162:165], v[174:177], v[42:45]
	v_mfma_f32_16x16x32_bf16 v[38:41], v[154:157], v[186:189], v[38:41]
	v_mfma_f32_16x16x32_bf16 v[34:37], v[162:165], v[186:189], v[34:37]
	v_mfma_f32_16x16x32_bf16 v[222:225], v[158:161], v[144:147], v[62:65]
	v_mfma_f32_16x16x32_bf16 v[226:229], v[166:169], v[144:147], v[58:61]
	v_mfma_f32_16x16x32_bf16 v[230:233], v[158:161], v[170:173], v[54:57]
	v_mfma_f32_16x16x32_bf16 v[234:237], v[166:169], v[170:173], v[50:53]
	v_mfma_f32_16x16x32_bf16 v[238:241], v[158:161], v[178:181], v[46:49]
	v_mfma_f32_16x16x32_bf16 v[242:245], v[166:169], v[178:181], v[42:45]
	v_mfma_f32_16x16x32_bf16 v[152:155], v[158:161], v[190:193], v[38:41]
	v_mfma_f32_16x16x32_bf16 v[156:159], v[166:169], v[190:193], v[34:37]
	v_mfma_f32_16x16x32_bf16 v[30:33], v[98:101], v[138:141], v[30:33]
	v_mfma_f32_16x16x32_bf16 v[22:25], v[98:101], v[148:151], v[22:25]
	v_mfma_f32_16x16x32_bf16 v[14:17], v[98:101], v[174:177], v[14:17]
	v_mfma_f32_16x16x32_bf16 v[6:9], v[98:101], v[186:189], v[6:9]
	v_mfma_f32_16x16x32_bf16 v[30:33], v[106:109], v[144:147], v[30:33]
	v_mfma_f32_16x16x32_bf16 v[26:29], v[114:117], v[138:141], v[26:29]
	v_mfma_f32_16x16x32_bf16 v[22:25], v[106:109], v[170:173], v[22:25]
	v_mfma_f32_16x16x32_bf16 v[18:21], v[114:117], v[148:151], v[18:21]
	v_mfma_f32_16x16x32_bf16 v[14:17], v[106:109], v[178:181], v[14:17]
	v_mfma_f32_16x16x32_bf16 v[10:13], v[114:117], v[174:177], v[10:13]
	v_mfma_f32_16x16x32_bf16 v[6:9], v[106:109], v[190:193], v[6:9]
	v_mfma_f32_16x16x32_bf16 v[2:5], v[114:117], v[186:189], v[2:5]
	v_mfma_f32_16x16x32_bf16 v[138:141], v[122:125], v[144:147], v[26:29]
	v_mfma_f32_16x16x32_bf16 v[144:147], v[122:125], v[170:173], v[18:21]
	v_mfma_f32_16x16x32_bf16 v[148:151], v[122:125], v[178:181], v[10:13]
	v_mfma_f32_16x16x32_bf16 v[160:163], v[122:125], v[190:193], v[2:5]
	v_add_u32_e32 v18, s85, v134
	s_nop 1
	v_add_u32_e32 v2, v18, v143
	v_add_u32_e32 v10, v18, v135
	v_add_u32_e32 v19, v18, v136
	v_add_u32_e32 v26, v18, v137
	s_barrier
	ds_read_b128 v[2:5], v2
	ds_read_b128 v[10:13], v10
	ds_read_b128 v[18:21], v19
	ds_read_b128 v[26:29], v26
	ds_read_b128 v[34:37], v184 offset:32768
	ds_read_b128 v[38:41], v0 offset:32768
	ds_read_b128 v[42:45], v194 offset:32768
	ds_read_b128 v[46:49], v195 offset:32768
	ds_read_b128 v[164:167], v196 offset:32768
	ds_read_b128 v[168:171], v197 offset:32768
	ds_read_b128 v[172:175], v206 offset:32768
	ds_read_b128 v[176:179], v207 offset:32768
	s_waitcnt vmcnt(2)
	s_barrier
	s_waitcnt lgkmcnt(0)
	s_waitcnt lgkmcnt(0)
	v_mfma_f32_16x16x32_bf16 v[50:53], v[2:5], v[34:37], v[118:121]
	v_mfma_f32_16x16x32_bf16 v[122:125], v[10:13], v[38:41], v[50:53]
	v_mfma_f32_16x16x32_bf16 v[50:53], v[18:21], v[34:37], v[126:129]
	v_mfma_f32_16x16x32_bf16 v[126:129], v[26:29], v[38:41], v[50:53]
	v_mfma_f32_16x16x32_bf16 v[50:53], v[2:5], v[42:45], v[130:133]
	v_mfma_f32_16x16x32_bf16 v[114:117], v[10:13], v[46:49], v[50:53]
	v_mfma_f32_16x16x32_bf16 v[50:53], v[18:21], v[42:45], v[198:201]
	v_mfma_f32_16x16x32_bf16 v[118:121], v[26:29], v[46:49], v[50:53]
	v_mfma_f32_16x16x32_bf16 v[50:53], v[2:5], v[164:167], v[110:113]
	v_mfma_f32_16x16x32_bf16 v[106:109], v[10:13], v[168:171], v[50:53]
	v_mfma_f32_16x16x32_bf16 v[50:53], v[18:21], v[164:167], v[202:205]
	v_mfma_f32_16x16x32_bf16 v[110:113], v[26:29], v[168:171], v[50:53]
	v_mfma_f32_16x16x32_bf16 v[50:53], v[2:5], v[172:175], v[102:105]
	v_mfma_f32_16x16x32_bf16 v[98:101], v[10:13], v[176:179], v[50:53]
	v_mfma_f32_16x16x32_bf16 v[50:53], v[18:21], v[172:175], v[218:221]
	v_mfma_f32_16x16x32_bf16 v[102:105], v[26:29], v[176:179], v[50:53]
	s_nop 5
	v_add_u32_e32 v50, s94, v134
	v_add_u32_e32 v51, v50, v143
	s_barrier
	v_add_u32_e32 v52, v50, v135
	ds_read_b128 v[130:133], v51
	ds_read_b128 v[180:183], v52
	v_add_u32_e32 v51, v50, v136
	v_add_u32_e32 v50, v50, v137
	ds_read_b128 v[134:137], v51
	ds_read_b128 v[186:189], v50
	s_waitcnt vmcnt(0)
	s_barrier
	s_waitcnt lgkmcnt(0)
	s_waitcnt lgkmcnt(0)
	v_mfma_f32_16x16x32_bf16 v[50:53], v[130:133], v[34:37], v[94:97]
	v_mfma_f32_16x16x32_bf16 v[34:37], v[134:137], v[34:37], v[90:93]
	v_mfma_f32_16x16x32_bf16 v[62:65], v[186:189], v[38:41], v[34:37]
	v_mfma_f32_16x16x32_bf16 v[34:37], v[130:133], v[42:45], v[86:89]
	v_mfma_f32_16x16x32_bf16 v[58:61], v[180:183], v[38:41], v[50:53]
	v_mfma_f32_16x16x32_bf16 v[50:53], v[180:183], v[46:49], v[34:37]
	v_mfma_f32_16x16x32_bf16 v[34:37], v[134:137], v[42:45], v[82:85]
	v_mfma_f32_16x16x32_bf16 v[54:57], v[186:189], v[46:49], v[34:37]
	v_mfma_f32_16x16x32_bf16 v[34:37], v[130:133], v[164:167], v[78:81]
	v_mfma_f32_16x16x32_bf16 v[42:45], v[180:183], v[168:171], v[34:37]
	v_mfma_f32_16x16x32_bf16 v[34:37], v[134:137], v[164:167], v[74:77]
	v_mfma_f32_16x16x32_bf16 v[46:49], v[186:189], v[168:171], v[34:37]
	v_mfma_f32_16x16x32_bf16 v[34:37], v[130:133], v[172:175], v[70:73]
	v_mfma_f32_16x16x32_bf16 v[38:41], v[134:137], v[172:175], v[66:69]
	v_mfma_f32_16x16x32_bf16 v[34:37], v[180:183], v[176:179], v[34:37]
	v_mfma_f32_16x16x32_bf16 v[38:41], v[186:189], v[176:179], v[38:41]
	s_barrier
	ds_read_b128 v[164:167], v184 offset:49152
	ds_read_b128 v[168:171], v0 offset:49152
	ds_read_b128 v[172:175], v194 offset:49152
	ds_read_b128 v[176:179], v195 offset:49152
	ds_read_b128 v[190:193], v196 offset:49152
	ds_read_b128 v[198:201], v197 offset:49152
	ds_read_b128 v[202:205], v206 offset:49152
	ds_read_b128 v[218:221], v207 offset:49152
	s_barrier
	s_waitcnt lgkmcnt(0)
	s_waitcnt lgkmcnt(0)
	v_mfma_f32_16x16x32_bf16 v[66:69], v[2:5], v[164:167], v[222:225]
	v_mfma_f32_16x16x32_bf16 v[90:93], v[10:13], v[168:171], v[66:69]
	v_mfma_f32_16x16x32_bf16 v[66:69], v[18:21], v[164:167], v[226:229]
	v_mfma_f32_16x16x32_bf16 v[94:97], v[26:29], v[168:171], v[66:69]
	v_mfma_f32_16x16x32_bf16 v[66:69], v[2:5], v[172:175], v[230:233]
	v_mfma_f32_16x16x32_bf16 v[82:85], v[10:13], v[176:179], v[66:69]
	v_mfma_f32_16x16x32_bf16 v[66:69], v[18:21], v[172:175], v[234:237]
	v_mfma_f32_16x16x32_bf16 v[86:89], v[26:29], v[176:179], v[66:69]
	v_mfma_f32_16x16x32_bf16 v[66:69], v[2:5], v[190:193], v[238:241]
	v_mfma_f32_16x16x32_bf16 v[74:77], v[10:13], v[198:201], v[66:69]
	v_mfma_f32_16x16x32_bf16 v[66:69], v[18:21], v[190:193], v[242:245]
	v_mfma_f32_16x16x32_bf16 v[2:5], v[2:5], v[202:205], v[152:155]
	v_mfma_f32_16x16x32_bf16 v[78:81], v[26:29], v[198:201], v[66:69]
	v_mfma_f32_16x16x32_bf16 v[66:69], v[10:13], v[218:221], v[2:5]
	v_mfma_f32_16x16x32_bf16 v[2:5], v[18:21], v[202:205], v[156:159]
	v_mfma_f32_16x16x32_bf16 v[70:73], v[26:29], v[218:221], v[2:5]
	v_mfma_f32_16x16x32_bf16 v[2:5], v[130:133], v[164:167], v[30:33]
	v_mfma_f32_16x16x32_bf16 v[26:29], v[180:183], v[168:171], v[2:5]
	v_mfma_f32_16x16x32_bf16 v[2:5], v[134:137], v[164:167], v[138:141]
	v_mfma_f32_16x16x32_bf16 v[30:33], v[186:189], v[168:171], v[2:5]
	v_mfma_f32_16x16x32_bf16 v[2:5], v[130:133], v[172:175], v[22:25]
	v_mfma_f32_16x16x32_bf16 v[18:21], v[180:183], v[176:179], v[2:5]
	v_mfma_f32_16x16x32_bf16 v[2:5], v[134:137], v[172:175], v[144:147]
	v_mfma_f32_16x16x32_bf16 v[22:25], v[186:189], v[176:179], v[2:5]
	v_mfma_f32_16x16x32_bf16 v[2:5], v[130:133], v[190:193], v[14:17]
	v_mfma_f32_16x16x32_bf16 v[10:13], v[180:183], v[198:201], v[2:5]
	v_mfma_f32_16x16x32_bf16 v[2:5], v[134:137], v[190:193], v[148:151]
	v_mfma_f32_16x16x32_bf16 v[14:17], v[186:189], v[198:201], v[2:5]
	v_mfma_f32_16x16x32_bf16 v[2:5], v[130:133], v[202:205], v[6:9]
	v_mfma_f32_16x16x32_bf16 v[6:9], v[134:137], v[202:205], v[160:163]
	v_mfma_f32_16x16x32_bf16 v[2:5], v[180:183], v[218:221], v[2:5]
	v_mfma_f32_16x16x32_bf16 v[6:9], v[186:189], v[218:221], v[6:9]
	s_movk_i32 s0, 0x100
	v_cmp_gt_u32_e32 vcc, s0, v142
	s_barrier
	s_and_saveexec_b64 s[2:3], vcc
	s_cbranch_execz .LBB0_262
	s_barrier

.LBB0_839:
	ds_read_b128 v[170:173], v163
	ds_read_b128 v[174:177], v163 offset:1024
	ds_read_b128 v[178:181], v163 offset:2048
	ds_read_b128 v[186:189], v163 offset:3072
	s_add_i32 s39, s25, 64
	s_add_i32 s55, s52, s25
	s_ashr_i32 s56, s39, 31
	s_add_i32 s58, s55, 64
	s_cmp_lt_i32 s39, s14
	s_cselect_b32 s57, s56, 0
	s_cselect_b32 s56, s39, s58
	s_lshl_b64 s[56:57], s[56:57], 1
	s_add_u32 s56, s9, s56
	v_add_u32_e32 v206, 0xc000, v144
	s_addc_u32 s57, s17, s57
	v_readfirstlane_b32 s39, v206
	v_add_u32_e32 v206, 0xc000, v145
	v_add_u32_e32 v184, v162, v154
	v_lshl_add_u64 v[182:183], s[56:57], 0, v[0:1]
	s_mov_b32 m0, s39
	v_readfirstlane_b32 s39, v206
	ds_read_b128 v[190:193], v184
	ds_read_b128 v[194:197], v184 offset:1024
	ds_read_b128 v[198:201], v164
	ds_read_b128 v[202:205], v164 offset:1024
	ds_read_b128 v[218:221], v165
	ds_read_b128 v[222:225], v165 offset:1024
	ds_read_b128 v[226:229], v166
	ds_read_b128 v[230:233], v166 offset:1024
	global_load_lds_dwordx4 v[182:183], off
	v_lshl_add_u64 v[182:183], s[56:57], 0, v[130:131]
	s_mov_b32 m0, s39
	s_nop 0
	global_load_lds_dwordx4 v[182:183], off
	s_waitcnt lgkmcnt(8)
	s_barrier
	s_waitcnt lgkmcnt(0)
	s_waitcnt lgkmcnt(0)
	v_mfma_f32_16x16x32_bf16 v[118:121], v[170:173], v[190:193], v[118:121]
	v_mfma_f32_16x16x32_bf16 v[126:129], v[178:181], v[190:193], v[126:129]
	v_mfma_f32_16x16x32_bf16 v[122:125], v[170:173], v[198:201], v[122:125]
	v_mfma_f32_16x16x32_bf16 v[114:117], v[178:181], v[198:201], v[114:117]
	v_mfma_f32_16x16x32_bf16 v[110:113], v[170:173], v[218:221], v[110:113]
	v_mfma_f32_16x16x32_bf16 v[106:109], v[178:181], v[218:221], v[106:109]
	v_mfma_f32_16x16x32_bf16 v[102:105], v[170:173], v[226:229], v[102:105]
	v_mfma_f32_16x16x32_bf16 v[98:101], v[178:181], v[226:229], v[98:101]
	v_mfma_f32_16x16x32_bf16 v[118:121], v[174:177], v[194:197], v[118:121]
	v_mfma_f32_16x16x32_bf16 v[126:129], v[186:189], v[194:197], v[126:129]
	v_mfma_f32_16x16x32_bf16 v[122:125], v[174:177], v[202:205], v[122:125]
	v_mfma_f32_16x16x32_bf16 v[114:117], v[186:189], v[202:205], v[114:117]
	v_mfma_f32_16x16x32_bf16 v[110:113], v[174:177], v[222:225], v[110:113]
	v_mfma_f32_16x16x32_bf16 v[106:109], v[186:189], v[222:225], v[106:109]
	v_mfma_f32_16x16x32_bf16 v[102:105], v[174:177], v[230:233], v[102:105]
	v_mfma_f32_16x16x32_bf16 v[98:101], v[186:189], v[230:233], v[98:101]
	s_barrier
	v_add_u32_e32 v208, s33, v141
	v_lshl_add_u64 v[182:183], v[138:139], 0, s[2:3]
	v_readfirstlane_b32 s39, v208
	v_lshl_add_u64 v[206:207], v[182:183], 0, s[36:37]
	s_mov_b32 m0, s39
	v_add_u32_e32 v214, s33, v142
	ds_read_b128 v[234:237], v167
	ds_read_b128 v[238:241], v167 offset:1024
	ds_read_b128 v[242:245], v167 offset:2048
	ds_read_b128 v[246:249], v167 offset:3072
	global_load_lds_dwordx4 v[206:207], off
	v_lshl_add_u64 v[206:207], v[136:137], 0, s[2:3]
	v_readfirstlane_b32 s39, v214
	v_lshl_add_u64 v[208:209], v[206:207], 0, s[36:37]
	s_mov_b32 m0, s39
	s_add_i32 s24, s24, 2
	global_load_lds_dwordx4 v[208:209], off
	s_barrier
	s_waitcnt lgkmcnt(0)
	s_waitcnt lgkmcnt(0)
	v_mfma_f32_16x16x32_bf16 v[94:97], v[234:237], v[190:193], v[94:97]
	v_mfma_f32_16x16x32_bf16 v[90:93], v[242:245], v[190:193], v[90:93]
	v_mfma_f32_16x16x32_bf16 v[86:89], v[234:237], v[198:201], v[86:89]
	v_mfma_f32_16x16x32_bf16 v[82:85], v[242:245], v[198:201], v[82:85]
	v_mfma_f32_16x16x32_bf16 v[78:81], v[234:237], v[218:221], v[78:81]
	v_mfma_f32_16x16x32_bf16 v[74:77], v[242:245], v[218:221], v[74:77]
	v_mfma_f32_16x16x32_bf16 v[70:73], v[234:237], v[226:229], v[70:73]
	v_mfma_f32_16x16x32_bf16 v[66:69], v[242:245], v[226:229], v[66:69]
	v_mfma_f32_16x16x32_bf16 v[94:97], v[238:241], v[194:197], v[94:97]
	v_mfma_f32_16x16x32_bf16 v[90:93], v[246:249], v[194:197], v[90:93]
	v_mfma_f32_16x16x32_bf16 v[86:89], v[238:241], v[202:205], v[86:89]
	v_mfma_f32_16x16x32_bf16 v[82:85], v[246:249], v[202:205], v[82:85]
	v_mfma_f32_16x16x32_bf16 v[78:81], v[238:241], v[222:225], v[78:81]
	v_mfma_f32_16x16x32_bf16 v[74:77], v[246:249], v[222:225], v[74:77]
	v_mfma_f32_16x16x32_bf16 v[70:73], v[238:241], v[230:233], v[70:73]
	v_mfma_f32_16x16x32_bf16 v[66:69], v[246:249], v[230:233], v[66:69]
	s_add_i32 s39, s25, 0x80
	s_ashr_i32 s56, s39, 31
	s_add_i32 s58, s55, 0x80
	s_cmp_lt_i32 s39, s14
	s_cselect_b32 s57, s56, 0
	s_cselect_b32 s56, s39, s58
	s_lshl_b64 s[56:57], s[56:57], 1
	s_add_u32 s58, s10, s56
	s_addc_u32 s59, s11, s57
	v_readfirstlane_b32 s63, v144
	v_lshl_add_u64 v[208:209], s[58:59], 0, v[0:1]
	s_mov_b32 m0, s63
	s_barrier
	ds_read_b128 v[190:193], v184 offset:16384
	ds_read_b128 v[194:197], v184 offset:17408
	ds_read_b128 v[198:201], v164 offset:16384
	ds_read_b128 v[202:205], v164 offset:17408
	ds_read_b128 v[218:221], v165 offset:16384
	ds_read_b128 v[222:225], v165 offset:17408
	ds_read_b128 v[226:229], v166 offset:16384
	ds_read_b128 v[230:233], v166 offset:17408
	global_load_lds_dwordx4 v[208:209], off
	v_lshl_add_u64 v[208:209], s[58:59], 0, v[130:131]
	v_readfirstlane_b32 s58, v145
	s_mov_b32 m0, s58
	s_nop 0
	global_load_lds_dwordx4 v[208:209], off
	s_barrier
	s_waitcnt lgkmcnt(0)
	s_waitcnt lgkmcnt(0)
	v_mfma_f32_16x16x32_bf16 v[62:65], v[170:173], v[190:193], v[62:65]
	v_mfma_f32_16x16x32_bf16 v[58:61], v[178:181], v[190:193], v[58:61]
	v_mfma_f32_16x16x32_bf16 v[54:57], v[170:173], v[198:201], v[54:57]
	v_mfma_f32_16x16x32_bf16 v[50:53], v[178:181], v[198:201], v[50:53]
	v_mfma_f32_16x16x32_bf16 v[46:49], v[170:173], v[218:221], v[46:49]
	v_mfma_f32_16x16x32_bf16 v[42:45], v[178:181], v[218:221], v[42:45]
	v_mfma_f32_16x16x32_bf16 v[38:41], v[170:173], v[226:229], v[38:41]
	v_mfma_f32_16x16x32_bf16 v[34:37], v[178:181], v[226:229], v[34:37]
	v_mfma_f32_16x16x32_bf16 v[62:65], v[174:177], v[194:197], v[62:65]
	v_mfma_f32_16x16x32_bf16 v[58:61], v[186:189], v[194:197], v[58:61]
	v_mfma_f32_16x16x32_bf16 v[54:57], v[174:177], v[202:205], v[54:57]
	v_mfma_f32_16x16x32_bf16 v[50:53], v[186:189], v[202:205], v[50:53]
	v_mfma_f32_16x16x32_bf16 v[46:49], v[174:177], v[222:225], v[46:49]
	v_mfma_f32_16x16x32_bf16 v[42:45], v[186:189], v[222:225], v[42:45]
	v_mfma_f32_16x16x32_bf16 v[38:41], v[174:177], v[230:233], v[38:41]
	v_mfma_f32_16x16x32_bf16 v[34:37], v[186:189], v[230:233], v[34:37]
	s_barrier
	v_add_u32_e32 v172, s86, v141
	v_lshl_add_u64 v[208:209], v[134:135], 0, s[2:3]
	v_readfirstlane_b32 s58, v172
	v_add_u32_e32 v172, s86, v142
	v_lshl_add_u64 v[170:171], v[208:209], 0, s[36:37]
	s_mov_b32 m0, s58
	v_lshl_add_u64 v[214:215], v[132:133], 0, s[2:3]
	v_readfirstlane_b32 s58, v172
	global_load_lds_dwordx4 v[170:171], off
	v_lshl_add_u64 v[170:171], v[214:215], 0, s[36:37]
	s_mov_b32 m0, s58
	s_nop 0
	global_load_lds_dwordx4 v[170:171], off
	s_waitcnt vmcnt(6)
	s_barrier
	v_mfma_f32_16x16x32_bf16 v[30:33], v[234:237], v[190:193], v[30:33]
	v_mfma_f32_16x16x32_bf16 v[26:29], v[242:245], v[190:193], v[26:29]
	v_mfma_f32_16x16x32_bf16 v[22:25], v[234:237], v[198:201], v[22:25]
	v_mfma_f32_16x16x32_bf16 v[18:21], v[242:245], v[198:201], v[18:21]
	v_mfma_f32_16x16x32_bf16 v[14:17], v[234:237], v[218:221], v[14:17]
	v_mfma_f32_16x16x32_bf16 v[10:13], v[242:245], v[218:221], v[10:13]
	v_mfma_f32_16x16x32_bf16 v[6:9], v[234:237], v[226:229], v[6:9]
	v_mfma_f32_16x16x32_bf16 v[2:5], v[242:245], v[226:229], v[2:5]
	v_mfma_f32_16x16x32_bf16 v[30:33], v[238:241], v[194:197], v[30:33]
	v_mfma_f32_16x16x32_bf16 v[26:29], v[246:249], v[194:197], v[26:29]
	v_mfma_f32_16x16x32_bf16 v[22:25], v[238:241], v[202:205], v[22:25]
	v_mfma_f32_16x16x32_bf16 v[18:21], v[246:249], v[202:205], v[18:21]
	v_mfma_f32_16x16x32_bf16 v[14:17], v[238:241], v[222:225], v[14:17]
	v_mfma_f32_16x16x32_bf16 v[10:13], v[246:249], v[222:225], v[10:13]
	v_mfma_f32_16x16x32_bf16 v[6:9], v[238:241], v[230:233], v[6:9]
	v_mfma_f32_16x16x32_bf16 v[2:5], v[246:249], v[230:233], v[2:5]
	s_barrier
	ds_read_b128 v[170:173], v168
	ds_read_b128 v[174:177], v168 offset:1024
	ds_read_b128 v[178:181], v168 offset:2048
	ds_read_b128 v[186:189], v168 offset:3072
	s_add_u32 s56, s9, s56
	v_add_u32_e32 v236, 0x4000, v144
	s_addc_u32 s57, s17, s57
	v_readfirstlane_b32 s58, v236
	v_lshl_add_u64 v[234:235], s[56:57], 0, v[0:1]
	s_mov_b32 m0, s58
	v_add_u32_e32 v236, 0x4000, v145
	ds_read_b128 v[190:193], v184 offset:32768
	ds_read_b128 v[194:197], v184 offset:33792
	ds_read_b128 v[198:201], v164 offset:32768
	ds_read_b128 v[202:205], v164 offset:33792
	ds_read_b128 v[218:221], v165 offset:32768
	ds_read_b128 v[222:225], v165 offset:33792
	ds_read_b128 v[226:229], v166 offset:32768
	ds_read_b128 v[230:233], v166 offset:33792
	global_load_lds_dwordx4 v[234:235], off
	v_lshl_add_u64 v[234:235], s[56:57], 0, v[130:131]
	v_readfirstlane_b32 s56, v236
	s_mov_b32 m0, s56
	s_nop 0
	global_load_lds_dwordx4 v[234:235], off
	s_waitcnt lgkmcnt(8)
	s_barrier
	s_waitcnt lgkmcnt(0)
	s_waitcnt lgkmcnt(0)
	v_mfma_f32_16x16x32_bf16 v[118:121], v[170:173], v[190:193], v[118:121]
	v_mfma_f32_16x16x32_bf16 v[126:129], v[178:181], v[190:193], v[126:129]
	v_mfma_f32_16x16x32_bf16 v[122:125], v[170:173], v[198:201], v[122:125]
	v_mfma_f32_16x16x32_bf16 v[114:117], v[178:181], v[198:201], v[114:117]
	v_mfma_f32_16x16x32_bf16 v[110:113], v[170:173], v[218:221], v[110:113]
	v_mfma_f32_16x16x32_bf16 v[106:109], v[178:181], v[218:221], v[106:109]
	v_mfma_f32_16x16x32_bf16 v[102:105], v[170:173], v[226:229], v[102:105]
	v_mfma_f32_16x16x32_bf16 v[98:101], v[178:181], v[226:229], v[98:101]
	v_mfma_f32_16x16x32_bf16 v[118:121], v[174:177], v[194:197], v[118:121]
	v_mfma_f32_16x16x32_bf16 v[126:129], v[186:189], v[194:197], v[126:129]
	v_mfma_f32_16x16x32_bf16 v[122:125], v[174:177], v[202:205], v[122:125]
	v_mfma_f32_16x16x32_bf16 v[114:117], v[186:189], v[202:205], v[114:117]
	v_mfma_f32_16x16x32_bf16 v[110:113], v[174:177], v[222:225], v[110:113]
	v_mfma_f32_16x16x32_bf16 v[106:109], v[186:189], v[222:225], v[106:109]
	v_mfma_f32_16x16x32_bf16 v[102:105], v[174:177], v[230:233], v[102:105]
	v_mfma_f32_16x16x32_bf16 v[98:101], v[186:189], v[230:233], v[98:101]
	s_barrier
	v_readfirstlane_b32 s56, v156
	v_lshl_add_u64 v[182:183], v[182:183], 0, s[60:61]
	s_mov_b32 m0, s56
	v_readfirstlane_b32 s56, v157
	ds_read_b128 v[234:237], v169
	ds_read_b128 v[238:241], v169 offset:1024
	ds_read_b128 v[242:245], v169 offset:2048
	ds_read_b128 v[246:249], v169 offset:3072
	global_load_lds_dwordx4 v[182:183], off
	v_lshl_add_u64 v[182:183], v[206:207], 0, s[60:61]
	s_mov_b32 m0, s56
	s_nop 0
	global_load_lds_dwordx4 v[182:183], off
	s_barrier
	s_waitcnt lgkmcnt(0)
	s_waitcnt lgkmcnt(0)
	v_mfma_f32_16x16x32_bf16 v[94:97], v[234:237], v[190:193], v[94:97]
	v_mfma_f32_16x16x32_bf16 v[90:93], v[242:245], v[190:193], v[90:93]
	v_mfma_f32_16x16x32_bf16 v[86:89], v[234:237], v[198:201], v[86:89]
	v_mfma_f32_16x16x32_bf16 v[82:85], v[242:245], v[198:201], v[82:85]
	v_mfma_f32_16x16x32_bf16 v[78:81], v[234:237], v[218:221], v[78:81]
	v_mfma_f32_16x16x32_bf16 v[74:77], v[242:245], v[218:221], v[74:77]
	v_mfma_f32_16x16x32_bf16 v[70:73], v[234:237], v[226:229], v[70:73]
	v_mfma_f32_16x16x32_bf16 v[66:69], v[242:245], v[226:229], v[66:69]
	v_mfma_f32_16x16x32_bf16 v[94:97], v[238:241], v[194:197], v[94:97]
	v_mfma_f32_16x16x32_bf16 v[90:93], v[246:249], v[194:197], v[90:93]
	v_mfma_f32_16x16x32_bf16 v[86:89], v[238:241], v[202:205], v[86:89]
	v_mfma_f32_16x16x32_bf16 v[82:85], v[246:249], v[202:205], v[82:85]
	v_mfma_f32_16x16x32_bf16 v[78:81], v[238:241], v[222:225], v[78:81]
	v_mfma_f32_16x16x32_bf16 v[74:77], v[246:249], v[222:225], v[74:77]
	v_mfma_f32_16x16x32_bf16 v[70:73], v[238:241], v[230:233], v[70:73]
	v_mfma_f32_16x16x32_bf16 v[66:69], v[246:249], v[230:233], v[66:69]
	s_addk_i32 s25, 0xc0
	s_ashr_i32 s56, s25, 31
	s_addk_i32 s55, 0xc0
	s_cmp_lt_i32 s25, s14
	s_cselect_b32 s57, s56, 0
	s_cselect_b32 s56, s25, s55
	s_lshl_b64 s[56:57], s[56:57], 1
	s_add_u32 s56, s10, s56
	s_addc_u32 s57, s11, s57
	v_readfirstlane_b32 s25, v158
	v_lshl_add_u64 v[182:183], s[56:57], 0, v[0:1]
	s_mov_b32 m0, s25
	v_readfirstlane_b32 s25, v159
	s_barrier
	ds_read_b128 v[190:193], v184 offset:49152
	ds_read_b128 v[194:197], v184 offset:50176
	ds_read_b128 v[198:201], v164 offset:49152
	ds_read_b128 v[202:205], v164 offset:50176
	ds_read_b128 v[218:221], v165 offset:49152
	ds_read_b128 v[222:225], v165 offset:50176
	ds_read_b128 v[226:229], v166 offset:49152
	ds_read_b128 v[230:233], v166 offset:50176
	global_load_lds_dwordx4 v[182:183], off
	v_lshl_add_u64 v[182:183], s[56:57], 0, v[130:131]
	s_mov_b32 m0, s25
	s_nop 0
	global_load_lds_dwordx4 v[182:183], off
	s_barrier
	s_waitcnt lgkmcnt(0)
	s_waitcnt lgkmcnt(0)
	v_mfma_f32_16x16x32_bf16 v[62:65], v[170:173], v[190:193], v[62:65]
	v_mfma_f32_16x16x32_bf16 v[58:61], v[178:181], v[190:193], v[58:61]
	v_mfma_f32_16x16x32_bf16 v[54:57], v[170:173], v[198:201], v[54:57]
	v_mfma_f32_16x16x32_bf16 v[50:53], v[178:181], v[198:201], v[50:53]
	v_mfma_f32_16x16x32_bf16 v[46:49], v[170:173], v[218:221], v[46:49]
	v_mfma_f32_16x16x32_bf16 v[42:45], v[178:181], v[218:221], v[42:45]
	v_mfma_f32_16x16x32_bf16 v[38:41], v[170:173], v[226:229], v[38:41]
	v_mfma_f32_16x16x32_bf16 v[34:37], v[178:181], v[226:229], v[34:37]
	v_mfma_f32_16x16x32_bf16 v[62:65], v[174:177], v[194:197], v[62:65]
	v_mfma_f32_16x16x32_bf16 v[58:61], v[186:189], v[194:197], v[58:61]
	v_mfma_f32_16x16x32_bf16 v[54:57], v[174:177], v[202:205], v[54:57]
	v_mfma_f32_16x16x32_bf16 v[50:53], v[186:189], v[202:205], v[50:53]
	v_mfma_f32_16x16x32_bf16 v[46:49], v[174:177], v[222:225], v[46:49]
	v_mfma_f32_16x16x32_bf16 v[42:45], v[186:189], v[222:225], v[42:45]
	v_mfma_f32_16x16x32_bf16 v[38:41], v[174:177], v[230:233], v[38:41]
	v_mfma_f32_16x16x32_bf16 v[34:37], v[186:189], v[230:233], v[34:37]
	s_barrier
	v_readfirstlane_b32 s25, v160
	v_lshl_add_u64 v[170:171], v[208:209], 0, s[60:61]
	s_mov_b32 m0, s25
	v_readfirstlane_b32 s25, v161
	global_load_lds_dwordx4 v[170:171], off
	v_lshl_add_u64 v[170:171], v[214:215], 0, s[60:61]
	s_mov_b32 m0, s25
	s_nop 0
	global_load_lds_dwordx4 v[170:171], off
	s_waitcnt vmcnt(6)
	s_barrier
	v_mfma_f32_16x16x32_bf16 v[30:33], v[234:237], v[190:193], v[30:33]
	v_mfma_f32_16x16x32_bf16 v[26:29], v[242:245], v[190:193], v[26:29]
	v_mfma_f32_16x16x32_bf16 v[22:25], v[234:237], v[198:201], v[22:25]
	v_mfma_f32_16x16x32_bf16 v[18:21], v[242:245], v[198:201], v[18:21]
	v_mfma_f32_16x16x32_bf16 v[14:17], v[234:237], v[218:221], v[14:17]
	v_mfma_f32_16x16x32_bf16 v[10:13], v[242:245], v[218:221], v[10:13]
	v_mfma_f32_16x16x32_bf16 v[6:9], v[234:237], v[226:229], v[6:9]
	v_mfma_f32_16x16x32_bf16 v[2:5], v[242:245], v[226:229], v[2:5]
	v_mfma_f32_16x16x32_bf16 v[30:33], v[238:241], v[194:197], v[30:33]
	v_mfma_f32_16x16x32_bf16 v[26:29], v[246:249], v[194:197], v[26:29]
	v_mfma_f32_16x16x32_bf16 v[22:25], v[238:241], v[202:205], v[22:25]
	v_mfma_f32_16x16x32_bf16 v[18:21], v[246:249], v[202:205], v[18:21]
	v_mfma_f32_16x16x32_bf16 v[14:17], v[238:241], v[222:225], v[14:17]
	v_mfma_f32_16x16x32_bf16 v[10:13], v[246:249], v[222:225], v[10:13]
	v_mfma_f32_16x16x32_bf16 v[6:9], v[238:241], v[230:233], v[6:9]
	v_mfma_f32_16x16x32_bf16 v[2:5], v[246:249], v[230:233], v[2:5]
	v_lshl_add_u64 v[132:133], v[132:133], 0, s[36:37]
	v_lshl_add_u64 v[134:135], v[134:135], 0, s[36:37]
	v_lshl_add_u64 v[136:137], v[136:137], 0, s[36:37]
	v_lshl_add_u64 v[138:139], v[138:139], 0, s[36:37]
	s_cmp_ge_i32 s24, s8
	s_mov_b32 s25, s39
	s_barrier
	s_cbranch_scc0 .LBB0_839
	v_mov_b32_e32 v132, v155
	v_or_b32_e32 v133, 0x400, v143
	v_or_b32_e32 v134, 0x800, v143
	v_or_b32_e32 v135, 0xc00, v143
	v_mov_b32_e32 v136, v154
.LBB0_841:
	s_lshl_b32 s2, s40, 6
	s_add_i32 s2, s16, s2
	s_sub_i32 s2, s2, 64
	s_ashr_i32 s3, s2, 31
	s_sub_i32 s8, s2, s14
	s_cmp_lt_i32 s2, s14
	s_cselect_b32 s3, s3, 0
	s_cselect_b32 s2, s2, s8
	s_lshl_b64 s[2:3], s[2:3], 1
	v_add_u32_e32 v137, s33, v132
	s_add_u32 s8, s68, s2
	v_add_u32_e32 v138, v137, v143
	s_addc_u32 s9, s69, s3
	s_lshl_b64 s[2:3], s[20:21], 1
	v_add_u32_e32 v139, v137, v133
	ds_read_b128 v[154:157], v138
	ds_read_b128 v[158:161], v139
	v_add_u32_e32 v138, v137, v134
	v_add_u32_e32 v137, v137, v135
	s_add_u32 s2, s8, s2
	ds_read_b128 v[162:165], v138
	ds_read_b128 v[166:169], v137
	v_add_u32_e32 v137, 16, v146
	s_addc_u32 s3, s9, s3
	v_add_u32_e32 v142, v137, v148
	v_add_u32_e32 v148, 16, v146
	v_lshl_add_u64 v[182:183], s[2:3], 0, v[0:1]
	v_add_u32_e32 v0, 0xc000, v144
	v_add_u32_e32 v184, v148, v147
	v_add_u32_e32 v147, 16, v146
	v_add_u32_e32 v146, 16, v146
	v_readfirstlane_b32 s8, v0
	v_add_u32_e32 v0, 0xc000, v145
	v_add_u32_e32 v141, v137, v136
	v_add_u32_e32 v207, v147, v149
	v_add_u32_e32 v209, v146, v151
	s_mov_b32 m0, s8
	v_lshl_add_u64 v[130:131], s[2:3], 0, v[130:131]
	v_readfirstlane_b32 s2, v0
	ds_read_b128 v[136:139], v141
	ds_read_b128 v[170:173], v142
	v_add_u32_e32 v206, v148, v150
	ds_read_b128 v[174:177], v184
	ds_read_b128 v[178:181], v206
	v_add_u32_e32 v208, v147, v152
	ds_read_b128 v[186:189], v207
	ds_read_b128 v[190:193], v208
	v_add_u32_e32 v214, v146, v153
	ds_read_b128 v[146:149], v209
	ds_read_b128 v[150:153], v214
	global_load_lds_dwordx4 v[182:183], off
	s_mov_b32 m0, s2
	s_nop 0
	global_load_lds_dwordx4 v[130:131], off
	s_barrier
	s_waitcnt lgkmcnt(0)
	s_waitcnt lgkmcnt(0)
	v_mfma_f32_16x16x32_bf16 v[118:121], v[154:157], v[136:139], v[118:121]
	v_mfma_f32_16x16x32_bf16 v[114:117], v[162:165], v[174:177], v[114:117]
	v_mfma_f32_16x16x32_bf16 v[102:105], v[154:157], v[146:149], v[102:105]
	v_mfma_f32_16x16x32_bf16 v[98:101], v[162:165], v[146:149], v[98:101]
	v_mfma_f32_16x16x32_bf16 v[118:121], v[158:161], v[170:173], v[118:121]
	v_mfma_f32_16x16x32_bf16 v[126:129], v[162:165], v[136:139], v[126:129]
	v_mfma_f32_16x16x32_bf16 v[122:125], v[154:157], v[174:177], v[122:125]
	v_mfma_f32_16x16x32_bf16 v[114:117], v[166:169], v[178:181], v[114:117]
	v_mfma_f32_16x16x32_bf16 v[110:113], v[154:157], v[186:189], v[110:113]
	v_mfma_f32_16x16x32_bf16 v[106:109], v[162:165], v[186:189], v[106:109]
	v_mfma_f32_16x16x32_bf16 v[102:105], v[158:161], v[150:153], v[102:105]
	v_mfma_f32_16x16x32_bf16 v[98:101], v[166:169], v[150:153], v[98:101]
	v_mfma_f32_16x16x32_bf16 v[194:197], v[166:169], v[170:173], v[126:129]
	v_mfma_f32_16x16x32_bf16 v[198:201], v[158:161], v[178:181], v[122:125]
	v_mfma_f32_16x16x32_bf16 v[202:205], v[158:161], v[190:193], v[110:113]
	v_mfma_f32_16x16x32_bf16 v[218:221], v[166:169], v[190:193], v[106:109]
	v_add_u32_e32 v0, s86, v132
	s_nop 0
	v_add_u32_e32 v106, v0, v143
	v_add_u32_e32 v110, v0, v133
	v_add_u32_e32 v122, v0, v134
	s_barrier
	ds_read_b128 v[106:109], v106
	ds_read_b128 v[110:113], v110
	v_add_u32_e32 v0, v0, v135
	ds_read_b128 v[122:125], v122
	ds_read_b128 v[126:129], v0
	s_barrier
	s_waitcnt lgkmcnt(0)
	s_waitcnt lgkmcnt(0)
	v_mfma_f32_16x16x32_bf16 v[86:89], v[106:109], v[174:177], v[86:89]
	v_mfma_f32_16x16x32_bf16 v[82:85], v[122:125], v[174:177], v[82:85]
	v_mfma_f32_16x16x32_bf16 v[70:73], v[106:109], v[146:149], v[70:73]
	v_mfma_f32_16x16x32_bf16 v[66:69], v[122:125], v[146:149], v[66:69]
	v_mfma_f32_16x16x32_bf16 v[94:97], v[106:109], v[136:139], v[94:97]
	v_mfma_f32_16x16x32_bf16 v[90:93], v[122:125], v[136:139], v[90:93]
	v_mfma_f32_16x16x32_bf16 v[86:89], v[110:113], v[178:181], v[86:89]
	v_mfma_f32_16x16x32_bf16 v[82:85], v[126:129], v[178:181], v[82:85]
	v_mfma_f32_16x16x32_bf16 v[78:81], v[106:109], v[186:189], v[78:81]
	v_mfma_f32_16x16x32_bf16 v[74:77], v[122:125], v[186:189], v[74:77]
	v_mfma_f32_16x16x32_bf16 v[70:73], v[110:113], v[150:153], v[70:73]
	v_mfma_f32_16x16x32_bf16 v[66:69], v[126:129], v[150:153], v[66:69]
	v_mfma_f32_16x16x32_bf16 v[222:225], v[110:113], v[170:173], v[94:97]
	v_mfma_f32_16x16x32_bf16 v[136:139], v[126:129], v[170:173], v[90:93]
	v_mfma_f32_16x16x32_bf16 v[170:173], v[110:113], v[190:193], v[78:81]
	v_mfma_f32_16x16x32_bf16 v[174:177], v[126:129], v[190:193], v[74:77]
	s_barrier
	s_nop 0
	ds_read_b128 v[74:77], v141 offset:16384
	ds_read_b128 v[78:81], v142 offset:16384
	ds_read_b128 v[90:93], v184 offset:16384
	ds_read_b128 v[94:97], v206 offset:16384
	ds_read_b128 v[144:147], v207 offset:16384
	ds_read_b128 v[148:151], v208 offset:16384
	ds_read_b128 v[178:181], v209 offset:16384
	ds_read_b128 v[186:189], v214 offset:16384
	s_waitcnt vmcnt(4)
	s_barrier
	s_waitcnt lgkmcnt(0)
	s_waitcnt lgkmcnt(0)
	v_mfma_f32_16x16x32_bf16 v[62:65], v[154:157], v[74:77], v[62:65]
	v_mfma_f32_16x16x32_bf16 v[58:61], v[162:165], v[74:77], v[58:61]
	v_mfma_f32_16x16x32_bf16 v[54:57], v[154:157], v[90:93], v[54:57]
	v_mfma_f32_16x16x32_bf16 v[50:53], v[162:165], v[90:93], v[50:53]
	v_mfma_f32_16x16x32_bf16 v[38:41], v[154:157], v[178:181], v[38:41]
	v_mfma_f32_16x16x32_bf16 v[34:37], v[162:165], v[178:181], v[34:37]
	v_mfma_f32_16x16x32_bf16 v[62:65], v[158:161], v[78:81], v[62:65]
	v_mfma_f32_16x16x32_bf16 v[58:61], v[166:169], v[78:81], v[58:61]
	v_mfma_f32_16x16x32_bf16 v[54:57], v[158:161], v[94:97], v[54:57]
	v_mfma_f32_16x16x32_bf16 v[50:53], v[166:169], v[94:97], v[50:53]
	v_mfma_f32_16x16x32_bf16 v[46:49], v[154:157], v[144:147], v[46:49]
	v_mfma_f32_16x16x32_bf16 v[42:45], v[162:165], v[144:147], v[42:45]
	v_mfma_f32_16x16x32_bf16 v[38:41], v[158:161], v[186:189], v[38:41]
	v_mfma_f32_16x16x32_bf16 v[34:37], v[166:169], v[186:189], v[34:37]
	v_mfma_f32_16x16x32_bf16 v[190:193], v[158:161], v[148:151], v[46:49]
	v_mfma_f32_16x16x32_bf16 v[226:229], v[166:169], v[148:151], v[42:45]
	v_mfma_f32_16x16x32_bf16 v[22:25], v[106:109], v[90:93], v[22:25]
	v_mfma_f32_16x16x32_bf16 v[18:21], v[122:125], v[90:93], v[18:21]
	v_mfma_f32_16x16x32_bf16 v[6:9], v[106:109], v[178:181], v[6:9]
	v_mfma_f32_16x16x32_bf16 v[2:5], v[122:125], v[178:181], v[2:5]
	v_mfma_f32_16x16x32_bf16 v[30:33], v[106:109], v[74:77], v[30:33]
	v_mfma_f32_16x16x32_bf16 v[26:29], v[122:125], v[74:77], v[26:29]
	v_mfma_f32_16x16x32_bf16 v[22:25], v[110:113], v[94:97], v[22:25]
	v_mfma_f32_16x16x32_bf16 v[18:21], v[126:129], v[94:97], v[18:21]
	v_mfma_f32_16x16x32_bf16 v[14:17], v[106:109], v[144:147], v[14:17]
	v_mfma_f32_16x16x32_bf16 v[10:13], v[122:125], v[144:147], v[10:13]
	v_mfma_f32_16x16x32_bf16 v[6:9], v[110:113], v[186:189], v[6:9]
	v_mfma_f32_16x16x32_bf16 v[2:5], v[126:129], v[186:189], v[2:5]
	v_mfma_f32_16x16x32_bf16 v[152:155], v[110:113], v[78:81], v[30:33]
	v_mfma_f32_16x16x32_bf16 v[156:159], v[126:129], v[78:81], v[26:29]
	v_mfma_f32_16x16x32_bf16 v[160:163], v[110:113], v[148:151], v[14:17]
	v_mfma_f32_16x16x32_bf16 v[144:147], v[126:129], v[148:151], v[10:13]
	v_add_u32_e32 v0, s85, v132
	s_nop 0
	v_add_u32_e32 v10, v0, v143
	v_add_u32_e32 v14, v0, v133
	v_add_u32_e32 v26, v0, v134
	s_barrier
	ds_read_b128 v[10:13], v10
	ds_read_b128 v[14:17], v14
	v_add_u32_e32 v0, v0, v135
	ds_read_b128 v[148:151], v26
	ds_read_b128 v[164:167], v0
	ds_read_b128 v[26:29], v141 offset:32768
	ds_read_b128 v[30:33], v142 offset:32768
	ds_read_b128 v[42:45], v184 offset:32768
	ds_read_b128 v[46:49], v206 offset:32768
	ds_read_b128 v[178:181], v207 offset:32768
	ds_read_b128 v[186:189], v208 offset:32768
	ds_read_b128 v[230:233], v209 offset:32768
	ds_read_b128 v[234:237], v214 offset:32768
	s_waitcnt vmcnt(2)
	s_barrier
	s_waitcnt lgkmcnt(0)
	s_waitcnt lgkmcnt(0)
	v_mfma_f32_16x16x32_bf16 v[74:77], v[10:13], v[26:29], v[118:121]
	v_mfma_f32_16x16x32_bf16 v[126:129], v[14:17], v[30:33], v[74:77]
	v_mfma_f32_16x16x32_bf16 v[74:77], v[148:151], v[26:29], v[194:197]
	v_mfma_f32_16x16x32_bf16 v[122:125], v[164:167], v[30:33], v[74:77]
	v_mfma_f32_16x16x32_bf16 v[74:77], v[10:13], v[42:45], v[198:201]
	v_mfma_f32_16x16x32_bf16 v[110:113], v[14:17], v[46:49], v[74:77]
	v_mfma_f32_16x16x32_bf16 v[74:77], v[148:151], v[42:45], v[114:117]
	v_mfma_f32_16x16x32_bf16 v[106:109], v[164:167], v[46:49], v[74:77]
	v_mfma_f32_16x16x32_bf16 v[74:77], v[10:13], v[178:181], v[202:205]
	v_mfma_f32_16x16x32_bf16 v[94:97], v[14:17], v[186:189], v[74:77]
	v_mfma_f32_16x16x32_bf16 v[74:77], v[148:151], v[178:181], v[218:221]
	v_mfma_f32_16x16x32_bf16 v[90:93], v[164:167], v[186:189], v[74:77]
	v_mfma_f32_16x16x32_bf16 v[74:77], v[10:13], v[230:233], v[102:105]
	v_mfma_f32_16x16x32_bf16 v[78:81], v[14:17], v[234:237], v[74:77]
	v_mfma_f32_16x16x32_bf16 v[74:77], v[148:151], v[230:233], v[98:101]
	v_mfma_f32_16x16x32_bf16 v[74:77], v[164:167], v[234:237], v[74:77]
	v_add_u32_e32 v0, s94, v132
	v_add_u32_e32 v98, v0, v143
	s_barrier
	v_add_u32_e32 v99, v0, v133
	ds_read_b128 v[130:133], v98
	ds_read_b128 v[194:197], v99
	v_add_u32_e32 v98, v0, v134
	v_add_u32_e32 v0, v0, v135
	ds_read_b128 v[198:201], v98
	ds_read_b128 v[202:205], v0
	s_waitcnt vmcnt(0)
	s_barrier
	s_waitcnt lgkmcnt(0)
	s_waitcnt lgkmcnt(0)
	v_mfma_f32_16x16x32_bf16 v[98:101], v[130:133], v[26:29], v[222:225]
	v_mfma_f32_16x16x32_bf16 v[26:29], v[198:201], v[26:29], v[136:139]
	v_mfma_f32_16x16x32_bf16 v[114:117], v[202:205], v[30:33], v[26:29]
	v_mfma_f32_16x16x32_bf16 v[26:29], v[130:133], v[42:45], v[86:89]
	v_mfma_f32_16x16x32_bf16 v[102:105], v[194:197], v[46:49], v[26:29]
	v_mfma_f32_16x16x32_bf16 v[26:29], v[198:201], v[42:45], v[82:85]
	v_mfma_f32_16x16x32_bf16 v[118:121], v[194:197], v[30:33], v[98:101]
	v_mfma_f32_16x16x32_bf16 v[98:101], v[202:205], v[46:49], v[26:29]
	v_mfma_f32_16x16x32_bf16 v[26:29], v[130:133], v[178:181], v[170:173]
	v_mfma_f32_16x16x32_bf16 v[86:89], v[194:197], v[186:189], v[26:29]
	v_mfma_f32_16x16x32_bf16 v[26:29], v[198:201], v[178:181], v[174:177]
	v_mfma_f32_16x16x32_bf16 v[82:85], v[202:205], v[186:189], v[26:29]
	v_mfma_f32_16x16x32_bf16 v[26:29], v[130:133], v[230:233], v[70:73]
	v_mfma_f32_16x16x32_bf16 v[70:73], v[194:197], v[234:237], v[26:29]
	v_mfma_f32_16x16x32_bf16 v[26:29], v[198:201], v[230:233], v[66:69]
	v_mfma_f32_16x16x32_bf16 v[66:69], v[202:205], v[234:237], v[26:29]
	s_barrier
	ds_read_b128 v[134:137], v141 offset:49152
	ds_read_b128 v[168:171], v142 offset:49152
	ds_read_b128 v[172:175], v184 offset:49152
	ds_read_b128 v[176:179], v206 offset:49152
	ds_read_b128 v[180:183], v207 offset:49152
	ds_read_b128 v[186:189], v208 offset:49152
	ds_read_b128 v[218:221], v209 offset:49152
	ds_read_b128 v[222:225], v214 offset:49152
	s_barrier
	s_waitcnt lgkmcnt(0)
	s_waitcnt lgkmcnt(0)
	v_mfma_f32_16x16x32_bf16 v[26:29], v[10:13], v[134:137], v[62:65]
	v_mfma_f32_16x16x32_bf16 v[62:65], v[14:17], v[168:171], v[26:29]
	v_mfma_f32_16x16x32_bf16 v[26:29], v[148:151], v[134:137], v[58:61]
	v_mfma_f32_16x16x32_bf16 v[58:61], v[164:167], v[168:171], v[26:29]
	v_mfma_f32_16x16x32_bf16 v[26:29], v[10:13], v[172:175], v[54:57]
	v_mfma_f32_16x16x32_bf16 v[46:49], v[14:17], v[176:179], v[26:29]
	v_mfma_f32_16x16x32_bf16 v[26:29], v[148:151], v[172:175], v[50:53]
	v_mfma_f32_16x16x32_bf16 v[42:45], v[164:167], v[176:179], v[26:29]
	v_mfma_f32_16x16x32_bf16 v[26:29], v[10:13], v[180:183], v[190:193]
	v_mfma_f32_16x16x32_bf16 v[10:13], v[10:13], v[218:221], v[38:41]
	v_mfma_f32_16x16x32_bf16 v[30:33], v[14:17], v[186:189], v[26:29]
	v_mfma_f32_16x16x32_bf16 v[26:29], v[148:151], v[180:183], v[226:229]
	v_mfma_f32_16x16x32_bf16 v[14:17], v[14:17], v[222:225], v[10:13]
	v_mfma_f32_16x16x32_bf16 v[10:13], v[148:151], v[218:221], v[34:37]
	v_mfma_f32_16x16x32_bf16 v[26:29], v[164:167], v[186:189], v[26:29]
	v_mfma_f32_16x16x32_bf16 v[10:13], v[164:167], v[222:225], v[10:13]
	v_mfma_f32_16x16x32_bf16 v[34:37], v[130:133], v[134:137], v[152:155]
	v_mfma_f32_16x16x32_bf16 v[54:57], v[194:197], v[168:171], v[34:37]
	v_mfma_f32_16x16x32_bf16 v[34:37], v[198:201], v[134:137], v[156:159]
	v_mfma_f32_16x16x32_bf16 v[18:21], v[198:201], v[172:175], v[18:21]
	v_mfma_f32_16x16x32_bf16 v[50:53], v[202:205], v[168:171], v[34:37]
	v_mfma_f32_16x16x32_bf16 v[22:25], v[130:133], v[172:175], v[22:25]
	v_mfma_f32_16x16x32_bf16 v[34:37], v[202:205], v[176:179], v[18:21]
	v_mfma_f32_16x16x32_bf16 v[18:21], v[130:133], v[180:183], v[160:163]
	v_mfma_f32_16x16x32_bf16 v[38:41], v[194:197], v[176:179], v[22:25]
	v_mfma_f32_16x16x32_bf16 v[22:25], v[194:197], v[186:189], v[18:21]
	v_mfma_f32_16x16x32_bf16 v[18:21], v[198:201], v[180:183], v[144:147]
	v_mfma_f32_16x16x32_bf16 v[6:9], v[130:133], v[218:221], v[6:9]
	v_mfma_f32_16x16x32_bf16 v[2:5], v[198:201], v[218:221], v[2:5]
	v_mfma_f32_16x16x32_bf16 v[18:21], v[202:205], v[186:189], v[18:21]
	v_mfma_f32_16x16x32_bf16 v[6:9], v[194:197], v[222:225], v[6:9]
	v_mfma_f32_16x16x32_bf16 v[2:5], v[202:205], v[222:225], v[2:5]
	s_movk_i32 s0, 0x100
	v_cmp_gt_u32_e32 vcc, s0, v140
	s_barrier
	s_and_saveexec_b64 s[2:3], vcc
	s_cbranch_execz .LBB0_843
	s_barrier

.LBB0_923:
	ds_read_b128 v[162:165], v158
	ds_read_b128 v[166:169], v158 offset:1024
	ds_read_b128 v[170:173], v158 offset:2048
	ds_read_b128 v[174:177], v158 offset:3072
	v_add_u32_e32 v159, 0xc000, v151
	v_lshl_add_u64 v[182:183], s[6:7], 0, v[134:135]
	v_readfirstlane_b32 s2, v159
	v_lshl_add_u64 v[160:161], v[182:183], 0, s[96:97]
	s_mov_b32 m0, s2
	ds_read_b128 v[178:181], v146
	ds_read_b128 v[186:189], v146 offset:1024
	ds_read_b128 v[190:193], v145
	ds_read_b128 v[198:201], v145 offset:1024
	ds_read_b128 v[202:205], v144
	ds_read_b128 v[218:221], v144 offset:1024
	ds_read_b128 v[222:225], v143
	ds_read_b128 v[226:229], v143 offset:1024
	global_load_lds_dwordx4 v[160:161], off
	v_add_u32_e32 v160, 0xc000, v153
	v_lshl_add_u64 v[194:195], s[6:7], 0, v[132:133]
	v_readfirstlane_b32 s2, v160
	v_lshl_add_u64 v[196:197], v[194:195], 0, s[96:97]
	s_mov_b32 m0, s2
	s_nop 0
	global_load_lds_dwordx4 v[196:197], off
	s_waitcnt lgkmcnt(8)
	s_barrier
	s_waitcnt lgkmcnt(0)
	s_waitcnt lgkmcnt(0)
	v_mfma_f32_16x16x32_bf16 v[126:129], v[162:165], v[178:181], v[126:129]
	v_mfma_f32_16x16x32_bf16 v[122:125], v[170:173], v[178:181], v[122:125]
	v_mfma_f32_16x16x32_bf16 v[118:121], v[162:165], v[190:193], v[118:121]
	v_mfma_f32_16x16x32_bf16 v[114:117], v[170:173], v[190:193], v[114:117]
	v_mfma_f32_16x16x32_bf16 v[110:113], v[162:165], v[202:205], v[110:113]
	v_mfma_f32_16x16x32_bf16 v[106:109], v[170:173], v[202:205], v[106:109]
	v_mfma_f32_16x16x32_bf16 v[102:105], v[162:165], v[222:225], v[102:105]
	v_mfma_f32_16x16x32_bf16 v[98:101], v[170:173], v[222:225], v[98:101]
	v_mfma_f32_16x16x32_bf16 v[126:129], v[166:169], v[186:189], v[126:129]
	v_mfma_f32_16x16x32_bf16 v[122:125], v[174:177], v[186:189], v[122:125]
	v_mfma_f32_16x16x32_bf16 v[118:121], v[166:169], v[198:201], v[118:121]
	v_mfma_f32_16x16x32_bf16 v[114:117], v[174:177], v[198:201], v[114:117]
	v_mfma_f32_16x16x32_bf16 v[110:113], v[166:169], v[218:221], v[110:113]
	v_mfma_f32_16x16x32_bf16 v[106:109], v[174:177], v[218:221], v[106:109]
	v_mfma_f32_16x16x32_bf16 v[102:105], v[166:169], v[226:229], v[102:105]
	v_mfma_f32_16x16x32_bf16 v[98:101], v[174:177], v[226:229], v[98:101]
	s_barrier
	v_add_u32_e32 v161, s33, v141
	v_lshl_add_u64 v[196:197], s[6:7], 0, v[138:139]
	v_readfirstlane_b32 s2, v161
	v_lshl_add_u64 v[206:207], v[196:197], 0, s[78:79]
	s_mov_b32 m0, s2
	v_add_u32_e32 v161, s33, v142
	ds_read_b128 v[230:233], v155
	ds_read_b128 v[234:237], v155 offset:1024
	ds_read_b128 v[238:241], v155 offset:2048
	ds_read_b128 v[242:245], v155 offset:3072
	global_load_lds_dwordx4 v[206:207], off
	v_lshl_add_u64 v[206:207], s[6:7], 0, v[136:137]
	v_readfirstlane_b32 s2, v161
	v_lshl_add_u64 v[246:247], v[206:207], 0, s[78:79]
	s_mov_b32 m0, s2
	s_nop 0
	global_load_lds_dwordx4 v[246:247], off
	s_barrier
	s_waitcnt lgkmcnt(0)
	s_waitcnt lgkmcnt(0)
	v_mfma_f32_16x16x32_bf16 v[94:97], v[230:233], v[178:181], v[94:97]
	v_mfma_f32_16x16x32_bf16 v[90:93], v[238:241], v[178:181], v[90:93]
	v_mfma_f32_16x16x32_bf16 v[86:89], v[230:233], v[190:193], v[86:89]
	v_mfma_f32_16x16x32_bf16 v[82:85], v[238:241], v[190:193], v[82:85]
	v_mfma_f32_16x16x32_bf16 v[78:81], v[230:233], v[202:205], v[78:81]
	v_mfma_f32_16x16x32_bf16 v[74:77], v[238:241], v[202:205], v[74:77]
	v_mfma_f32_16x16x32_bf16 v[70:73], v[230:233], v[222:225], v[70:73]
	v_mfma_f32_16x16x32_bf16 v[66:69], v[238:241], v[222:225], v[66:69]
	v_mfma_f32_16x16x32_bf16 v[94:97], v[234:237], v[186:189], v[94:97]
	v_mfma_f32_16x16x32_bf16 v[90:93], v[242:245], v[186:189], v[90:93]
	v_mfma_f32_16x16x32_bf16 v[86:89], v[234:237], v[198:201], v[86:89]
	v_mfma_f32_16x16x32_bf16 v[82:85], v[242:245], v[198:201], v[82:85]
	v_mfma_f32_16x16x32_bf16 v[78:81], v[234:237], v[218:221], v[78:81]
	v_mfma_f32_16x16x32_bf16 v[74:77], v[242:245], v[218:221], v[74:77]
	v_mfma_f32_16x16x32_bf16 v[70:73], v[234:237], v[226:229], v[70:73]
	v_mfma_f32_16x16x32_bf16 v[66:69], v[242:245], v[226:229], v[66:69]
	v_readfirstlane_b32 s2, v151
	v_lshl_add_u64 v[246:247], v[182:183], 0, s[82:83]
	s_mov_b32 m0, s2
	v_readfirstlane_b32 s2, v153
	s_barrier
	ds_read_b128 v[178:181], v146 offset:16384
	ds_read_b128 v[186:189], v146 offset:17408
	ds_read_b128 v[190:193], v145 offset:16384
	ds_read_b128 v[198:201], v145 offset:17408
	ds_read_b128 v[202:205], v144 offset:16384
	ds_read_b128 v[218:221], v144 offset:17408
	ds_read_b128 v[222:225], v143 offset:16384
	ds_read_b128 v[226:229], v143 offset:17408
	global_load_lds_dwordx4 v[246:247], off
	v_lshl_add_u64 v[246:247], v[194:195], 0, s[82:83]
	s_mov_b32 m0, s2
	s_nop 0
	global_load_lds_dwordx4 v[246:247], off
	s_barrier
	s_waitcnt lgkmcnt(0)
	s_waitcnt lgkmcnt(0)
	v_mfma_f32_16x16x32_bf16 v[62:65], v[162:165], v[178:181], v[62:65]
	v_mfma_f32_16x16x32_bf16 v[58:61], v[170:173], v[178:181], v[58:61]
	v_mfma_f32_16x16x32_bf16 v[54:57], v[162:165], v[190:193], v[54:57]
	v_mfma_f32_16x16x32_bf16 v[50:53], v[170:173], v[190:193], v[50:53]
	v_mfma_f32_16x16x32_bf16 v[46:49], v[162:165], v[202:205], v[46:49]
	v_mfma_f32_16x16x32_bf16 v[42:45], v[170:173], v[202:205], v[42:45]
	v_mfma_f32_16x16x32_bf16 v[38:41], v[162:165], v[222:225], v[38:41]
	v_mfma_f32_16x16x32_bf16 v[34:37], v[170:173], v[222:225], v[34:37]
	v_mfma_f32_16x16x32_bf16 v[62:65], v[166:169], v[186:189], v[62:65]
	v_mfma_f32_16x16x32_bf16 v[58:61], v[174:177], v[186:189], v[58:61]
	v_mfma_f32_16x16x32_bf16 v[54:57], v[166:169], v[198:201], v[54:57]
	v_mfma_f32_16x16x32_bf16 v[50:53], v[174:177], v[198:201], v[50:53]
	v_mfma_f32_16x16x32_bf16 v[46:49], v[166:169], v[218:221], v[46:49]
	v_mfma_f32_16x16x32_bf16 v[42:45], v[174:177], v[218:221], v[42:45]
	v_mfma_f32_16x16x32_bf16 v[38:41], v[166:169], v[226:229], v[38:41]
	v_mfma_f32_16x16x32_bf16 v[34:37], v[174:177], v[226:229], v[34:37]
	s_barrier
	v_add_u32_e32 v161, s86, v141
	v_lshl_add_u64 v[162:163], v[196:197], 0, s[90:91]
	v_readfirstlane_b32 s2, v161
	v_add_u32_e32 v161, s86, v142
	s_mov_b32 m0, s2
	v_readfirstlane_b32 s2, v161
	global_load_lds_dwordx4 v[162:163], off
	v_lshl_add_u64 v[162:163], v[206:207], 0, s[90:91]
	s_mov_b32 m0, s2
	s_nop 0
	global_load_lds_dwordx4 v[162:163], off
	s_waitcnt vmcnt(6)
	s_barrier
	v_mfma_f32_16x16x32_bf16 v[30:33], v[230:233], v[178:181], v[30:33]
	v_mfma_f32_16x16x32_bf16 v[26:29], v[238:241], v[178:181], v[26:29]
	v_mfma_f32_16x16x32_bf16 v[22:25], v[230:233], v[190:193], v[22:25]
	v_mfma_f32_16x16x32_bf16 v[18:21], v[238:241], v[190:193], v[18:21]
	v_mfma_f32_16x16x32_bf16 v[14:17], v[230:233], v[202:205], v[14:17]
	v_mfma_f32_16x16x32_bf16 v[10:13], v[238:241], v[202:205], v[10:13]
	v_mfma_f32_16x16x32_bf16 v[6:9], v[230:233], v[222:225], v[6:9]
	v_mfma_f32_16x16x32_bf16 v[2:5], v[238:241], v[222:225], v[2:5]
	v_mfma_f32_16x16x32_bf16 v[30:33], v[234:237], v[186:189], v[30:33]
	v_mfma_f32_16x16x32_bf16 v[26:29], v[242:245], v[186:189], v[26:29]
	v_mfma_f32_16x16x32_bf16 v[22:25], v[234:237], v[198:201], v[22:25]
	v_mfma_f32_16x16x32_bf16 v[18:21], v[242:245], v[198:201], v[18:21]
	v_mfma_f32_16x16x32_bf16 v[14:17], v[234:237], v[218:221], v[14:17]
	v_mfma_f32_16x16x32_bf16 v[10:13], v[242:245], v[218:221], v[10:13]
	v_mfma_f32_16x16x32_bf16 v[6:9], v[234:237], v[226:229], v[6:9]
	v_mfma_f32_16x16x32_bf16 v[2:5], v[242:245], v[226:229], v[2:5]
	s_barrier
	ds_read_b128 v[162:165], v148
	ds_read_b128 v[166:169], v148 offset:1024
	ds_read_b128 v[170:173], v148 offset:2048
	ds_read_b128 v[174:177], v148 offset:3072
	v_add_u32_e32 v161, 0x4000, v151
	v_lshl_add_u64 v[230:231], v[182:183], 0, s[34:35]
	v_readfirstlane_b32 s2, v161
	v_add_u32_e32 v161, 0x4000, v153
	s_mov_b32 m0, s2
	v_readfirstlane_b32 s2, v161
	ds_read_b128 v[178:181], v146 offset:32768
	ds_read_b128 v[186:189], v146 offset:33792
	ds_read_b128 v[190:193], v145 offset:32768
	ds_read_b128 v[198:201], v145 offset:33792
	ds_read_b128 v[202:205], v144 offset:32768
	ds_read_b128 v[218:221], v144 offset:33792
	ds_read_b128 v[222:225], v143 offset:32768
	ds_read_b128 v[226:229], v143 offset:33792
	global_load_lds_dwordx4 v[230:231], off
	v_lshl_add_u64 v[230:231], v[194:195], 0, s[34:35]
	s_mov_b32 m0, s2
	s_nop 0
	global_load_lds_dwordx4 v[230:231], off
	s_waitcnt lgkmcnt(8)
	s_barrier
	s_waitcnt lgkmcnt(0)
	s_waitcnt lgkmcnt(0)
	v_mfma_f32_16x16x32_bf16 v[126:129], v[162:165], v[178:181], v[126:129]
	v_mfma_f32_16x16x32_bf16 v[122:125], v[170:173], v[178:181], v[122:125]
	v_mfma_f32_16x16x32_bf16 v[118:121], v[162:165], v[190:193], v[118:121]
	v_mfma_f32_16x16x32_bf16 v[114:117], v[170:173], v[190:193], v[114:117]
	v_mfma_f32_16x16x32_bf16 v[110:113], v[162:165], v[202:205], v[110:113]
	v_mfma_f32_16x16x32_bf16 v[106:109], v[170:173], v[202:205], v[106:109]
	v_mfma_f32_16x16x32_bf16 v[102:105], v[162:165], v[222:225], v[102:105]
	v_mfma_f32_16x16x32_bf16 v[98:101], v[170:173], v[222:225], v[98:101]
	v_mfma_f32_16x16x32_bf16 v[126:129], v[166:169], v[186:189], v[126:129]
	v_mfma_f32_16x16x32_bf16 v[122:125], v[174:177], v[186:189], v[122:125]
	v_mfma_f32_16x16x32_bf16 v[118:121], v[166:169], v[198:201], v[118:121]
	v_mfma_f32_16x16x32_bf16 v[114:117], v[174:177], v[198:201], v[114:117]
	v_mfma_f32_16x16x32_bf16 v[110:113], v[166:169], v[218:221], v[110:113]
	v_mfma_f32_16x16x32_bf16 v[106:109], v[174:177], v[218:221], v[106:109]
	v_mfma_f32_16x16x32_bf16 v[102:105], v[166:169], v[226:229], v[102:105]
	v_mfma_f32_16x16x32_bf16 v[98:101], v[174:177], v[226:229], v[98:101]
	s_barrier
	v_readfirstlane_b32 s2, v149
	v_lshl_add_u64 v[246:247], v[196:197], 0, s[92:93]
	s_mov_b32 m0, s2
	v_readfirstlane_b32 s2, v150
	ds_read_b128 v[230:233], v147
	ds_read_b128 v[234:237], v147 offset:1024
	ds_read_b128 v[238:241], v147 offset:2048
	ds_read_b128 v[242:245], v147 offset:3072
	global_load_lds_dwordx4 v[246:247], off
	v_lshl_add_u64 v[246:247], v[206:207], 0, s[92:93]
	s_mov_b32 m0, s2
	s_nop 0
	global_load_lds_dwordx4 v[246:247], off
	s_barrier
	s_waitcnt lgkmcnt(0)
	s_waitcnt lgkmcnt(0)
	v_mfma_f32_16x16x32_bf16 v[94:97], v[230:233], v[178:181], v[94:97]
	v_mfma_f32_16x16x32_bf16 v[90:93], v[238:241], v[178:181], v[90:93]
	v_mfma_f32_16x16x32_bf16 v[86:89], v[230:233], v[190:193], v[86:89]
	v_mfma_f32_16x16x32_bf16 v[82:85], v[238:241], v[190:193], v[82:85]
	v_mfma_f32_16x16x32_bf16 v[78:81], v[230:233], v[202:205], v[78:81]
	v_mfma_f32_16x16x32_bf16 v[74:77], v[238:241], v[202:205], v[74:77]
	v_mfma_f32_16x16x32_bf16 v[70:73], v[230:233], v[222:225], v[70:73]
	v_mfma_f32_16x16x32_bf16 v[66:69], v[238:241], v[222:225], v[66:69]
	v_mfma_f32_16x16x32_bf16 v[94:97], v[234:237], v[186:189], v[94:97]
	v_mfma_f32_16x16x32_bf16 v[90:93], v[242:245], v[186:189], v[90:93]
	v_mfma_f32_16x16x32_bf16 v[86:89], v[234:237], v[198:201], v[86:89]
	v_mfma_f32_16x16x32_bf16 v[82:85], v[242:245], v[198:201], v[82:85]
	v_mfma_f32_16x16x32_bf16 v[78:81], v[234:237], v[218:221], v[78:81]
	v_mfma_f32_16x16x32_bf16 v[74:77], v[242:245], v[218:221], v[74:77]
	v_mfma_f32_16x16x32_bf16 v[70:73], v[234:237], v[226:229], v[70:73]
	v_mfma_f32_16x16x32_bf16 v[66:69], v[242:245], v[226:229], v[66:69]
	v_readfirstlane_b32 s2, v152
	v_lshl_add_u64 v[182:183], v[182:183], 0, s[50:51]
	s_mov_b32 m0, s2
	v_readfirstlane_b32 s2, v154
	s_barrier
	ds_read_b128 v[178:181], v146 offset:49152
	ds_read_b128 v[186:189], v146 offset:50176
	ds_read_b128 v[190:193], v145 offset:49152
	ds_read_b128 v[198:201], v145 offset:50176
	ds_read_b128 v[202:205], v144 offset:49152
	ds_read_b128 v[218:221], v144 offset:50176
	ds_read_b128 v[222:225], v143 offset:49152
	ds_read_b128 v[226:229], v143 offset:50176
	global_load_lds_dwordx4 v[182:183], off
	v_lshl_add_u64 v[182:183], v[194:195], 0, s[50:51]
	s_mov_b32 m0, s2
	s_nop 0
	global_load_lds_dwordx4 v[182:183], off
	s_barrier
	s_waitcnt lgkmcnt(0)
	s_waitcnt lgkmcnt(0)
	v_mfma_f32_16x16x32_bf16 v[62:65], v[162:165], v[178:181], v[62:65]
	v_mfma_f32_16x16x32_bf16 v[58:61], v[170:173], v[178:181], v[58:61]
	v_mfma_f32_16x16x32_bf16 v[54:57], v[162:165], v[190:193], v[54:57]
	v_mfma_f32_16x16x32_bf16 v[50:53], v[170:173], v[190:193], v[50:53]
	v_mfma_f32_16x16x32_bf16 v[46:49], v[162:165], v[202:205], v[46:49]
	v_mfma_f32_16x16x32_bf16 v[42:45], v[170:173], v[202:205], v[42:45]
	v_mfma_f32_16x16x32_bf16 v[38:41], v[162:165], v[222:225], v[38:41]
	v_mfma_f32_16x16x32_bf16 v[34:37], v[170:173], v[222:225], v[34:37]
	v_mfma_f32_16x16x32_bf16 v[62:65], v[166:169], v[186:189], v[62:65]
	v_mfma_f32_16x16x32_bf16 v[58:61], v[174:177], v[186:189], v[58:61]
	v_mfma_f32_16x16x32_bf16 v[54:57], v[166:169], v[198:201], v[54:57]
	v_mfma_f32_16x16x32_bf16 v[50:53], v[174:177], v[198:201], v[50:53]
	v_mfma_f32_16x16x32_bf16 v[46:49], v[166:169], v[218:221], v[46:49]
	v_mfma_f32_16x16x32_bf16 v[42:45], v[174:177], v[218:221], v[42:45]
	v_mfma_f32_16x16x32_bf16 v[38:41], v[166:169], v[226:229], v[38:41]
	v_mfma_f32_16x16x32_bf16 v[34:37], v[174:177], v[226:229], v[34:37]
	s_barrier
	v_readfirstlane_b32 s2, v156
	v_lshl_add_u64 v[162:163], v[196:197], 0, s[4:5]
	s_mov_b32 m0, s2
	v_readfirstlane_b32 s2, v157
	global_load_lds_dwordx4 v[162:163], off
	v_lshl_add_u64 v[162:163], v[206:207], 0, s[4:5]
	s_mov_b32 m0, s2
	s_nop 0
	global_load_lds_dwordx4 v[162:163], off
	s_waitcnt vmcnt(6)
	s_barrier
	v_mfma_f32_16x16x32_bf16 v[30:33], v[230:233], v[178:181], v[30:33]
	v_mfma_f32_16x16x32_bf16 v[26:29], v[238:241], v[178:181], v[26:29]
	v_mfma_f32_16x16x32_bf16 v[22:25], v[230:233], v[190:193], v[22:25]
	v_mfma_f32_16x16x32_bf16 v[18:21], v[238:241], v[190:193], v[18:21]
	v_mfma_f32_16x16x32_bf16 v[14:17], v[230:233], v[202:205], v[14:17]
	v_mfma_f32_16x16x32_bf16 v[10:13], v[238:241], v[202:205], v[10:13]
	v_mfma_f32_16x16x32_bf16 v[6:9], v[230:233], v[222:225], v[6:9]
	v_mfma_f32_16x16x32_bf16 v[2:5], v[238:241], v[222:225], v[2:5]
	v_mfma_f32_16x16x32_bf16 v[30:33], v[234:237], v[186:189], v[30:33]
	v_mfma_f32_16x16x32_bf16 v[26:29], v[242:245], v[186:189], v[26:29]
	v_mfma_f32_16x16x32_bf16 v[22:25], v[234:237], v[198:201], v[22:25]
	v_mfma_f32_16x16x32_bf16 v[18:21], v[242:245], v[198:201], v[18:21]
	v_mfma_f32_16x16x32_bf16 v[14:17], v[234:237], v[218:221], v[14:17]
	v_mfma_f32_16x16x32_bf16 v[10:13], v[242:245], v[218:221], v[10:13]
	v_mfma_f32_16x16x32_bf16 v[6:9], v[234:237], v[226:229], v[6:9]
	v_mfma_f32_16x16x32_bf16 v[2:5], v[242:245], v[226:229], v[2:5]
	s_add_i32 s16, s16, 2
	v_lshl_add_u64 v[132:133], v[132:133], 0, s[36:37]
	v_lshl_add_u64 v[134:135], v[134:135], 0, s[36:37]
	v_lshl_add_u64 v[136:137], v[136:137], 0, s[36:37]
	s_cmp_gt_u32 s16, 11
	v_lshl_add_u64 v[138:139], v[138:139], 0, s[36:37]
	s_barrier
	s_cbranch_scc0 .LBB0_923
	s_or_b32 s2, s22, 0x80
	s_ashr_i32 s3, s2, 31
	s_lshl_b64 s[2:3], s[2:3], 11
	s_add_u32 s2, s30, s2
	s_addc_u32 s3, s31, s3
	v_readfirstlane_b32 s10, v159
	v_lshl_add_u64 v[156:157], s[2:3], 0, v[0:1]
	s_mov_b32 m0, s10
	v_lshl_add_u64 v[130:131], s[2:3], 0, v[130:131]
	v_readfirstlane_b32 s2, v160
	ds_read_b128 v[132:135], v158
	ds_read_b128 v[136:139], v158 offset:1024
	ds_read_b128 v[150:153], v158 offset:2048
	ds_read_b128 v[162:165], v158 offset:3072
	ds_read_b128 v[166:169], v146
	ds_read_b128 v[170:173], v146 offset:1024
	ds_read_b128 v[174:177], v145
	ds_read_b128 v[178:181], v145 offset:1024
	ds_read_b128 v[186:189], v144
	ds_read_b128 v[190:193], v144 offset:1024
	ds_read_b128 v[198:201], v143
	ds_read_b128 v[202:205], v143 offset:1024
	global_load_lds_dwordx4 v[156:157], off
	s_mov_b32 m0, s2
	s_nop 0
	global_load_lds_dwordx4 v[130:131], off
	s_barrier
	s_waitcnt lgkmcnt(0)
	s_waitcnt lgkmcnt(0)
	v_mfma_f32_16x16x32_bf16 v[126:129], v[132:135], v[166:169], v[126:129]
	v_mfma_f32_16x16x32_bf16 v[118:121], v[132:135], v[174:177], v[118:121]
	v_mfma_f32_16x16x32_bf16 v[110:113], v[132:135], v[186:189], v[110:113]
	v_mfma_f32_16x16x32_bf16 v[102:105], v[132:135], v[198:201], v[102:105]
	v_mfma_f32_16x16x32_bf16 v[126:129], v[136:139], v[170:173], v[126:129]
	v_mfma_f32_16x16x32_bf16 v[122:125], v[150:153], v[166:169], v[122:125]
	v_mfma_f32_16x16x32_bf16 v[118:121], v[136:139], v[178:181], v[118:121]
	v_mfma_f32_16x16x32_bf16 v[114:117], v[150:153], v[174:177], v[114:117]
	v_mfma_f32_16x16x32_bf16 v[110:113], v[136:139], v[190:193], v[110:113]
	v_mfma_f32_16x16x32_bf16 v[106:109], v[150:153], v[186:189], v[106:109]
	v_mfma_f32_16x16x32_bf16 v[102:105], v[136:139], v[202:205], v[102:105]
	v_mfma_f32_16x16x32_bf16 v[98:101], v[150:153], v[198:201], v[98:101]
	v_mfma_f32_16x16x32_bf16 v[156:159], v[162:165], v[170:173], v[122:125]
	v_mfma_f32_16x16x32_bf16 v[218:221], v[162:165], v[178:181], v[114:117]
	v_mfma_f32_16x16x32_bf16 v[222:225], v[162:165], v[190:193], v[106:109]
	v_mfma_f32_16x16x32_bf16 v[226:229], v[162:165], v[202:205], v[98:101]
	s_barrier
	s_nop 1
	ds_read_b128 v[98:101], v155
	ds_read_b128 v[106:109], v155 offset:1024
	ds_read_b128 v[114:117], v155 offset:2048
	ds_read_b128 v[122:125], v155 offset:3072
	s_barrier
	s_waitcnt lgkmcnt(0)
	s_waitcnt lgkmcnt(0)
	v_mfma_f32_16x16x32_bf16 v[94:97], v[98:101], v[166:169], v[94:97]
	v_mfma_f32_16x16x32_bf16 v[86:89], v[98:101], v[174:177], v[86:89]
	v_mfma_f32_16x16x32_bf16 v[78:81], v[98:101], v[186:189], v[78:81]
	v_mfma_f32_16x16x32_bf16 v[70:73], v[98:101], v[198:201], v[70:73]
	v_mfma_f32_16x16x32_bf16 v[94:97], v[106:109], v[170:173], v[94:97]
	v_mfma_f32_16x16x32_bf16 v[90:93], v[114:117], v[166:169], v[90:93]
	v_mfma_f32_16x16x32_bf16 v[86:89], v[106:109], v[178:181], v[86:89]
	v_mfma_f32_16x16x32_bf16 v[82:85], v[114:117], v[174:177], v[82:85]
	v_mfma_f32_16x16x32_bf16 v[78:81], v[106:109], v[190:193], v[78:81]
	v_mfma_f32_16x16x32_bf16 v[74:77], v[114:117], v[186:189], v[74:77]
	v_mfma_f32_16x16x32_bf16 v[70:73], v[106:109], v[202:205], v[70:73]
	v_mfma_f32_16x16x32_bf16 v[66:69], v[114:117], v[198:201], v[66:69]
	v_mfma_f32_16x16x32_bf16 v[166:169], v[122:125], v[170:173], v[90:93]
	v_mfma_f32_16x16x32_bf16 v[170:173], v[122:125], v[178:181], v[82:85]
	v_mfma_f32_16x16x32_bf16 v[174:177], v[122:125], v[190:193], v[74:77]
	v_mfma_f32_16x16x32_bf16 v[178:181], v[122:125], v[202:205], v[66:69]
	s_barrier
	s_nop 1
	ds_read_b128 v[66:69], v146 offset:16384
	ds_read_b128 v[74:77], v146 offset:17408
	ds_read_b128 v[82:85], v145 offset:16384
	ds_read_b128 v[90:93], v145 offset:17408
	ds_read_b128 v[186:189], v144 offset:16384
	ds_read_b128 v[190:193], v144 offset:17408
	ds_read_b128 v[198:201], v143 offset:16384
	ds_read_b128 v[202:205], v143 offset:17408
	s_waitcnt vmcnt(4)
	s_barrier
	s_waitcnt lgkmcnt(0)
	s_waitcnt lgkmcnt(0)
	v_mfma_f32_16x16x32_bf16 v[62:65], v[132:135], v[66:69], v[62:65]
	v_mfma_f32_16x16x32_bf16 v[54:57], v[132:135], v[82:85], v[54:57]
	v_mfma_f32_16x16x32_bf16 v[46:49], v[132:135], v[186:189], v[46:49]
	v_mfma_f32_16x16x32_bf16 v[38:41], v[132:135], v[198:201], v[38:41]
	v_mfma_f32_16x16x32_bf16 v[62:65], v[136:139], v[74:77], v[62:65]
	v_mfma_f32_16x16x32_bf16 v[58:61], v[150:153], v[66:69], v[58:61]
	v_mfma_f32_16x16x32_bf16 v[54:57], v[136:139], v[90:93], v[54:57]
	v_mfma_f32_16x16x32_bf16 v[50:53], v[150:153], v[82:85], v[50:53]
	v_mfma_f32_16x16x32_bf16 v[46:49], v[136:139], v[190:193], v[46:49]
	v_mfma_f32_16x16x32_bf16 v[42:45], v[150:153], v[186:189], v[42:45]
	v_mfma_f32_16x16x32_bf16 v[38:41], v[136:139], v[202:205], v[38:41]
	v_mfma_f32_16x16x32_bf16 v[34:37], v[150:153], v[198:201], v[34:37]
	v_mfma_f32_16x16x32_bf16 v[230:233], v[162:165], v[74:77], v[58:61]
	v_mfma_f32_16x16x32_bf16 v[234:237], v[162:165], v[90:93], v[50:53]
	v_mfma_f32_16x16x32_bf16 v[238:241], v[162:165], v[190:193], v[42:45]
	v_mfma_f32_16x16x32_bf16 v[130:133], v[162:165], v[202:205], v[34:37]
	v_mfma_f32_16x16x32_bf16 v[30:33], v[98:101], v[66:69], v[30:33]
	v_mfma_f32_16x16x32_bf16 v[22:25], v[98:101], v[82:85], v[22:25]
	v_mfma_f32_16x16x32_bf16 v[14:17], v[98:101], v[186:189], v[14:17]
	v_mfma_f32_16x16x32_bf16 v[6:9], v[98:101], v[198:201], v[6:9]
	v_mfma_f32_16x16x32_bf16 v[30:33], v[106:109], v[74:77], v[30:33]
	v_mfma_f32_16x16x32_bf16 v[26:29], v[114:117], v[66:69], v[26:29]
	v_mfma_f32_16x16x32_bf16 v[22:25], v[106:109], v[90:93], v[22:25]
	v_mfma_f32_16x16x32_bf16 v[18:21], v[114:117], v[82:85], v[18:21]
	v_mfma_f32_16x16x32_bf16 v[14:17], v[106:109], v[190:193], v[14:17]
	v_mfma_f32_16x16x32_bf16 v[10:13], v[114:117], v[186:189], v[10:13]
	v_mfma_f32_16x16x32_bf16 v[6:9], v[106:109], v[202:205], v[6:9]
	v_mfma_f32_16x16x32_bf16 v[2:5], v[114:117], v[198:201], v[2:5]
	v_mfma_f32_16x16x32_bf16 v[134:137], v[122:125], v[74:77], v[26:29]
	v_mfma_f32_16x16x32_bf16 v[150:153], v[122:125], v[90:93], v[18:21]
	v_mfma_f32_16x16x32_bf16 v[160:163], v[122:125], v[190:193], v[10:13]
	v_mfma_f32_16x16x32_bf16 v[186:189], v[122:125], v[202:205], v[2:5]
	s_barrier
	s_nop 1
	ds_read_b128 v[2:5], v148
	ds_read_b128 v[10:13], v148 offset:1024
	ds_read_b128 v[190:193], v148 offset:2048
	ds_read_b128 v[198:201], v148 offset:3072
	ds_read_b128 v[18:21], v146 offset:32768
	ds_read_b128 v[26:29], v146 offset:33792
	ds_read_b128 v[34:37], v145 offset:32768
	ds_read_b128 v[42:45], v145 offset:33792
	ds_read_b128 v[50:53], v144 offset:32768
	ds_read_b128 v[58:61], v144 offset:33792
	ds_read_b128 v[202:205], v143 offset:32768
	ds_read_b128 v[242:245], v143 offset:33792
	s_waitcnt vmcnt(2)
	s_barrier
	s_waitcnt lgkmcnt(0)
	s_waitcnt lgkmcnt(0)
	v_mfma_f32_16x16x32_bf16 v[66:69], v[2:5], v[18:21], v[126:129]
	v_mfma_f32_16x16x32_bf16 v[122:125], v[10:13], v[26:29], v[66:69]
	v_mfma_f32_16x16x32_bf16 v[66:69], v[190:193], v[18:21], v[156:159]
	v_mfma_f32_16x16x32_bf16 v[114:117], v[198:201], v[26:29], v[66:69]
	v_mfma_f32_16x16x32_bf16 v[66:69], v[2:5], v[34:37], v[118:121]
	v_mfma_f32_16x16x32_bf16 v[106:109], v[10:13], v[42:45], v[66:69]
	v_mfma_f32_16x16x32_bf16 v[66:69], v[190:193], v[34:37], v[218:221]
	v_mfma_f32_16x16x32_bf16 v[98:101], v[198:201], v[42:45], v[66:69]
	v_mfma_f32_16x16x32_bf16 v[66:69], v[2:5], v[50:53], v[110:113]
	v_mfma_f32_16x16x32_bf16 v[90:93], v[10:13], v[58:61], v[66:69]
	v_mfma_f32_16x16x32_bf16 v[66:69], v[190:193], v[50:53], v[222:225]
	v_mfma_f32_16x16x32_bf16 v[82:85], v[198:201], v[58:61], v[66:69]
	v_mfma_f32_16x16x32_bf16 v[66:69], v[2:5], v[202:205], v[102:105]
	v_mfma_f32_16x16x32_bf16 v[74:77], v[10:13], v[242:245], v[66:69]
	v_mfma_f32_16x16x32_bf16 v[66:69], v[190:193], v[202:205], v[226:229]
	v_mfma_f32_16x16x32_bf16 v[66:69], v[198:201], v[242:245], v[66:69]
	s_barrier
	ds_read_b128 v[154:157], v147
	ds_read_b128 v[218:221], v147 offset:1024
	ds_read_b128 v[222:225], v147 offset:2048
	ds_read_b128 v[226:229], v147 offset:3072
	s_waitcnt vmcnt(0)
	s_barrier
	s_waitcnt lgkmcnt(0)
	s_waitcnt lgkmcnt(0)
	v_mfma_f32_16x16x32_bf16 v[94:97], v[154:157], v[18:21], v[94:97]
	v_mfma_f32_16x16x32_bf16 v[18:21], v[222:225], v[18:21], v[166:169]
	v_mfma_f32_16x16x32_bf16 v[118:121], v[226:229], v[26:29], v[18:21]
	v_mfma_f32_16x16x32_bf16 v[18:21], v[154:157], v[34:37], v[86:89]
	v_mfma_f32_16x16x32_bf16 v[110:113], v[218:221], v[42:45], v[18:21]
	v_mfma_f32_16x16x32_bf16 v[18:21], v[222:225], v[34:37], v[170:173]
	v_mfma_f32_16x16x32_bf16 v[102:105], v[226:229], v[42:45], v[18:21]
	v_mfma_f32_16x16x32_bf16 v[18:21], v[154:157], v[50:53], v[78:81]
	v_mfma_f32_16x16x32_bf16 v[126:129], v[218:221], v[26:29], v[94:97]
	v_mfma_f32_16x16x32_bf16 v[94:97], v[218:221], v[58:61], v[18:21]
	v_mfma_f32_16x16x32_bf16 v[18:21], v[222:225], v[50:53], v[174:177]
	v_mfma_f32_16x16x32_bf16 v[86:89], v[226:229], v[58:61], v[18:21]
	v_mfma_f32_16x16x32_bf16 v[18:21], v[154:157], v[202:205], v[70:73]
	v_mfma_f32_16x16x32_bf16 v[78:81], v[218:221], v[242:245], v[18:21]
	v_mfma_f32_16x16x32_bf16 v[18:21], v[222:225], v[202:205], v[178:181]
	v_mfma_f32_16x16x32_bf16 v[70:73], v[226:229], v[242:245], v[18:21]
	s_barrier
	ds_read_b128 v[164:167], v146 offset:49152
	ds_read_b128 v[146:149], v146 offset:50176
	ds_read_b128 v[168:171], v145 offset:49152
	ds_read_b128 v[172:175], v145 offset:50176
	ds_read_b128 v[176:179], v144 offset:49152
	ds_read_b128 v[180:183], v144 offset:50176
	ds_read_b128 v[202:205], v143 offset:49152
	ds_read_b128 v[142:145], v143 offset:50176
	s_barrier
	s_waitcnt lgkmcnt(0)
	s_waitcnt lgkmcnt(0)
	v_mfma_f32_16x16x32_bf16 v[18:21], v[2:5], v[164:167], v[62:65]
	v_mfma_f32_16x16x32_bf16 v[58:61], v[10:13], v[146:149], v[18:21]
	v_mfma_f32_16x16x32_bf16 v[18:21], v[190:193], v[164:167], v[230:233]
	v_mfma_f32_16x16x32_bf16 v[50:53], v[198:201], v[146:149], v[18:21]
	v_mfma_f32_16x16x32_bf16 v[18:21], v[2:5], v[168:171], v[54:57]
	v_mfma_f32_16x16x32_bf16 v[42:45], v[10:13], v[172:175], v[18:21]
	v_mfma_f32_16x16x32_bf16 v[18:21], v[190:193], v[168:171], v[234:237]
	v_mfma_f32_16x16x32_bf16 v[34:37], v[198:201], v[172:175], v[18:21]
	v_mfma_f32_16x16x32_bf16 v[18:21], v[2:5], v[176:179], v[46:49]
	v_mfma_f32_16x16x32_bf16 v[2:5], v[2:5], v[202:205], v[38:41]
	v_mfma_f32_16x16x32_bf16 v[26:29], v[10:13], v[180:183], v[18:21]
	v_mfma_f32_16x16x32_bf16 v[18:21], v[190:193], v[176:179], v[238:241]
	v_mfma_f32_16x16x32_bf16 v[10:13], v[10:13], v[142:145], v[2:5]
	v_mfma_f32_16x16x32_bf16 v[2:5], v[190:193], v[202:205], v[130:133]
	v_mfma_f32_16x16x32_bf16 v[18:21], v[198:201], v[180:183], v[18:21]
	v_mfma_f32_16x16x32_bf16 v[2:5], v[198:201], v[142:145], v[2:5]
	v_mfma_f32_16x16x32_bf16 v[30:33], v[154:157], v[164:167], v[30:33]
	v_mfma_f32_16x16x32_bf16 v[62:65], v[218:221], v[146:149], v[30:33]
	v_mfma_f32_16x16x32_bf16 v[30:33], v[222:225], v[164:167], v[134:137]
	v_mfma_f32_16x16x32_bf16 v[22:25], v[154:157], v[168:171], v[22:25]
	v_mfma_f32_16x16x32_bf16 v[14:17], v[154:157], v[176:179], v[14:17]
	v_mfma_f32_16x16x32_bf16 v[54:57], v[226:229], v[146:149], v[30:33]
	v_mfma_f32_16x16x32_bf16 v[46:49], v[218:221], v[172:175], v[22:25]
	v_mfma_f32_16x16x32_bf16 v[22:25], v[222:225], v[168:171], v[150:153]
	v_mfma_f32_16x16x32_bf16 v[30:33], v[218:221], v[180:183], v[14:17]
	v_mfma_f32_16x16x32_bf16 v[14:17], v[222:225], v[176:179], v[160:163]
	v_mfma_f32_16x16x32_bf16 v[6:9], v[154:157], v[202:205], v[6:9]
	v_mfma_f32_16x16x32_bf16 v[38:41], v[226:229], v[172:175], v[22:25]
	v_mfma_f32_16x16x32_bf16 v[22:25], v[226:229], v[180:183], v[14:17]
	v_mfma_f32_16x16x32_bf16 v[14:17], v[218:221], v[142:145], v[6:9]
	v_mfma_f32_16x16x32_bf16 v[6:9], v[222:225], v[202:205], v[186:189]
	v_mfma_f32_16x16x32_bf16 v[6:9], v[226:229], v[142:145], v[6:9]
	s_movk_i32 s1, 0x100
	v_cmp_gt_u32_e32 vcc, s1, v140
	s_barrier
	s_and_saveexec_b64 s[2:3], vcc
	s_cbranch_execz .LBB0_926
	s_barrier
